# v20 + same 32-load batching applied to all 18 P0 transpose loops
# baseline (speedup 1.0000x reference)
; __device__ __forceinline__ void p0_transpose_item(const float* W, int N, bf16_t* WT, int ldt, int k0, int n0, int nrow0, int kcol0, LAS float* scr, int lane) {
; #pragma unroll 8
;     for (int i = 0; i < 32; ++i) { const int kk = 2 * i + (lane >> 5); scr[kk * 33 + (lane & 31)] = W[(size_t)(k0 + kk) * N + n0 + (lane & 31)]; }
.LBB0_40:
	s_lshl_b32 s16, s15, 1
	s_lshl_b32 s17, s14, 1
	v_or_b32_e32 v50, s16, v1
	v_or_b32_e32 v51, s17, v2
	s_add_i32 s18, s16, 4
	s_add_i32 s19, s17, 4
	s_add_i32 s20, s16, 8
	s_add_i32 s21, s17, 8
	s_add_i32 s22, s16, 12
	s_add_i32 s23, s17, 12
	s_add_i32 s24, s16, 16
	s_add_i32 s25, s17, 16
	s_add_i32 s26, s16, 20
	s_add_i32 s27, s17, 20
	s_add_i32 s28, s16, 24
	s_add_i32 s29, s17, 24
	s_add_i32 s16, s16, 28
	s_add_i32 s17, s17, 28
	v_add_u32_e32 v20, s8, v51
	v_or_b32_e32 v52, s18, v1
	v_or_b32_e32 v53, s19, v2
	v_or_b32_e32 v54, s20, v1
	v_or_b32_e32 v55, s21, v2
	v_or_b32_e32 v56, s22, v1
	v_or_b32_e32 v57, s23, v2
	v_or_b32_e32 v58, s24, v1
	v_or_b32_e32 v59, s25, v2
	v_or_b32_e32 v60, s26, v1
	v_or_b32_e32 v61, s27, v2
	v_or_b32_e32 v62, s28, v1
	v_or_b32_e32 v63, s29, v2
	v_or_b32_e32 v64, s16, v1
	v_or_b32_e32 v65, s17, v2
	v_add_u32_e32 v18, s7, v50
	v_ashrrev_i32_e32 v21, 31, v20
	v_add_u32_e32 v22, s7, v52
	v_add_u32_e32 v24, s8, v53
	v_add_u32_e32 v26, s7, v54
	v_add_u32_e32 v28, s8, v55
	v_add_u32_e32 v30, s7, v56
	v_add_u32_e32 v32, s8, v57
	v_add_u32_e32 v34, s7, v58
	v_add_u32_e32 v36, s8, v59
	v_add_u32_e32 v38, s7, v60
	v_add_u32_e32 v40, s8, v61
	v_add_u32_e32 v42, s7, v62
	v_add_u32_e32 v44, s8, v63
	v_add_u32_e32 v46, s7, v64
	v_add_u32_e32 v48, s8, v65
	v_ashrrev_i32_e32 v19, 31, v18
	v_lshlrev_b64 v[20:21], 14, v[20:21]
	v_ashrrev_i32_e32 v25, 31, v24
	v_ashrrev_i32_e32 v23, 31, v22
	v_ashrrev_i32_e32 v29, 31, v28
	v_ashrrev_i32_e32 v27, 31, v26
	v_ashrrev_i32_e32 v33, 31, v32
	v_ashrrev_i32_e32 v31, 31, v30
	v_ashrrev_i32_e32 v37, 31, v36
	v_ashrrev_i32_e32 v35, 31, v34
	v_ashrrev_i32_e32 v41, 31, v40
	v_ashrrev_i32_e32 v39, 31, v38
	v_ashrrev_i32_e32 v45, 31, v44
	v_ashrrev_i32_e32 v43, 31, v42
	v_ashrrev_i32_e32 v49, 31, v48
	v_ashrrev_i32_e32 v47, 31, v46
	v_lshlrev_b64 v[18:19], 14, v[18:19]
	v_lshl_add_u64 v[20:21], v[10:11], 0, v[20:21]
	v_lshlrev_b64 v[22:23], 14, v[22:23]
	v_lshlrev_b64 v[24:25], 14, v[24:25]
	v_lshlrev_b64 v[26:27], 14, v[26:27]
	v_lshlrev_b64 v[28:29], 14, v[28:29]
	v_lshlrev_b64 v[30:31], 14, v[30:31]
	v_lshlrev_b64 v[32:33], 14, v[32:33]
	v_lshlrev_b64 v[34:35], 14, v[34:35]
	v_lshlrev_b64 v[36:37], 14, v[36:37]
	v_lshlrev_b64 v[38:39], 14, v[38:39]
	v_lshlrev_b64 v[40:41], 14, v[40:41]
	v_lshlrev_b64 v[42:43], 14, v[42:43]
	v_lshlrev_b64 v[44:45], 14, v[44:45]
	v_lshlrev_b64 v[46:47], 14, v[46:47]
	v_lshlrev_b64 v[48:49], 14, v[48:49]
	v_lshl_add_u64 v[18:19], v[10:11], 0, v[18:19]
	v_lshl_add_u64 v[24:25], v[10:11], 0, v[24:25]
	v_lshl_add_u64 v[22:23], v[10:11], 0, v[22:23]
	v_lshl_add_u64 v[28:29], v[10:11], 0, v[28:29]
	v_lshl_add_u64 v[26:27], v[10:11], 0, v[26:27]
	v_lshl_add_u64 v[32:33], v[10:11], 0, v[32:33]
	v_lshl_add_u64 v[30:31], v[10:11], 0, v[30:31]
	v_lshl_add_u64 v[36:37], v[10:11], 0, v[36:37]
	v_lshl_add_u64 v[34:35], v[10:11], 0, v[34:35]
	v_lshl_add_u64 v[40:41], v[10:11], 0, v[40:41]
	v_lshl_add_u64 v[38:39], v[10:11], 0, v[38:39]
	v_lshl_add_u64 v[44:45], v[10:11], 0, v[44:45]
	v_lshl_add_u64 v[42:43], v[10:11], 0, v[42:43]
	v_lshl_add_u64 v[48:49], v[10:11], 0, v[48:49]
	v_lshl_add_u64 v[46:47], v[10:11], 0, v[46:47]
	global_load_dword v66, v[20:21], off
	global_load_dword v67, v[18:19], off
	global_load_dword v68, v[24:25], off
	global_load_dword v69, v[22:23], off
	global_load_dword v70, v[28:29], off
	global_load_dword v71, v[26:27], off
	global_load_dword v72, v[32:33], off
	global_load_dword v73, v[30:31], off
	global_load_dword v74, v[36:37], off
	global_load_dword v75, v[34:35], off
	global_load_dword v76, v[40:41], off
	global_load_dword v77, v[38:39], off
	global_load_dword v78, v[44:45], off
	global_load_dword v79, v[42:43], off
	global_load_dword v80, v[48:49], off
	global_load_dword v81, v[46:47], off
	s_add_i32 s14, s14, 16
	s_add_i32 s15, s15, 16
	s_add_i32 s9, s9, -16
	v_mad_u64_u32 v[18:19], s[16:17], v51, s13, v[4:5]
	s_cmp_lg_u32 s9, 0
	v_mad_u64_u32 v[20:21], s[16:17], v50, s13, v[4:5]
	v_mad_u64_u32 v[22:23], s[16:17], v53, s13, v[4:5]
	v_mad_u64_u32 v[24:25], s[16:17], v52, s13, v[4:5]
	v_mad_u64_u32 v[26:27], s[16:17], v55, s13, v[4:5]
	v_mad_u64_u32 v[28:29], s[16:17], v54, s13, v[4:5]
	v_mad_u64_u32 v[30:31], s[16:17], v57, s13, v[4:5]
	v_mad_u64_u32 v[32:33], s[16:17], v56, s13, v[4:5]
	v_mad_u64_u32 v[34:35], s[16:17], v59, s13, v[4:5]
	v_mad_u64_u32 v[36:37], s[16:17], v58, s13, v[4:5]
	v_mad_u64_u32 v[38:39], s[16:17], v61, s13, v[4:5]
	v_mad_u64_u32 v[40:41], s[16:17], v60, s13, v[4:5]
	v_mad_u64_u32 v[42:43], s[16:17], v63, s13, v[4:5]
	v_mad_u64_u32 v[44:45], s[16:17], v62, s13, v[4:5]
	v_mad_u64_u32 v[46:47], s[16:17], v65, s13, v[4:5]
	v_mad_u64_u32 v[48:49], s[16:17], v64, s13, v[4:5]
	s_nop 7
	s_lshl_b32 s16, s15, 1
	s_lshl_b32 s17, s14, 1
	v_or_b32_e32 v172, s16, v1
	v_or_b32_e32 v173, s17, v2
	s_add_i32 s18, s16, 4
	s_add_i32 s19, s17, 4
	s_add_i32 s20, s16, 8
	s_add_i32 s21, s17, 8
	s_add_i32 s22, s16, 12
	s_add_i32 s23, s17, 12
	s_add_i32 s24, s16, 16
	s_add_i32 s25, s17, 16
	s_add_i32 s26, s16, 20
	s_add_i32 s27, s17, 20
	s_add_i32 s28, s16, 24
	s_add_i32 s29, s17, 24
	s_add_i32 s16, s16, 28
	s_add_i32 s17, s17, 28
	v_add_u32_e32 v142, s8, v173
	v_or_b32_e32 v174, s18, v1
	v_or_b32_e32 v175, s19, v2
	v_or_b32_e32 v176, s20, v1
	v_or_b32_e32 v177, s21, v2
	v_or_b32_e32 v178, s22, v1
	v_or_b32_e32 v179, s23, v2
	v_or_b32_e32 v180, s24, v1
	v_or_b32_e32 v181, s25, v2
	v_or_b32_e32 v182, s26, v1
	v_or_b32_e32 v183, s27, v2
	v_or_b32_e32 v184, s28, v1
	v_or_b32_e32 v185, s29, v2
	v_or_b32_e32 v186, s16, v1
	v_or_b32_e32 v187, s17, v2
	v_add_u32_e32 v140, s7, v172
	v_ashrrev_i32_e32 v143, 31, v142
	v_add_u32_e32 v144, s7, v174
; __device__ __forceinline__ void p0_transpose_item(const float* W, int N, bf16_t* WT, int ldt, int k0, int n0, int nrow0, int kcol0, LAS float* scr, int lane) {
; #pragma unroll 8
;     for (int i = 0; i < 32; ++i) { const int kk = 2 * i + (lane >> 5); scr[kk * 33 + (lane & 31)] = W[(size_t)(k0 + kk) * N + n0 + (lane & 31)]; }
	v_add_u32_e32 v146, s8, v175
	v_add_u32_e32 v148, s7, v176
	v_add_u32_e32 v150, s8, v177
	v_add_u32_e32 v152, s7, v178
	v_add_u32_e32 v154, s8, v179
	v_add_u32_e32 v156, s7, v180
	v_add_u32_e32 v158, s8, v181
	v_add_u32_e32 v160, s7, v182
	v_add_u32_e32 v162, s8, v183
	v_add_u32_e32 v164, s7, v184
	v_add_u32_e32 v166, s8, v185
	v_add_u32_e32 v168, s7, v186
	v_add_u32_e32 v170, s8, v187
	v_ashrrev_i32_e32 v141, 31, v140
	v_lshlrev_b64 v[142:143], 14, v[142:143]
	v_ashrrev_i32_e32 v147, 31, v146
	v_ashrrev_i32_e32 v145, 31, v144
	v_ashrrev_i32_e32 v151, 31, v150
	v_ashrrev_i32_e32 v149, 31, v148
	v_ashrrev_i32_e32 v155, 31, v154
	v_ashrrev_i32_e32 v153, 31, v152
	v_ashrrev_i32_e32 v159, 31, v158
	v_ashrrev_i32_e32 v157, 31, v156
	v_ashrrev_i32_e32 v163, 31, v162
	v_ashrrev_i32_e32 v161, 31, v160
	v_ashrrev_i32_e32 v167, 31, v166
	v_ashrrev_i32_e32 v165, 31, v164
	v_ashrrev_i32_e32 v171, 31, v170
	v_ashrrev_i32_e32 v169, 31, v168
	v_lshlrev_b64 v[140:141], 14, v[140:141]
	v_lshl_add_u64 v[142:143], v[10:11], 0, v[142:143]
	v_lshlrev_b64 v[144:145], 14, v[144:145]
	v_lshlrev_b64 v[146:147], 14, v[146:147]
	v_lshlrev_b64 v[148:149], 14, v[148:149]
	v_lshlrev_b64 v[150:151], 14, v[150:151]
	v_lshlrev_b64 v[152:153], 14, v[152:153]
	v_lshlrev_b64 v[154:155], 14, v[154:155]
	v_lshlrev_b64 v[156:157], 14, v[156:157]
	v_lshlrev_b64 v[158:159], 14, v[158:159]
	v_lshlrev_b64 v[160:161], 14, v[160:161]
	v_lshlrev_b64 v[162:163], 14, v[162:163]
	v_lshlrev_b64 v[164:165], 14, v[164:165]
	v_lshlrev_b64 v[166:167], 14, v[166:167]
	v_lshlrev_b64 v[168:169], 14, v[168:169]
	v_lshlrev_b64 v[170:171], 14, v[170:171]
	v_lshl_add_u64 v[140:141], v[10:11], 0, v[140:141]
	v_lshl_add_u64 v[146:147], v[10:11], 0, v[146:147]
	v_lshl_add_u64 v[144:145], v[10:11], 0, v[144:145]
	v_lshl_add_u64 v[150:151], v[10:11], 0, v[150:151]
	v_lshl_add_u64 v[148:149], v[10:11], 0, v[148:149]
	v_lshl_add_u64 v[154:155], v[10:11], 0, v[154:155]
	v_lshl_add_u64 v[152:153], v[10:11], 0, v[152:153]
	v_lshl_add_u64 v[158:159], v[10:11], 0, v[158:159]
	v_lshl_add_u64 v[156:157], v[10:11], 0, v[156:157]
	v_lshl_add_u64 v[162:163], v[10:11], 0, v[162:163]
	v_lshl_add_u64 v[160:161], v[10:11], 0, v[160:161]
	v_lshl_add_u64 v[166:167], v[10:11], 0, v[166:167]
	v_lshl_add_u64 v[164:165], v[10:11], 0, v[164:165]
	v_lshl_add_u64 v[170:171], v[10:11], 0, v[170:171]
	v_lshl_add_u64 v[168:169], v[10:11], 0, v[168:169]
	global_load_dword v188, v[142:143], off
	global_load_dword v189, v[140:141], off
	global_load_dword v190, v[146:147], off
	global_load_dword v191, v[144:145], off
	global_load_dword v192, v[150:151], off
	global_load_dword v193, v[148:149], off
	global_load_dword v194, v[154:155], off
	global_load_dword v195, v[152:153], off
	global_load_dword v196, v[158:159], off
	global_load_dword v197, v[156:157], off
	global_load_dword v198, v[162:163], off
	global_load_dword v199, v[160:161], off
	global_load_dword v200, v[166:167], off
	global_load_dword v201, v[164:165], off
	global_load_dword v202, v[170:171], off
	global_load_dword v203, v[168:169], off
	s_add_i32 s14, s14, 16
	s_add_i32 s15, s15, 16
	s_add_i32 s9, s9, -16
	v_mad_u64_u32 v[140:141], s[16:17], v173, s13, v[4:5]
	s_cmp_lg_u32 s9, 0
	v_mad_u64_u32 v[142:143], s[16:17], v172, s13, v[4:5]
	v_mad_u64_u32 v[144:145], s[16:17], v175, s13, v[4:5]
	v_mad_u64_u32 v[146:147], s[16:17], v174, s13, v[4:5]
	v_mad_u64_u32 v[148:149], s[16:17], v177, s13, v[4:5]
	v_mad_u64_u32 v[150:151], s[16:17], v176, s13, v[4:5]
	v_mad_u64_u32 v[152:153], s[16:17], v179, s13, v[4:5]
	v_mad_u64_u32 v[154:155], s[16:17], v178, s13, v[4:5]
	v_mad_u64_u32 v[156:157], s[16:17], v181, s13, v[4:5]
	v_mad_u64_u32 v[158:159], s[16:17], v180, s13, v[4:5]
	v_mad_u64_u32 v[160:161], s[16:17], v183, s13, v[4:5]
	v_mad_u64_u32 v[162:163], s[16:17], v182, s13, v[4:5]
	v_mad_u64_u32 v[164:165], s[16:17], v185, s13, v[4:5]
	v_mad_u64_u32 v[166:167], s[16:17], v184, s13, v[4:5]
	v_mad_u64_u32 v[168:169], s[16:17], v187, s13, v[4:5]
	v_mad_u64_u32 v[170:171], s[16:17], v186, s13, v[4:5]
	s_waitcnt vmcnt(31)
; #define LAS __attribute__((address_space(3)))
; __device__ __forceinline__ unsigned cvt_pk_bf16(float lo, float hi) { unsigned r; asm volatile("v_cvt_pk_bf16_f32 %0, %1, %2" : "=v"(r) : "v"(lo), "v"(hi)); return r; }
; #define LDS_WAIT() asm volatile("s_waitcnt lgkmcnt(0)" ::: "memory")
; __device__ __forceinline__ void p0_transpose_item(const float* W, int N, bf16_t* WT, int ldt, int k0, int n0, int nrow0, int kcol0, LAS float* scr, int lane) {
; #pragma unroll 8
;     for (int i = 0; i < 32; ++i) { const int kk = 2 * i + (lane >> 5); scr[kk * 33 + (lane & 31)] = W[(size_t)(k0 + kk) * N + n0 + (lane & 31)]; }
;     LDS_WAIT(); asm volatile("" ::: "memory");
;     const int c = lane & 7;
; #pragma unroll
;     for (int j = 0; j < 4; ++j) { const int n = (lane >> 3) + 8 * j; const LAS float* s = scr + (8 * c) * 33 + n;
;         u32x4 o; o.x = cvt_pk_bf16(s[0 * 33], s[1 * 33]); o.y = cvt_pk_bf16(s[2 * 33], s[3 * 33]); o.z = cvt_pk_bf16(s[4 * 33], s[5 * 33]); o.w = cvt_pk_bf16(s[6 * 33], s[7 * 33]);
;         *(u32x4*)(WT + (size_t)(nrow0 + n) * ldt + kcol0 + k0 + 8 * c) = o; }
;     LDS_WAIT(); asm volatile("" ::: "memory");
; }
; __device__ __forceinline__ void p0_prologue(const Frame& F) {
;     ...
;                 for (int it = first; it < nitems; it += NGW) { const int kb = it / nblk, nbk = it % nblk, n0 = nbk * 32;
;                     const int nrow0 = (jb == 0 && n0 >= 3392) ? n0 + 192 : n0;
;                     p0_transpose_item(W, J.N, WT, J.ldt, kb * 64, n0, nrow0, J.kcol0, scr, F.lane); }
	ds_write_b32 v18, v66
	s_waitcnt vmcnt(30)
	ds_write_b32 v20, v67
	s_waitcnt vmcnt(29)
	ds_write_b32 v22, v68
	s_waitcnt vmcnt(28)
	ds_write_b32 v24, v69
	s_waitcnt vmcnt(27)
	ds_write_b32 v26, v70
	s_waitcnt vmcnt(26)
	ds_write_b32 v28, v71
	s_waitcnt vmcnt(25)
	ds_write_b32 v30, v72
	s_waitcnt vmcnt(24)
	ds_write_b32 v32, v73
	s_waitcnt vmcnt(23)
	ds_write_b32 v34, v74
	s_waitcnt vmcnt(22)
	ds_write_b32 v36, v75
	s_waitcnt vmcnt(21)
	ds_write_b32 v38, v76
	s_waitcnt vmcnt(20)
	ds_write_b32 v40, v77
	s_waitcnt vmcnt(19)
	ds_write_b32 v42, v78
	s_waitcnt vmcnt(18)
	ds_write_b32 v44, v79
	s_waitcnt vmcnt(17)
	ds_write_b32 v46, v80
	s_waitcnt vmcnt(16)
	ds_write_b32 v48, v81
	s_waitcnt vmcnt(15)
	ds_write_b32 v140, v188
	s_waitcnt vmcnt(14)
	ds_write_b32 v142, v189
	s_waitcnt vmcnt(13)
	ds_write_b32 v144, v190
	s_waitcnt vmcnt(12)
	ds_write_b32 v146, v191
	s_waitcnt vmcnt(11)
	ds_write_b32 v148, v192
	s_waitcnt vmcnt(10)
	ds_write_b32 v150, v193
	s_waitcnt vmcnt(9)
	ds_write_b32 v152, v194
	s_waitcnt vmcnt(8)
	ds_write_b32 v154, v195
	s_waitcnt vmcnt(7)
	ds_write_b32 v156, v196
	s_waitcnt vmcnt(6)
	ds_write_b32 v158, v197
	s_waitcnt vmcnt(5)
	ds_write_b32 v160, v198
	s_waitcnt vmcnt(4)
	ds_write_b32 v162, v199
	s_waitcnt vmcnt(3)
	ds_write_b32 v164, v200
	s_waitcnt vmcnt(2)
	ds_write_b32 v166, v201
	s_waitcnt vmcnt(1)
	ds_write_b32 v168, v202
	s_waitcnt vmcnt(0)
	ds_write_b32 v170, v203
	s_waitcnt lgkmcnt(0)
	v_or_b32_e32 v22, s6, v3
	ds_read2_b32 v[10:11], v5 offset1:33
	s_ashr_i32 s9, s8, 31
	v_ashrrev_i32_e32 v23, 31, v22
	s_waitcnt lgkmcnt(0)
	v_cvt_pk_bf16_f32 v18, v10, v11
	ds_read2_b32 v[10:11], v5 offset0:66 offset1:99
	v_lshl_add_u64 v[24:25], s[8:9], 1, v[8:9]
	v_lshlrev_b64 v[22:23], 10, v[22:23]
	s_waitcnt lgkmcnt(0)
	v_cvt_pk_bf16_f32 v19, v10, v11
	ds_read2_b32 v[10:11], v5 offset0:132 offset1:165
	v_lshl_add_u64 v[22:23], v[24:25], 0, v[22:23]
	s_waitcnt lgkmcnt(0)
	v_cvt_pk_bf16_f32 v20, v10, v11
	ds_read2_b32 v[10:11], v5 offset0:198 offset1:231
	s_waitcnt lgkmcnt(0)
	v_cvt_pk_bf16_f32 v21, v10, v11
	global_store_dwordx4 v[22:23], v[18:21], off
	v_or_b32_e32 v22, s6, v13
	ds_read2_b32 v[10:11], v5 offset0:8 offset1:41
	v_ashrrev_i32_e32 v23, 31, v22
	s_waitcnt lgkmcnt(0)
	v_cvt_pk_bf16_f32 v18, v10, v11
	ds_read2_b32 v[10:11], v5 offset0:74 offset1:107
	v_lshlrev_b64 v[22:23], 10, v[22:23]
	s_waitcnt lgkmcnt(0)
	v_cvt_pk_bf16_f32 v19, v10, v11
	ds_read2_b32 v[10:11], v5 offset0:140 offset1:173
	v_lshl_add_u64 v[22:23], v[24:25], 0, v[22:23]
	s_waitcnt lgkmcnt(0)
	v_cvt_pk_bf16_f32 v20, v10, v11
	ds_read2_b32 v[10:11], v5 offset0:206 offset1:239
	s_waitcnt lgkmcnt(0)
	v_cvt_pk_bf16_f32 v21, v10, v11
	global_store_dwordx4 v[22:23], v[18:21], off
	v_or_b32_e32 v22, s6, v16
	ds_read2_b32 v[10:11], v5 offset0:16 offset1:49
	v_ashrrev_i32_e32 v23, 31, v22
	s_waitcnt lgkmcnt(0)
	v_cvt_pk_bf16_f32 v18, v10, v11
	ds_read2_b32 v[10:11], v5 offset0:82 offset1:115
	v_lshlrev_b64 v[22:23], 10, v[22:23]
	s_waitcnt lgkmcnt(0)
	v_cvt_pk_bf16_f32 v19, v10, v11
	ds_read2_b32 v[10:11], v5 offset0:148 offset1:181
	v_lshl_add_u64 v[22:23], v[24:25], 0, v[22:23]
	s_waitcnt lgkmcnt(0)
	v_cvt_pk_bf16_f32 v20, v10, v11
	ds_read2_b32 v[10:11], v5 offset0:214 offset1:247
	s_waitcnt lgkmcnt(0)
	v_cvt_pk_bf16_f32 v21, v10, v11
	global_store_dwordx4 v[22:23], v[18:21], off
	v_or_b32_e32 v22, s6, v17
	ds_read2_b32 v[10:11], v5 offset0:24 offset1:57
	v_ashrrev_i32_e32 v23, 31, v22
	s_waitcnt lgkmcnt(0)
	v_cvt_pk_bf16_f32 v18, v10, v11
	ds_read2_b32 v[10:11], v5 offset0:90 offset1:123
	v_lshlrev_b64 v[22:23], 10, v[22:23]
	s_waitcnt lgkmcnt(0)
	v_cvt_pk_bf16_f32 v19, v10, v11
	ds_read2_b32 v[10:11], v5 offset0:156 offset1:189
	v_lshl_add_u64 v[22:23], v[24:25], 0, v[22:23]
	s_waitcnt lgkmcnt(0)
	v_cvt_pk_bf16_f32 v20, v10, v11
	ds_read2_b32 v[10:11], v5 offset0:222 offset1:255
	s_waitcnt lgkmcnt(0)
	v_cvt_pk_bf16_f32 v21, v10, v11
	global_store_dwordx4 v[22:23], v[18:21], off
	s_waitcnt lgkmcnt(0)
	s_add_i32 s12, s12, s3
	s_cmpk_lt_i32 s12, 0x400
	s_cbranch_scc1 .LBB0_39

; __device__ __forceinline__ void p0_transpose_item(const float* W, int N, bf16_t* WT, int ldt, int k0, int n0, int nrow0, int kcol0, LAS float* scr, int lane) {
; #pragma unroll 8
;     for (int i = 0; i < 32; ++i) { const int kk = 2 * i + (lane >> 5); scr[kk * 33 + (lane & 31)] = W[(size_t)(k0 + kk) * N + n0 + (lane & 31)]; }
.LBB0_45:
	s_lshl_b32 s16, s15, 1
	s_lshl_b32 s17, s14, 1
	v_or_b32_e32 v50, s16, v1
	v_or_b32_e32 v51, s17, v2
	s_add_i32 s18, s16, 4
	s_add_i32 s19, s17, 4
	s_add_i32 s20, s16, 8
	s_add_i32 s21, s17, 8
	s_add_i32 s22, s16, 12
	s_add_i32 s23, s17, 12
	s_add_i32 s24, s16, 16
	s_add_i32 s25, s17, 16
	s_add_i32 s26, s16, 20
	s_add_i32 s27, s17, 20
	s_add_i32 s28, s16, 24
	s_add_i32 s29, s17, 24
	s_add_i32 s16, s16, 28
	s_add_i32 s17, s17, 28
	v_add_u32_e32 v20, s8, v51
	v_or_b32_e32 v52, s18, v1
	v_or_b32_e32 v53, s19, v2
	v_or_b32_e32 v54, s20, v1
	v_or_b32_e32 v55, s21, v2
	v_or_b32_e32 v56, s22, v1
	v_or_b32_e32 v57, s23, v2
	v_or_b32_e32 v58, s24, v1
	v_or_b32_e32 v59, s25, v2
	v_or_b32_e32 v60, s26, v1
	v_or_b32_e32 v61, s27, v2
	v_or_b32_e32 v62, s28, v1
	v_or_b32_e32 v63, s29, v2
	v_or_b32_e32 v64, s16, v1
	v_or_b32_e32 v65, s17, v2
	v_add_u32_e32 v18, s7, v50
	v_ashrrev_i32_e32 v21, 31, v20
	v_add_u32_e32 v22, s7, v52
	v_add_u32_e32 v24, s8, v53
	v_add_u32_e32 v26, s7, v54
	v_add_u32_e32 v28, s8, v55
	v_add_u32_e32 v30, s7, v56
	v_add_u32_e32 v32, s8, v57
	v_add_u32_e32 v34, s7, v58
	v_add_u32_e32 v36, s8, v59
	v_add_u32_e32 v38, s7, v60
	v_add_u32_e32 v40, s8, v61
	v_add_u32_e32 v42, s7, v62
	v_add_u32_e32 v44, s8, v63
	v_add_u32_e32 v46, s7, v64
	v_add_u32_e32 v48, s8, v65
	v_ashrrev_i32_e32 v19, 31, v18
	v_lshlrev_b64 v[20:21], 12, v[20:21]
	v_ashrrev_i32_e32 v25, 31, v24
	v_ashrrev_i32_e32 v23, 31, v22
	v_ashrrev_i32_e32 v29, 31, v28
	v_ashrrev_i32_e32 v27, 31, v26
	v_ashrrev_i32_e32 v33, 31, v32
	v_ashrrev_i32_e32 v31, 31, v30
	v_ashrrev_i32_e32 v37, 31, v36
	v_ashrrev_i32_e32 v35, 31, v34
	v_ashrrev_i32_e32 v41, 31, v40
	v_ashrrev_i32_e32 v39, 31, v38
	v_ashrrev_i32_e32 v45, 31, v44
	v_ashrrev_i32_e32 v43, 31, v42
	v_ashrrev_i32_e32 v49, 31, v48
	v_ashrrev_i32_e32 v47, 31, v46
	v_lshlrev_b64 v[18:19], 12, v[18:19]
	v_lshl_add_u64 v[20:21], v[10:11], 0, v[20:21]
	v_lshlrev_b64 v[22:23], 12, v[22:23]
	v_lshlrev_b64 v[24:25], 12, v[24:25]
	v_lshlrev_b64 v[26:27], 12, v[26:27]
	v_lshlrev_b64 v[28:29], 12, v[28:29]
	v_lshlrev_b64 v[30:31], 12, v[30:31]
	v_lshlrev_b64 v[32:33], 12, v[32:33]
	v_lshlrev_b64 v[34:35], 12, v[34:35]
	v_lshlrev_b64 v[36:37], 12, v[36:37]
	v_lshlrev_b64 v[38:39], 12, v[38:39]
	v_lshlrev_b64 v[40:41], 12, v[40:41]
	v_lshlrev_b64 v[42:43], 12, v[42:43]
	v_lshlrev_b64 v[44:45], 12, v[44:45]
	v_lshlrev_b64 v[46:47], 12, v[46:47]
	v_lshlrev_b64 v[48:49], 12, v[48:49]
	v_lshl_add_u64 v[18:19], v[10:11], 0, v[18:19]
	v_lshl_add_u64 v[24:25], v[10:11], 0, v[24:25]
	v_lshl_add_u64 v[22:23], v[10:11], 0, v[22:23]
	v_lshl_add_u64 v[28:29], v[10:11], 0, v[28:29]
	v_lshl_add_u64 v[26:27], v[10:11], 0, v[26:27]
	v_lshl_add_u64 v[32:33], v[10:11], 0, v[32:33]
	v_lshl_add_u64 v[30:31], v[10:11], 0, v[30:31]
	v_lshl_add_u64 v[36:37], v[10:11], 0, v[36:37]
	v_lshl_add_u64 v[34:35], v[10:11], 0, v[34:35]
	v_lshl_add_u64 v[40:41], v[10:11], 0, v[40:41]
	v_lshl_add_u64 v[38:39], v[10:11], 0, v[38:39]
	v_lshl_add_u64 v[44:45], v[10:11], 0, v[44:45]
	v_lshl_add_u64 v[42:43], v[10:11], 0, v[42:43]
	v_lshl_add_u64 v[48:49], v[10:11], 0, v[48:49]
	v_lshl_add_u64 v[46:47], v[10:11], 0, v[46:47]
	global_load_dword v66, v[20:21], off
	global_load_dword v67, v[18:19], off
	global_load_dword v68, v[24:25], off
	global_load_dword v69, v[22:23], off
	global_load_dword v70, v[28:29], off
	global_load_dword v71, v[26:27], off
	global_load_dword v72, v[32:33], off
	global_load_dword v73, v[30:31], off
	global_load_dword v74, v[36:37], off
	global_load_dword v75, v[34:35], off
	global_load_dword v76, v[40:41], off
	global_load_dword v77, v[38:39], off
	global_load_dword v78, v[44:45], off
	global_load_dword v79, v[42:43], off
	global_load_dword v80, v[48:49], off
	global_load_dword v81, v[46:47], off
	s_add_i32 s14, s14, 16
	s_add_i32 s15, s15, 16
	s_add_i32 s9, s9, -16
	v_mad_u64_u32 v[18:19], s[16:17], v51, s13, v[4:5]
	s_cmp_lg_u32 s9, 0
	v_mad_u64_u32 v[20:21], s[16:17], v50, s13, v[4:5]
	v_mad_u64_u32 v[22:23], s[16:17], v53, s13, v[4:5]
	v_mad_u64_u32 v[24:25], s[16:17], v52, s13, v[4:5]
	v_mad_u64_u32 v[26:27], s[16:17], v55, s13, v[4:5]
	v_mad_u64_u32 v[28:29], s[16:17], v54, s13, v[4:5]
	v_mad_u64_u32 v[30:31], s[16:17], v57, s13, v[4:5]
	v_mad_u64_u32 v[32:33], s[16:17], v56, s13, v[4:5]
	v_mad_u64_u32 v[34:35], s[16:17], v59, s13, v[4:5]
	v_mad_u64_u32 v[36:37], s[16:17], v58, s13, v[4:5]
	v_mad_u64_u32 v[38:39], s[16:17], v61, s13, v[4:5]
	v_mad_u64_u32 v[40:41], s[16:17], v60, s13, v[4:5]
	v_mad_u64_u32 v[42:43], s[16:17], v63, s13, v[4:5]
	v_mad_u64_u32 v[44:45], s[16:17], v62, s13, v[4:5]
	v_mad_u64_u32 v[46:47], s[16:17], v65, s13, v[4:5]
	v_mad_u64_u32 v[48:49], s[16:17], v64, s13, v[4:5]
	s_nop 7
	s_lshl_b32 s16, s15, 1
	s_lshl_b32 s17, s14, 1
	v_or_b32_e32 v172, s16, v1
	v_or_b32_e32 v173, s17, v2
	s_add_i32 s18, s16, 4
	s_add_i32 s19, s17, 4
	s_add_i32 s20, s16, 8
	s_add_i32 s21, s17, 8
	s_add_i32 s22, s16, 12
	s_add_i32 s23, s17, 12
	s_add_i32 s24, s16, 16
	s_add_i32 s25, s17, 16
	s_add_i32 s26, s16, 20
	s_add_i32 s27, s17, 20
	s_add_i32 s28, s16, 24
	s_add_i32 s29, s17, 24
	s_add_i32 s16, s16, 28
	s_add_i32 s17, s17, 28
	v_add_u32_e32 v142, s8, v173
	v_or_b32_e32 v174, s18, v1
	v_or_b32_e32 v175, s19, v2
	v_or_b32_e32 v176, s20, v1
	v_or_b32_e32 v177, s21, v2
	v_or_b32_e32 v178, s22, v1
	v_or_b32_e32 v179, s23, v2
	v_or_b32_e32 v180, s24, v1
	v_or_b32_e32 v181, s25, v2
	v_or_b32_e32 v182, s26, v1
	v_or_b32_e32 v183, s27, v2
	v_or_b32_e32 v184, s28, v1
	v_or_b32_e32 v185, s29, v2
	v_or_b32_e32 v186, s16, v1
	v_or_b32_e32 v187, s17, v2
	v_add_u32_e32 v140, s7, v172
	v_ashrrev_i32_e32 v143, 31, v142
	v_add_u32_e32 v144, s7, v174
; __device__ __forceinline__ void p0_transpose_item(const float* W, int N, bf16_t* WT, int ldt, int k0, int n0, int nrow0, int kcol0, LAS float* scr, int lane) {
; #pragma unroll 8
;     for (int i = 0; i < 32; ++i) { const int kk = 2 * i + (lane >> 5); scr[kk * 33 + (lane & 31)] = W[(size_t)(k0 + kk) * N + n0 + (lane & 31)]; }
	v_add_u32_e32 v146, s8, v175
	v_add_u32_e32 v148, s7, v176
	v_add_u32_e32 v150, s8, v177
	v_add_u32_e32 v152, s7, v178
	v_add_u32_e32 v154, s8, v179
	v_add_u32_e32 v156, s7, v180
	v_add_u32_e32 v158, s8, v181
	v_add_u32_e32 v160, s7, v182
	v_add_u32_e32 v162, s8, v183
	v_add_u32_e32 v164, s7, v184
	v_add_u32_e32 v166, s8, v185
	v_add_u32_e32 v168, s7, v186
	v_add_u32_e32 v170, s8, v187
	v_ashrrev_i32_e32 v141, 31, v140
	v_lshlrev_b64 v[142:143], 12, v[142:143]
	v_ashrrev_i32_e32 v147, 31, v146
	v_ashrrev_i32_e32 v145, 31, v144
	v_ashrrev_i32_e32 v151, 31, v150
	v_ashrrev_i32_e32 v149, 31, v148
	v_ashrrev_i32_e32 v155, 31, v154
	v_ashrrev_i32_e32 v153, 31, v152
	v_ashrrev_i32_e32 v159, 31, v158
	v_ashrrev_i32_e32 v157, 31, v156
	v_ashrrev_i32_e32 v163, 31, v162
	v_ashrrev_i32_e32 v161, 31, v160
	v_ashrrev_i32_e32 v167, 31, v166
	v_ashrrev_i32_e32 v165, 31, v164
	v_ashrrev_i32_e32 v171, 31, v170
	v_ashrrev_i32_e32 v169, 31, v168
	v_lshlrev_b64 v[140:141], 12, v[140:141]
	v_lshl_add_u64 v[142:143], v[10:11], 0, v[142:143]
	v_lshlrev_b64 v[144:145], 12, v[144:145]
	v_lshlrev_b64 v[146:147], 12, v[146:147]
	v_lshlrev_b64 v[148:149], 12, v[148:149]
	v_lshlrev_b64 v[150:151], 12, v[150:151]
	v_lshlrev_b64 v[152:153], 12, v[152:153]
	v_lshlrev_b64 v[154:155], 12, v[154:155]
	v_lshlrev_b64 v[156:157], 12, v[156:157]
	v_lshlrev_b64 v[158:159], 12, v[158:159]
	v_lshlrev_b64 v[160:161], 12, v[160:161]
	v_lshlrev_b64 v[162:163], 12, v[162:163]
	v_lshlrev_b64 v[164:165], 12, v[164:165]
	v_lshlrev_b64 v[166:167], 12, v[166:167]
	v_lshlrev_b64 v[168:169], 12, v[168:169]
	v_lshlrev_b64 v[170:171], 12, v[170:171]
	v_lshl_add_u64 v[140:141], v[10:11], 0, v[140:141]
	v_lshl_add_u64 v[146:147], v[10:11], 0, v[146:147]
	v_lshl_add_u64 v[144:145], v[10:11], 0, v[144:145]
	v_lshl_add_u64 v[150:151], v[10:11], 0, v[150:151]
	v_lshl_add_u64 v[148:149], v[10:11], 0, v[148:149]
	v_lshl_add_u64 v[154:155], v[10:11], 0, v[154:155]
	v_lshl_add_u64 v[152:153], v[10:11], 0, v[152:153]
	v_lshl_add_u64 v[158:159], v[10:11], 0, v[158:159]
	v_lshl_add_u64 v[156:157], v[10:11], 0, v[156:157]
	v_lshl_add_u64 v[162:163], v[10:11], 0, v[162:163]
	v_lshl_add_u64 v[160:161], v[10:11], 0, v[160:161]
	v_lshl_add_u64 v[166:167], v[10:11], 0, v[166:167]
	v_lshl_add_u64 v[164:165], v[10:11], 0, v[164:165]
	v_lshl_add_u64 v[170:171], v[10:11], 0, v[170:171]
	v_lshl_add_u64 v[168:169], v[10:11], 0, v[168:169]
	global_load_dword v188, v[142:143], off
	global_load_dword v189, v[140:141], off
	global_load_dword v190, v[146:147], off
	global_load_dword v191, v[144:145], off
	global_load_dword v192, v[150:151], off
	global_load_dword v193, v[148:149], off
	global_load_dword v194, v[154:155], off
	global_load_dword v195, v[152:153], off
	global_load_dword v196, v[158:159], off
	global_load_dword v197, v[156:157], off
	global_load_dword v198, v[162:163], off
	global_load_dword v199, v[160:161], off
	global_load_dword v200, v[166:167], off
	global_load_dword v201, v[164:165], off
	global_load_dword v202, v[170:171], off
	global_load_dword v203, v[168:169], off
	s_add_i32 s14, s14, 16
	s_add_i32 s15, s15, 16
	s_add_i32 s9, s9, -16
	v_mad_u64_u32 v[140:141], s[16:17], v173, s13, v[4:5]
	s_cmp_lg_u32 s9, 0
	v_mad_u64_u32 v[142:143], s[16:17], v172, s13, v[4:5]
	v_mad_u64_u32 v[144:145], s[16:17], v175, s13, v[4:5]
	v_mad_u64_u32 v[146:147], s[16:17], v174, s13, v[4:5]
	v_mad_u64_u32 v[148:149], s[16:17], v177, s13, v[4:5]
	v_mad_u64_u32 v[150:151], s[16:17], v176, s13, v[4:5]
	v_mad_u64_u32 v[152:153], s[16:17], v179, s13, v[4:5]
	v_mad_u64_u32 v[154:155], s[16:17], v178, s13, v[4:5]
	v_mad_u64_u32 v[156:157], s[16:17], v181, s13, v[4:5]
	v_mad_u64_u32 v[158:159], s[16:17], v180, s13, v[4:5]
	v_mad_u64_u32 v[160:161], s[16:17], v183, s13, v[4:5]
	v_mad_u64_u32 v[162:163], s[16:17], v182, s13, v[4:5]
	v_mad_u64_u32 v[164:165], s[16:17], v185, s13, v[4:5]
	v_mad_u64_u32 v[166:167], s[16:17], v184, s13, v[4:5]
	v_mad_u64_u32 v[168:169], s[16:17], v187, s13, v[4:5]
	v_mad_u64_u32 v[170:171], s[16:17], v186, s13, v[4:5]
	s_waitcnt vmcnt(31)
; #define LAS __attribute__((address_space(3)))
; __device__ __forceinline__ unsigned cvt_pk_bf16(float lo, float hi) { unsigned r; asm volatile("v_cvt_pk_bf16_f32 %0, %1, %2" : "=v"(r) : "v"(lo), "v"(hi)); return r; }
; #define LDS_WAIT() asm volatile("s_waitcnt lgkmcnt(0)" ::: "memory")
; __device__ __forceinline__ void p0_transpose_item(const float* W, int N, bf16_t* WT, int ldt, int k0, int n0, int nrow0, int kcol0, LAS float* scr, int lane) {
; #pragma unroll 8
;     for (int i = 0; i < 32; ++i) { const int kk = 2 * i + (lane >> 5); scr[kk * 33 + (lane & 31)] = W[(size_t)(k0 + kk) * N + n0 + (lane & 31)]; }
;     LDS_WAIT(); asm volatile("" ::: "memory");
;     const int c = lane & 7;
; #pragma unroll
;     for (int j = 0; j < 4; ++j) { const int n = (lane >> 3) + 8 * j; const LAS float* s = scr + (8 * c) * 33 + n;
;         u32x4 o; o.x = cvt_pk_bf16(s[0 * 33], s[1 * 33]); o.y = cvt_pk_bf16(s[2 * 33], s[3 * 33]); o.z = cvt_pk_bf16(s[4 * 33], s[5 * 33]); o.w = cvt_pk_bf16(s[6 * 33], s[7 * 33]);
;         *(u32x4*)(WT + (size_t)(nrow0 + n) * ldt + kcol0 + k0 + 8 * c) = o; }
;     LDS_WAIT(); asm volatile("" ::: "memory");
; }
; __device__ __forceinline__ void p0_prologue(const Frame& F) {
;     ...
;                 for (int it = first; it < nitems; it += NGW) { const int kb = it / nblk, nbk = it % nblk, n0 = nbk * 32;
;                     const int nrow0 = (jb == 0 && n0 >= 3392) ? n0 + 192 : n0;
;                     p0_transpose_item(W, J.N, WT, J.ldt, kb * 64, n0, nrow0, J.kcol0, scr, F.lane); }
	ds_write_b32 v18, v66
	s_waitcnt vmcnt(30)
	ds_write_b32 v20, v67
	s_waitcnt vmcnt(29)
	ds_write_b32 v22, v68
	s_waitcnt vmcnt(28)
	ds_write_b32 v24, v69
	s_waitcnt vmcnt(27)
	ds_write_b32 v26, v70
	s_waitcnt vmcnt(26)
	ds_write_b32 v28, v71
	s_waitcnt vmcnt(25)
	ds_write_b32 v30, v72
	s_waitcnt vmcnt(24)
	ds_write_b32 v32, v73
	s_waitcnt vmcnt(23)
	ds_write_b32 v34, v74
	s_waitcnt vmcnt(22)
	ds_write_b32 v36, v75
	s_waitcnt vmcnt(21)
	ds_write_b32 v38, v76
	s_waitcnt vmcnt(20)
	ds_write_b32 v40, v77
	s_waitcnt vmcnt(19)
	ds_write_b32 v42, v78
	s_waitcnt vmcnt(18)
	ds_write_b32 v44, v79
	s_waitcnt vmcnt(17)
	ds_write_b32 v46, v80
	s_waitcnt vmcnt(16)
	ds_write_b32 v48, v81
	s_waitcnt vmcnt(15)
	ds_write_b32 v140, v188
	s_waitcnt vmcnt(14)
	ds_write_b32 v142, v189
	s_waitcnt vmcnt(13)
	ds_write_b32 v144, v190
	s_waitcnt vmcnt(12)
	ds_write_b32 v146, v191
	s_waitcnt vmcnt(11)
	ds_write_b32 v148, v192
	s_waitcnt vmcnt(10)
	ds_write_b32 v150, v193
	s_waitcnt vmcnt(9)
	ds_write_b32 v152, v194
	s_waitcnt vmcnt(8)
	ds_write_b32 v154, v195
	s_waitcnt vmcnt(7)
	ds_write_b32 v156, v196
	s_waitcnt vmcnt(6)
	ds_write_b32 v158, v197
	s_waitcnt vmcnt(5)
	ds_write_b32 v160, v198
	s_waitcnt vmcnt(4)
	ds_write_b32 v162, v199
	s_waitcnt vmcnt(3)
	ds_write_b32 v164, v200
	s_waitcnt vmcnt(2)
	ds_write_b32 v166, v201
	s_waitcnt vmcnt(1)
	ds_write_b32 v168, v202
	s_waitcnt vmcnt(0)
	ds_write_b32 v170, v203
	s_waitcnt lgkmcnt(0)
	v_or_b32_e32 v22, s6, v3
	ds_read2_b32 v[10:11], v5 offset1:33
	s_ashr_i32 s9, s8, 31
	v_ashrrev_i32_e32 v23, 31, v22
	s_waitcnt lgkmcnt(0)
	v_cvt_pk_bf16_f32 v18, v10, v11
	ds_read2_b32 v[10:11], v5 offset0:66 offset1:99
	v_lshl_add_u64 v[24:25], s[8:9], 1, v[8:9]
	v_lshlrev_b64 v[22:23], 11, v[22:23]
	s_waitcnt lgkmcnt(0)
	v_cvt_pk_bf16_f32 v19, v10, v11
	ds_read2_b32 v[10:11], v5 offset0:132 offset1:165
	v_lshl_add_u64 v[22:23], v[24:25], 0, v[22:23]
	s_waitcnt lgkmcnt(0)
	v_cvt_pk_bf16_f32 v20, v10, v11
	ds_read2_b32 v[10:11], v5 offset0:198 offset1:231
	s_waitcnt lgkmcnt(0)
	v_cvt_pk_bf16_f32 v21, v10, v11
	global_store_dwordx4 v[22:23], v[18:21], off
	v_or_b32_e32 v22, s6, v13
	ds_read2_b32 v[10:11], v5 offset0:8 offset1:41
	v_ashrrev_i32_e32 v23, 31, v22
	s_waitcnt lgkmcnt(0)
	v_cvt_pk_bf16_f32 v18, v10, v11
	ds_read2_b32 v[10:11], v5 offset0:74 offset1:107
	v_lshlrev_b64 v[22:23], 11, v[22:23]
	s_waitcnt lgkmcnt(0)
	v_cvt_pk_bf16_f32 v19, v10, v11
	ds_read2_b32 v[10:11], v5 offset0:140 offset1:173
	v_lshl_add_u64 v[22:23], v[24:25], 0, v[22:23]
	s_waitcnt lgkmcnt(0)
	v_cvt_pk_bf16_f32 v20, v10, v11
	ds_read2_b32 v[10:11], v5 offset0:206 offset1:239
	s_waitcnt lgkmcnt(0)
	v_cvt_pk_bf16_f32 v21, v10, v11
	global_store_dwordx4 v[22:23], v[18:21], off
	v_or_b32_e32 v22, s6, v16
	ds_read2_b32 v[10:11], v5 offset0:16 offset1:49
	v_ashrrev_i32_e32 v23, 31, v22
	s_waitcnt lgkmcnt(0)
	v_cvt_pk_bf16_f32 v18, v10, v11
	ds_read2_b32 v[10:11], v5 offset0:82 offset1:115
	v_lshlrev_b64 v[22:23], 11, v[22:23]
	s_waitcnt lgkmcnt(0)
	v_cvt_pk_bf16_f32 v19, v10, v11
	ds_read2_b32 v[10:11], v5 offset0:148 offset1:181
	v_lshl_add_u64 v[22:23], v[24:25], 0, v[22:23]
	s_waitcnt lgkmcnt(0)
	v_cvt_pk_bf16_f32 v20, v10, v11
	ds_read2_b32 v[10:11], v5 offset0:214 offset1:247
	s_waitcnt lgkmcnt(0)
	v_cvt_pk_bf16_f32 v21, v10, v11
	global_store_dwordx4 v[22:23], v[18:21], off
	v_or_b32_e32 v22, s6, v17
	ds_read2_b32 v[10:11], v5 offset0:24 offset1:57
	v_ashrrev_i32_e32 v23, 31, v22
	s_waitcnt lgkmcnt(0)
	v_cvt_pk_bf16_f32 v18, v10, v11
	ds_read2_b32 v[10:11], v5 offset0:90 offset1:123
	v_lshlrev_b64 v[22:23], 11, v[22:23]
	s_waitcnt lgkmcnt(0)
	v_cvt_pk_bf16_f32 v19, v10, v11
	ds_read2_b32 v[10:11], v5 offset0:156 offset1:189
	v_lshl_add_u64 v[22:23], v[24:25], 0, v[22:23]
	s_waitcnt lgkmcnt(0)
	v_cvt_pk_bf16_f32 v20, v10, v11
	ds_read2_b32 v[10:11], v5 offset0:222 offset1:255
	s_waitcnt lgkmcnt(0)
	v_cvt_pk_bf16_f32 v21, v10, v11
	global_store_dwordx4 v[22:23], v[18:21], off
	s_waitcnt lgkmcnt(0)
	s_add_i32 s12, s12, s3
	s_cmpk_lt_i32 s12, 0x200
	s_cbranch_scc1 .LBB0_44

; __device__ __forceinline__ void p0_transpose_item(const float* W, int N, bf16_t* WT, int ldt, int k0, int n0, int nrow0, int kcol0, LAS float* scr, int lane) {
; #pragma unroll 8
;     for (int i = 0; i < 32; ++i) { const int kk = 2 * i + (lane >> 5); scr[kk * 33 + (lane & 31)] = W[(size_t)(k0 + kk) * N + n0 + (lane & 31)]; }
.LBB0_55:
	s_lshl_b32 s16, s15, 1
	s_lshl_b32 s17, s14, 1
	v_or_b32_e32 v50, s16, v1
	v_or_b32_e32 v51, s17, v2
	s_add_i32 s18, s16, 4
	s_add_i32 s19, s17, 4
	s_add_i32 s20, s16, 8
	s_add_i32 s21, s17, 8
	s_add_i32 s22, s16, 12
	s_add_i32 s23, s17, 12
	s_add_i32 s24, s16, 16
	s_add_i32 s25, s17, 16
	s_add_i32 s26, s16, 20
	s_add_i32 s27, s17, 20
	s_add_i32 s28, s16, 24
	s_add_i32 s29, s17, 24
	s_add_i32 s16, s16, 28
	s_add_i32 s17, s17, 28
	v_add_u32_e32 v20, s8, v51
	v_or_b32_e32 v52, s18, v1
	v_or_b32_e32 v53, s19, v2
	v_or_b32_e32 v54, s20, v1
	v_or_b32_e32 v55, s21, v2
	v_or_b32_e32 v56, s22, v1
	v_or_b32_e32 v57, s23, v2
	v_or_b32_e32 v58, s24, v1
	v_or_b32_e32 v59, s25, v2
	v_or_b32_e32 v60, s26, v1
	v_or_b32_e32 v61, s27, v2
	v_or_b32_e32 v62, s28, v1
	v_or_b32_e32 v63, s29, v2
	v_or_b32_e32 v64, s16, v1
	v_or_b32_e32 v65, s17, v2
	v_add_u32_e32 v18, s7, v50
	v_ashrrev_i32_e32 v21, 31, v20
	v_add_u32_e32 v22, s7, v52
	v_add_u32_e32 v24, s8, v53
	v_add_u32_e32 v26, s7, v54
	v_add_u32_e32 v28, s8, v55
	v_add_u32_e32 v30, s7, v56
	v_add_u32_e32 v32, s8, v57
	v_add_u32_e32 v34, s7, v58
	v_add_u32_e32 v36, s8, v59
	v_add_u32_e32 v38, s7, v60
	v_add_u32_e32 v40, s8, v61
	v_add_u32_e32 v42, s7, v62
	v_add_u32_e32 v44, s8, v63
	v_add_u32_e32 v46, s7, v64
	v_add_u32_e32 v48, s8, v65
	v_ashrrev_i32_e32 v19, 31, v18
	v_lshlrev_b64 v[20:21], 14, v[20:21]
	v_ashrrev_i32_e32 v25, 31, v24
	v_ashrrev_i32_e32 v23, 31, v22
	v_ashrrev_i32_e32 v29, 31, v28
	v_ashrrev_i32_e32 v27, 31, v26
	v_ashrrev_i32_e32 v33, 31, v32
	v_ashrrev_i32_e32 v31, 31, v30
	v_ashrrev_i32_e32 v37, 31, v36
	v_ashrrev_i32_e32 v35, 31, v34
	v_ashrrev_i32_e32 v41, 31, v40
	v_ashrrev_i32_e32 v39, 31, v38
	v_ashrrev_i32_e32 v45, 31, v44
	v_ashrrev_i32_e32 v43, 31, v42
	v_ashrrev_i32_e32 v49, 31, v48
	v_ashrrev_i32_e32 v47, 31, v46
	v_lshlrev_b64 v[18:19], 14, v[18:19]
	v_lshl_add_u64 v[20:21], v[10:11], 0, v[20:21]
	v_lshlrev_b64 v[22:23], 14, v[22:23]
	v_lshlrev_b64 v[24:25], 14, v[24:25]
	v_lshlrev_b64 v[26:27], 14, v[26:27]
	v_lshlrev_b64 v[28:29], 14, v[28:29]
	v_lshlrev_b64 v[30:31], 14, v[30:31]
	v_lshlrev_b64 v[32:33], 14, v[32:33]
	v_lshlrev_b64 v[34:35], 14, v[34:35]
	v_lshlrev_b64 v[36:37], 14, v[36:37]
	v_lshlrev_b64 v[38:39], 14, v[38:39]
	v_lshlrev_b64 v[40:41], 14, v[40:41]
	v_lshlrev_b64 v[42:43], 14, v[42:43]
	v_lshlrev_b64 v[44:45], 14, v[44:45]
	v_lshlrev_b64 v[46:47], 14, v[46:47]
	v_lshlrev_b64 v[48:49], 14, v[48:49]
	v_lshl_add_u64 v[18:19], v[10:11], 0, v[18:19]
	v_lshl_add_u64 v[24:25], v[10:11], 0, v[24:25]
	v_lshl_add_u64 v[22:23], v[10:11], 0, v[22:23]
	v_lshl_add_u64 v[28:29], v[10:11], 0, v[28:29]
	v_lshl_add_u64 v[26:27], v[10:11], 0, v[26:27]
	v_lshl_add_u64 v[32:33], v[10:11], 0, v[32:33]
	v_lshl_add_u64 v[30:31], v[10:11], 0, v[30:31]
	v_lshl_add_u64 v[36:37], v[10:11], 0, v[36:37]
	v_lshl_add_u64 v[34:35], v[10:11], 0, v[34:35]
	v_lshl_add_u64 v[40:41], v[10:11], 0, v[40:41]
	v_lshl_add_u64 v[38:39], v[10:11], 0, v[38:39]
	v_lshl_add_u64 v[44:45], v[10:11], 0, v[44:45]
	v_lshl_add_u64 v[42:43], v[10:11], 0, v[42:43]
	v_lshl_add_u64 v[48:49], v[10:11], 0, v[48:49]
	v_lshl_add_u64 v[46:47], v[10:11], 0, v[46:47]
	global_load_dword v66, v[20:21], off
	global_load_dword v67, v[18:19], off
	global_load_dword v68, v[24:25], off
	global_load_dword v69, v[22:23], off
	global_load_dword v70, v[28:29], off
	global_load_dword v71, v[26:27], off
	global_load_dword v72, v[32:33], off
	global_load_dword v73, v[30:31], off
	global_load_dword v74, v[36:37], off
	global_load_dword v75, v[34:35], off
	global_load_dword v76, v[40:41], off
	global_load_dword v77, v[38:39], off
	global_load_dword v78, v[44:45], off
	global_load_dword v79, v[42:43], off
	global_load_dword v80, v[48:49], off
	global_load_dword v81, v[46:47], off
	s_add_i32 s14, s14, 16
	s_add_i32 s15, s15, 16
	s_add_i32 s9, s9, -16
	v_mad_u64_u32 v[18:19], s[16:17], v51, s13, v[4:5]
	s_cmp_lg_u32 s9, 0
	v_mad_u64_u32 v[20:21], s[16:17], v50, s13, v[4:5]
	v_mad_u64_u32 v[22:23], s[16:17], v53, s13, v[4:5]
	v_mad_u64_u32 v[24:25], s[16:17], v52, s13, v[4:5]
	v_mad_u64_u32 v[26:27], s[16:17], v55, s13, v[4:5]
	v_mad_u64_u32 v[28:29], s[16:17], v54, s13, v[4:5]
	v_mad_u64_u32 v[30:31], s[16:17], v57, s13, v[4:5]
	v_mad_u64_u32 v[32:33], s[16:17], v56, s13, v[4:5]
	v_mad_u64_u32 v[34:35], s[16:17], v59, s13, v[4:5]
	v_mad_u64_u32 v[36:37], s[16:17], v58, s13, v[4:5]
	v_mad_u64_u32 v[38:39], s[16:17], v61, s13, v[4:5]
	v_mad_u64_u32 v[40:41], s[16:17], v60, s13, v[4:5]
	v_mad_u64_u32 v[42:43], s[16:17], v63, s13, v[4:5]
	v_mad_u64_u32 v[44:45], s[16:17], v62, s13, v[4:5]
	v_mad_u64_u32 v[46:47], s[16:17], v65, s13, v[4:5]
	v_mad_u64_u32 v[48:49], s[16:17], v64, s13, v[4:5]
	s_nop 7
	s_lshl_b32 s16, s15, 1
	s_lshl_b32 s17, s14, 1
	v_or_b32_e32 v172, s16, v1
	v_or_b32_e32 v173, s17, v2
	s_add_i32 s18, s16, 4
	s_add_i32 s19, s17, 4
	s_add_i32 s20, s16, 8
	s_add_i32 s21, s17, 8
	s_add_i32 s22, s16, 12
	s_add_i32 s23, s17, 12
	s_add_i32 s24, s16, 16
	s_add_i32 s25, s17, 16
	s_add_i32 s26, s16, 20
	s_add_i32 s27, s17, 20
	s_add_i32 s28, s16, 24
	s_add_i32 s29, s17, 24
	s_add_i32 s16, s16, 28
	s_add_i32 s17, s17, 28
	v_add_u32_e32 v142, s8, v173
	v_or_b32_e32 v174, s18, v1
	v_or_b32_e32 v175, s19, v2
	v_or_b32_e32 v176, s20, v1
	v_or_b32_e32 v177, s21, v2
	v_or_b32_e32 v178, s22, v1
	v_or_b32_e32 v179, s23, v2
	v_or_b32_e32 v180, s24, v1
	v_or_b32_e32 v181, s25, v2
	v_or_b32_e32 v182, s26, v1
	v_or_b32_e32 v183, s27, v2
	v_or_b32_e32 v184, s28, v1
	v_or_b32_e32 v185, s29, v2
	v_or_b32_e32 v186, s16, v1
	v_or_b32_e32 v187, s17, v2
	v_add_u32_e32 v140, s7, v172
	v_ashrrev_i32_e32 v143, 31, v142
	v_add_u32_e32 v144, s7, v174
; __device__ __forceinline__ void p0_transpose_item(const float* W, int N, bf16_t* WT, int ldt, int k0, int n0, int nrow0, int kcol0, LAS float* scr, int lane) {
; #pragma unroll 8
;     for (int i = 0; i < 32; ++i) { const int kk = 2 * i + (lane >> 5); scr[kk * 33 + (lane & 31)] = W[(size_t)(k0 + kk) * N + n0 + (lane & 31)]; }
	v_add_u32_e32 v146, s8, v175
	v_add_u32_e32 v148, s7, v176
	v_add_u32_e32 v150, s8, v177
	v_add_u32_e32 v152, s7, v178
	v_add_u32_e32 v154, s8, v179
	v_add_u32_e32 v156, s7, v180
	v_add_u32_e32 v158, s8, v181
	v_add_u32_e32 v160, s7, v182
	v_add_u32_e32 v162, s8, v183
	v_add_u32_e32 v164, s7, v184
	v_add_u32_e32 v166, s8, v185
	v_add_u32_e32 v168, s7, v186
	v_add_u32_e32 v170, s8, v187
	v_ashrrev_i32_e32 v141, 31, v140
	v_lshlrev_b64 v[142:143], 14, v[142:143]
	v_ashrrev_i32_e32 v147, 31, v146
	v_ashrrev_i32_e32 v145, 31, v144
	v_ashrrev_i32_e32 v151, 31, v150
	v_ashrrev_i32_e32 v149, 31, v148
	v_ashrrev_i32_e32 v155, 31, v154
	v_ashrrev_i32_e32 v153, 31, v152
	v_ashrrev_i32_e32 v159, 31, v158
	v_ashrrev_i32_e32 v157, 31, v156
	v_ashrrev_i32_e32 v163, 31, v162
	v_ashrrev_i32_e32 v161, 31, v160
	v_ashrrev_i32_e32 v167, 31, v166
	v_ashrrev_i32_e32 v165, 31, v164
	v_ashrrev_i32_e32 v171, 31, v170
	v_ashrrev_i32_e32 v169, 31, v168
	v_lshlrev_b64 v[140:141], 14, v[140:141]
	v_lshl_add_u64 v[142:143], v[10:11], 0, v[142:143]
	v_lshlrev_b64 v[144:145], 14, v[144:145]
	v_lshlrev_b64 v[146:147], 14, v[146:147]
	v_lshlrev_b64 v[148:149], 14, v[148:149]
	v_lshlrev_b64 v[150:151], 14, v[150:151]
	v_lshlrev_b64 v[152:153], 14, v[152:153]
	v_lshlrev_b64 v[154:155], 14, v[154:155]
	v_lshlrev_b64 v[156:157], 14, v[156:157]
	v_lshlrev_b64 v[158:159], 14, v[158:159]
	v_lshlrev_b64 v[160:161], 14, v[160:161]
	v_lshlrev_b64 v[162:163], 14, v[162:163]
	v_lshlrev_b64 v[164:165], 14, v[164:165]
	v_lshlrev_b64 v[166:167], 14, v[166:167]
	v_lshlrev_b64 v[168:169], 14, v[168:169]
	v_lshlrev_b64 v[170:171], 14, v[170:171]
	v_lshl_add_u64 v[140:141], v[10:11], 0, v[140:141]
	v_lshl_add_u64 v[146:147], v[10:11], 0, v[146:147]
	v_lshl_add_u64 v[144:145], v[10:11], 0, v[144:145]
	v_lshl_add_u64 v[150:151], v[10:11], 0, v[150:151]
	v_lshl_add_u64 v[148:149], v[10:11], 0, v[148:149]
	v_lshl_add_u64 v[154:155], v[10:11], 0, v[154:155]
	v_lshl_add_u64 v[152:153], v[10:11], 0, v[152:153]
	v_lshl_add_u64 v[158:159], v[10:11], 0, v[158:159]
	v_lshl_add_u64 v[156:157], v[10:11], 0, v[156:157]
	v_lshl_add_u64 v[162:163], v[10:11], 0, v[162:163]
	v_lshl_add_u64 v[160:161], v[10:11], 0, v[160:161]
	v_lshl_add_u64 v[166:167], v[10:11], 0, v[166:167]
	v_lshl_add_u64 v[164:165], v[10:11], 0, v[164:165]
	v_lshl_add_u64 v[170:171], v[10:11], 0, v[170:171]
	v_lshl_add_u64 v[168:169], v[10:11], 0, v[168:169]
	global_load_dword v188, v[142:143], off
	global_load_dword v189, v[140:141], off
	global_load_dword v190, v[146:147], off
	global_load_dword v191, v[144:145], off
	global_load_dword v192, v[150:151], off
	global_load_dword v193, v[148:149], off
	global_load_dword v194, v[154:155], off
	global_load_dword v195, v[152:153], off
	global_load_dword v196, v[158:159], off
	global_load_dword v197, v[156:157], off
	global_load_dword v198, v[162:163], off
	global_load_dword v199, v[160:161], off
	global_load_dword v200, v[166:167], off
	global_load_dword v201, v[164:165], off
	global_load_dword v202, v[170:171], off
	global_load_dword v203, v[168:169], off
	s_add_i32 s14, s14, 16
	s_add_i32 s15, s15, 16
	s_add_i32 s9, s9, -16
	v_mad_u64_u32 v[140:141], s[16:17], v173, s13, v[4:5]
	s_cmp_lg_u32 s9, 0
	v_mad_u64_u32 v[142:143], s[16:17], v172, s13, v[4:5]
	v_mad_u64_u32 v[144:145], s[16:17], v175, s13, v[4:5]
	v_mad_u64_u32 v[146:147], s[16:17], v174, s13, v[4:5]
	v_mad_u64_u32 v[148:149], s[16:17], v177, s13, v[4:5]
	v_mad_u64_u32 v[150:151], s[16:17], v176, s13, v[4:5]
	v_mad_u64_u32 v[152:153], s[16:17], v179, s13, v[4:5]
	v_mad_u64_u32 v[154:155], s[16:17], v178, s13, v[4:5]
	v_mad_u64_u32 v[156:157], s[16:17], v181, s13, v[4:5]
	v_mad_u64_u32 v[158:159], s[16:17], v180, s13, v[4:5]
	v_mad_u64_u32 v[160:161], s[16:17], v183, s13, v[4:5]
	v_mad_u64_u32 v[162:163], s[16:17], v182, s13, v[4:5]
	v_mad_u64_u32 v[164:165], s[16:17], v185, s13, v[4:5]
	v_mad_u64_u32 v[166:167], s[16:17], v184, s13, v[4:5]
	v_mad_u64_u32 v[168:169], s[16:17], v187, s13, v[4:5]
	v_mad_u64_u32 v[170:171], s[16:17], v186, s13, v[4:5]
	s_waitcnt vmcnt(31)
; #define LAS __attribute__((address_space(3)))
; __device__ __forceinline__ unsigned cvt_pk_bf16(float lo, float hi) { unsigned r; asm volatile("v_cvt_pk_bf16_f32 %0, %1, %2" : "=v"(r) : "v"(lo), "v"(hi)); return r; }
; #define LDS_WAIT() asm volatile("s_waitcnt lgkmcnt(0)" ::: "memory")
; __device__ __forceinline__ void p0_transpose_item(const float* W, int N, bf16_t* WT, int ldt, int k0, int n0, int nrow0, int kcol0, LAS float* scr, int lane) {
; #pragma unroll 8
;     for (int i = 0; i < 32; ++i) { const int kk = 2 * i + (lane >> 5); scr[kk * 33 + (lane & 31)] = W[(size_t)(k0 + kk) * N + n0 + (lane & 31)]; }
;     LDS_WAIT(); asm volatile("" ::: "memory");
;     const int c = lane & 7;
; #pragma unroll
;     for (int j = 0; j < 4; ++j) { const int n = (lane >> 3) + 8 * j; const LAS float* s = scr + (8 * c) * 33 + n;
;         u32x4 o; o.x = cvt_pk_bf16(s[0 * 33], s[1 * 33]); o.y = cvt_pk_bf16(s[2 * 33], s[3 * 33]); o.z = cvt_pk_bf16(s[4 * 33], s[5 * 33]); o.w = cvt_pk_bf16(s[6 * 33], s[7 * 33]);
;         *(u32x4*)(WT + (size_t)(nrow0 + n) * ldt + kcol0 + k0 + 8 * c) = o; }
;     LDS_WAIT(); asm volatile("" ::: "memory");
; }
; __device__ __forceinline__ void p0_prologue(const Frame& F) {
;     ...
;                 for (int it = first; it < nitems; it += NGW) { const int kb = it / nblk, nbk = it % nblk, n0 = nbk * 32;
;                     const int nrow0 = (jb == 0 && n0 >= 3392) ? n0 + 192 : n0;
;                     p0_transpose_item(W, J.N, WT, J.ldt, kb * 64, n0, nrow0, J.kcol0, scr, F.lane); }
	ds_write_b32 v18, v66
	s_waitcnt vmcnt(30)
	ds_write_b32 v20, v67
	s_waitcnt vmcnt(29)
	ds_write_b32 v22, v68
	s_waitcnt vmcnt(28)
	ds_write_b32 v24, v69
	s_waitcnt vmcnt(27)
	ds_write_b32 v26, v70
	s_waitcnt vmcnt(26)
	ds_write_b32 v28, v71
	s_waitcnt vmcnt(25)
	ds_write_b32 v30, v72
	s_waitcnt vmcnt(24)
	ds_write_b32 v32, v73
	s_waitcnt vmcnt(23)
	ds_write_b32 v34, v74
	s_waitcnt vmcnt(22)
	ds_write_b32 v36, v75
	s_waitcnt vmcnt(21)
	ds_write_b32 v38, v76
	s_waitcnt vmcnt(20)
	ds_write_b32 v40, v77
	s_waitcnt vmcnt(19)
	ds_write_b32 v42, v78
	s_waitcnt vmcnt(18)
	ds_write_b32 v44, v79
	s_waitcnt vmcnt(17)
	ds_write_b32 v46, v80
	s_waitcnt vmcnt(16)
	ds_write_b32 v48, v81
	s_waitcnt vmcnt(15)
	ds_write_b32 v140, v188
	s_waitcnt vmcnt(14)
	ds_write_b32 v142, v189
	s_waitcnt vmcnt(13)
	ds_write_b32 v144, v190
	s_waitcnt vmcnt(12)
	ds_write_b32 v146, v191
	s_waitcnt vmcnt(11)
	ds_write_b32 v148, v192
	s_waitcnt vmcnt(10)
	ds_write_b32 v150, v193
	s_waitcnt vmcnt(9)
	ds_write_b32 v152, v194
	s_waitcnt vmcnt(8)
	ds_write_b32 v154, v195
	s_waitcnt vmcnt(7)
	ds_write_b32 v156, v196
	s_waitcnt vmcnt(6)
	ds_write_b32 v158, v197
	s_waitcnt vmcnt(5)
	ds_write_b32 v160, v198
	s_waitcnt vmcnt(4)
	ds_write_b32 v162, v199
	s_waitcnt vmcnt(3)
	ds_write_b32 v164, v200
	s_waitcnt vmcnt(2)
	ds_write_b32 v166, v201
	s_waitcnt vmcnt(1)
	ds_write_b32 v168, v202
	s_waitcnt vmcnt(0)
	ds_write_b32 v170, v203
	s_waitcnt lgkmcnt(0)
	v_or_b32_e32 v22, s6, v3
	ds_read2_b32 v[10:11], v5 offset1:33
	s_ashr_i32 s9, s8, 31
	v_ashrrev_i32_e32 v23, 31, v22
	s_waitcnt lgkmcnt(0)
	v_cvt_pk_bf16_f32 v18, v10, v11
	ds_read2_b32 v[10:11], v5 offset0:66 offset1:99
	v_lshl_add_u64 v[24:25], s[8:9], 1, v[8:9]
	v_lshlrev_b64 v[22:23], 13, v[22:23]
	s_waitcnt lgkmcnt(0)
	v_cvt_pk_bf16_f32 v19, v10, v11
	ds_read2_b32 v[10:11], v5 offset0:132 offset1:165
	v_lshl_add_u64 v[22:23], v[24:25], 0, v[22:23]
	s_waitcnt lgkmcnt(0)
	v_cvt_pk_bf16_f32 v20, v10, v11
	ds_read2_b32 v[10:11], v5 offset0:198 offset1:231
	s_waitcnt lgkmcnt(0)
	v_cvt_pk_bf16_f32 v21, v10, v11
	global_store_dwordx4 v[22:23], v[18:21], off
	v_or_b32_e32 v22, s6, v13
	ds_read2_b32 v[10:11], v5 offset0:8 offset1:41
	v_ashrrev_i32_e32 v23, 31, v22
	s_waitcnt lgkmcnt(0)
	v_cvt_pk_bf16_f32 v18, v10, v11
	ds_read2_b32 v[10:11], v5 offset0:74 offset1:107
	v_lshlrev_b64 v[22:23], 13, v[22:23]
	s_waitcnt lgkmcnt(0)
	v_cvt_pk_bf16_f32 v19, v10, v11
	ds_read2_b32 v[10:11], v5 offset0:140 offset1:173
	v_lshl_add_u64 v[22:23], v[24:25], 0, v[22:23]
	s_waitcnt lgkmcnt(0)
	v_cvt_pk_bf16_f32 v20, v10, v11
	ds_read2_b32 v[10:11], v5 offset0:206 offset1:239
	s_waitcnt lgkmcnt(0)
	v_cvt_pk_bf16_f32 v21, v10, v11
	global_store_dwordx4 v[22:23], v[18:21], off
	v_or_b32_e32 v22, s6, v16
	ds_read2_b32 v[10:11], v5 offset0:16 offset1:49
	v_ashrrev_i32_e32 v23, 31, v22
	s_waitcnt lgkmcnt(0)
	v_cvt_pk_bf16_f32 v18, v10, v11
	ds_read2_b32 v[10:11], v5 offset0:82 offset1:115
	v_lshlrev_b64 v[22:23], 13, v[22:23]
	s_waitcnt lgkmcnt(0)
	v_cvt_pk_bf16_f32 v19, v10, v11
	ds_read2_b32 v[10:11], v5 offset0:148 offset1:181
	v_lshl_add_u64 v[22:23], v[24:25], 0, v[22:23]
	s_waitcnt lgkmcnt(0)
	v_cvt_pk_bf16_f32 v20, v10, v11
	ds_read2_b32 v[10:11], v5 offset0:214 offset1:247
	s_waitcnt lgkmcnt(0)
	v_cvt_pk_bf16_f32 v21, v10, v11
	global_store_dwordx4 v[22:23], v[18:21], off
	v_or_b32_e32 v22, s6, v17
	ds_read2_b32 v[10:11], v5 offset0:24 offset1:57
	v_ashrrev_i32_e32 v23, 31, v22
	s_waitcnt lgkmcnt(0)
	v_cvt_pk_bf16_f32 v18, v10, v11
	ds_read2_b32 v[10:11], v5 offset0:90 offset1:123
	v_lshlrev_b64 v[22:23], 13, v[22:23]
	s_waitcnt lgkmcnt(0)
	v_cvt_pk_bf16_f32 v19, v10, v11
	ds_read2_b32 v[10:11], v5 offset0:156 offset1:189
	v_lshl_add_u64 v[22:23], v[24:25], 0, v[22:23]
	s_waitcnt lgkmcnt(0)
	v_cvt_pk_bf16_f32 v20, v10, v11
	ds_read2_b32 v[10:11], v5 offset0:222 offset1:255
	s_waitcnt lgkmcnt(0)
	v_cvt_pk_bf16_f32 v21, v10, v11
	global_store_dwordx4 v[22:23], v[18:21], off
	s_waitcnt lgkmcnt(0)
	s_add_i32 s12, s12, s3
	s_cmpk_lt_i32 s12, 0x800
	s_cbranch_scc1 .LBB0_54

; __device__ __forceinline__ void p0_transpose_item(const float* W, int N, bf16_t* WT, int ldt, int k0, int n0, int nrow0, int kcol0, LAS float* scr, int lane) {
; #pragma unroll 8
;     for (int i = 0; i < 32; ++i) { const int kk = 2 * i + (lane >> 5); scr[kk * 33 + (lane & 31)] = W[(size_t)(k0 + kk) * N + n0 + (lane & 31)]; }
.LBB0_60:
	s_lshl_b32 s16, s15, 1
	s_lshl_b32 s17, s14, 1
	v_or_b32_e32 v50, s16, v1
	v_or_b32_e32 v51, s17, v2
	s_add_i32 s18, s16, 4
	s_add_i32 s19, s17, 4
	s_add_i32 s20, s16, 8
	s_add_i32 s21, s17, 8
	s_add_i32 s22, s16, 12
	s_add_i32 s23, s17, 12
	s_add_i32 s24, s16, 16
	s_add_i32 s25, s17, 16
	s_add_i32 s26, s16, 20
	s_add_i32 s27, s17, 20
	s_add_i32 s28, s16, 24
	s_add_i32 s29, s17, 24
	s_add_i32 s16, s16, 28
	s_add_i32 s17, s17, 28
	v_add_u32_e32 v20, s8, v51
	v_or_b32_e32 v52, s18, v1
	v_or_b32_e32 v53, s19, v2
	v_or_b32_e32 v54, s20, v1
	v_or_b32_e32 v55, s21, v2
	v_or_b32_e32 v56, s22, v1
	v_or_b32_e32 v57, s23, v2
	v_or_b32_e32 v58, s24, v1
	v_or_b32_e32 v59, s25, v2
	v_or_b32_e32 v60, s26, v1
	v_or_b32_e32 v61, s27, v2
	v_or_b32_e32 v62, s28, v1
	v_or_b32_e32 v63, s29, v2
	v_or_b32_e32 v64, s16, v1
	v_or_b32_e32 v65, s17, v2
	v_add_u32_e32 v18, s7, v50
	v_ashrrev_i32_e32 v21, 31, v20
	v_add_u32_e32 v22, s7, v52
	v_add_u32_e32 v24, s8, v53
	v_add_u32_e32 v26, s7, v54
	v_add_u32_e32 v28, s8, v55
	v_add_u32_e32 v30, s7, v56
	v_add_u32_e32 v32, s8, v57
	v_add_u32_e32 v34, s7, v58
	v_add_u32_e32 v36, s8, v59
	v_add_u32_e32 v38, s7, v60
	v_add_u32_e32 v40, s8, v61
	v_add_u32_e32 v42, s7, v62
	v_add_u32_e32 v44, s8, v63
	v_add_u32_e32 v46, s7, v64
	v_add_u32_e32 v48, s8, v65
	v_ashrrev_i32_e32 v19, 31, v18
	v_lshlrev_b64 v[20:21], 14, v[20:21]
	v_ashrrev_i32_e32 v25, 31, v24
	v_ashrrev_i32_e32 v23, 31, v22
	v_ashrrev_i32_e32 v29, 31, v28
	v_ashrrev_i32_e32 v27, 31, v26
	v_ashrrev_i32_e32 v33, 31, v32
	v_ashrrev_i32_e32 v31, 31, v30
	v_ashrrev_i32_e32 v37, 31, v36
	v_ashrrev_i32_e32 v35, 31, v34
	v_ashrrev_i32_e32 v41, 31, v40
	v_ashrrev_i32_e32 v39, 31, v38
	v_ashrrev_i32_e32 v45, 31, v44
	v_ashrrev_i32_e32 v43, 31, v42
	v_ashrrev_i32_e32 v49, 31, v48
	v_ashrrev_i32_e32 v47, 31, v46
	v_lshlrev_b64 v[18:19], 14, v[18:19]
	v_lshl_add_u64 v[20:21], v[10:11], 0, v[20:21]
	v_lshlrev_b64 v[22:23], 14, v[22:23]
	v_lshlrev_b64 v[24:25], 14, v[24:25]
	v_lshlrev_b64 v[26:27], 14, v[26:27]
	v_lshlrev_b64 v[28:29], 14, v[28:29]
	v_lshlrev_b64 v[30:31], 14, v[30:31]
	v_lshlrev_b64 v[32:33], 14, v[32:33]
	v_lshlrev_b64 v[34:35], 14, v[34:35]
	v_lshlrev_b64 v[36:37], 14, v[36:37]
	v_lshlrev_b64 v[38:39], 14, v[38:39]
	v_lshlrev_b64 v[40:41], 14, v[40:41]
	v_lshlrev_b64 v[42:43], 14, v[42:43]
	v_lshlrev_b64 v[44:45], 14, v[44:45]
	v_lshlrev_b64 v[46:47], 14, v[46:47]
	v_lshlrev_b64 v[48:49], 14, v[48:49]
	v_lshl_add_u64 v[18:19], v[10:11], 0, v[18:19]
	v_lshl_add_u64 v[24:25], v[10:11], 0, v[24:25]
	v_lshl_add_u64 v[22:23], v[10:11], 0, v[22:23]
	v_lshl_add_u64 v[28:29], v[10:11], 0, v[28:29]
	v_lshl_add_u64 v[26:27], v[10:11], 0, v[26:27]
	v_lshl_add_u64 v[32:33], v[10:11], 0, v[32:33]
	v_lshl_add_u64 v[30:31], v[10:11], 0, v[30:31]
	v_lshl_add_u64 v[36:37], v[10:11], 0, v[36:37]
	v_lshl_add_u64 v[34:35], v[10:11], 0, v[34:35]
	v_lshl_add_u64 v[40:41], v[10:11], 0, v[40:41]
	v_lshl_add_u64 v[38:39], v[10:11], 0, v[38:39]
	v_lshl_add_u64 v[44:45], v[10:11], 0, v[44:45]
	v_lshl_add_u64 v[42:43], v[10:11], 0, v[42:43]
	v_lshl_add_u64 v[48:49], v[10:11], 0, v[48:49]
	v_lshl_add_u64 v[46:47], v[10:11], 0, v[46:47]
	global_load_dword v66, v[20:21], off
	global_load_dword v67, v[18:19], off
	global_load_dword v68, v[24:25], off
	global_load_dword v69, v[22:23], off
	global_load_dword v70, v[28:29], off
	global_load_dword v71, v[26:27], off
	global_load_dword v72, v[32:33], off
	global_load_dword v73, v[30:31], off
	global_load_dword v74, v[36:37], off
	global_load_dword v75, v[34:35], off
	global_load_dword v76, v[40:41], off
	global_load_dword v77, v[38:39], off
	global_load_dword v78, v[44:45], off
	global_load_dword v79, v[42:43], off
	global_load_dword v80, v[48:49], off
	global_load_dword v81, v[46:47], off
	s_add_i32 s14, s14, 16
	s_add_i32 s15, s15, 16
	s_add_i32 s9, s9, -16
	v_mad_u64_u32 v[18:19], s[16:17], v51, s13, v[4:5]
	s_cmp_lg_u32 s9, 0
	v_mad_u64_u32 v[20:21], s[16:17], v50, s13, v[4:5]
	v_mad_u64_u32 v[22:23], s[16:17], v53, s13, v[4:5]
	v_mad_u64_u32 v[24:25], s[16:17], v52, s13, v[4:5]
	v_mad_u64_u32 v[26:27], s[16:17], v55, s13, v[4:5]
	v_mad_u64_u32 v[28:29], s[16:17], v54, s13, v[4:5]
	v_mad_u64_u32 v[30:31], s[16:17], v57, s13, v[4:5]
	v_mad_u64_u32 v[32:33], s[16:17], v56, s13, v[4:5]
	v_mad_u64_u32 v[34:35], s[16:17], v59, s13, v[4:5]
	v_mad_u64_u32 v[36:37], s[16:17], v58, s13, v[4:5]
	v_mad_u64_u32 v[38:39], s[16:17], v61, s13, v[4:5]
	v_mad_u64_u32 v[40:41], s[16:17], v60, s13, v[4:5]
	v_mad_u64_u32 v[42:43], s[16:17], v63, s13, v[4:5]
	v_mad_u64_u32 v[44:45], s[16:17], v62, s13, v[4:5]
	v_mad_u64_u32 v[46:47], s[16:17], v65, s13, v[4:5]
	v_mad_u64_u32 v[48:49], s[16:17], v64, s13, v[4:5]
	s_nop 7
	s_lshl_b32 s16, s15, 1
	s_lshl_b32 s17, s14, 1
	v_or_b32_e32 v172, s16, v1
	v_or_b32_e32 v173, s17, v2
	s_add_i32 s18, s16, 4
	s_add_i32 s19, s17, 4
	s_add_i32 s20, s16, 8
	s_add_i32 s21, s17, 8
	s_add_i32 s22, s16, 12
	s_add_i32 s23, s17, 12
	s_add_i32 s24, s16, 16
	s_add_i32 s25, s17, 16
	s_add_i32 s26, s16, 20
	s_add_i32 s27, s17, 20
	s_add_i32 s28, s16, 24
	s_add_i32 s29, s17, 24
	s_add_i32 s16, s16, 28
	s_add_i32 s17, s17, 28
	v_add_u32_e32 v142, s8, v173
	v_or_b32_e32 v174, s18, v1
	v_or_b32_e32 v175, s19, v2
	v_or_b32_e32 v176, s20, v1
	v_or_b32_e32 v177, s21, v2
	v_or_b32_e32 v178, s22, v1
	v_or_b32_e32 v179, s23, v2
	v_or_b32_e32 v180, s24, v1
	v_or_b32_e32 v181, s25, v2
	v_or_b32_e32 v182, s26, v1
	v_or_b32_e32 v183, s27, v2
	v_or_b32_e32 v184, s28, v1
	v_or_b32_e32 v185, s29, v2
	v_or_b32_e32 v186, s16, v1
	v_or_b32_e32 v187, s17, v2
	v_add_u32_e32 v140, s7, v172
	v_ashrrev_i32_e32 v143, 31, v142
	v_add_u32_e32 v144, s7, v174
; __device__ __forceinline__ void p0_transpose_item(const float* W, int N, bf16_t* WT, int ldt, int k0, int n0, int nrow0, int kcol0, LAS float* scr, int lane) {
; #pragma unroll 8
;     for (int i = 0; i < 32; ++i) { const int kk = 2 * i + (lane >> 5); scr[kk * 33 + (lane & 31)] = W[(size_t)(k0 + kk) * N + n0 + (lane & 31)]; }
	v_add_u32_e32 v146, s8, v175
	v_add_u32_e32 v148, s7, v176
	v_add_u32_e32 v150, s8, v177
	v_add_u32_e32 v152, s7, v178
	v_add_u32_e32 v154, s8, v179
	v_add_u32_e32 v156, s7, v180
	v_add_u32_e32 v158, s8, v181
	v_add_u32_e32 v160, s7, v182
	v_add_u32_e32 v162, s8, v183
	v_add_u32_e32 v164, s7, v184
	v_add_u32_e32 v166, s8, v185
	v_add_u32_e32 v168, s7, v186
	v_add_u32_e32 v170, s8, v187
	v_ashrrev_i32_e32 v141, 31, v140
	v_lshlrev_b64 v[142:143], 14, v[142:143]
	v_ashrrev_i32_e32 v147, 31, v146
	v_ashrrev_i32_e32 v145, 31, v144
	v_ashrrev_i32_e32 v151, 31, v150
	v_ashrrev_i32_e32 v149, 31, v148
	v_ashrrev_i32_e32 v155, 31, v154
	v_ashrrev_i32_e32 v153, 31, v152
	v_ashrrev_i32_e32 v159, 31, v158
	v_ashrrev_i32_e32 v157, 31, v156
	v_ashrrev_i32_e32 v163, 31, v162
	v_ashrrev_i32_e32 v161, 31, v160
	v_ashrrev_i32_e32 v167, 31, v166
	v_ashrrev_i32_e32 v165, 31, v164
	v_ashrrev_i32_e32 v171, 31, v170
	v_ashrrev_i32_e32 v169, 31, v168
	v_lshlrev_b64 v[140:141], 14, v[140:141]
	v_lshl_add_u64 v[142:143], v[10:11], 0, v[142:143]
	v_lshlrev_b64 v[144:145], 14, v[144:145]
	v_lshlrev_b64 v[146:147], 14, v[146:147]
	v_lshlrev_b64 v[148:149], 14, v[148:149]
	v_lshlrev_b64 v[150:151], 14, v[150:151]
	v_lshlrev_b64 v[152:153], 14, v[152:153]
	v_lshlrev_b64 v[154:155], 14, v[154:155]
	v_lshlrev_b64 v[156:157], 14, v[156:157]
	v_lshlrev_b64 v[158:159], 14, v[158:159]
	v_lshlrev_b64 v[160:161], 14, v[160:161]
	v_lshlrev_b64 v[162:163], 14, v[162:163]
	v_lshlrev_b64 v[164:165], 14, v[164:165]
	v_lshlrev_b64 v[166:167], 14, v[166:167]
	v_lshlrev_b64 v[168:169], 14, v[168:169]
	v_lshlrev_b64 v[170:171], 14, v[170:171]
	v_lshl_add_u64 v[140:141], v[10:11], 0, v[140:141]
	v_lshl_add_u64 v[146:147], v[10:11], 0, v[146:147]
	v_lshl_add_u64 v[144:145], v[10:11], 0, v[144:145]
	v_lshl_add_u64 v[150:151], v[10:11], 0, v[150:151]
	v_lshl_add_u64 v[148:149], v[10:11], 0, v[148:149]
	v_lshl_add_u64 v[154:155], v[10:11], 0, v[154:155]
	v_lshl_add_u64 v[152:153], v[10:11], 0, v[152:153]
	v_lshl_add_u64 v[158:159], v[10:11], 0, v[158:159]
	v_lshl_add_u64 v[156:157], v[10:11], 0, v[156:157]
	v_lshl_add_u64 v[162:163], v[10:11], 0, v[162:163]
	v_lshl_add_u64 v[160:161], v[10:11], 0, v[160:161]
	v_lshl_add_u64 v[166:167], v[10:11], 0, v[166:167]
	v_lshl_add_u64 v[164:165], v[10:11], 0, v[164:165]
	v_lshl_add_u64 v[170:171], v[10:11], 0, v[170:171]
	v_lshl_add_u64 v[168:169], v[10:11], 0, v[168:169]
	global_load_dword v188, v[142:143], off
	global_load_dword v189, v[140:141], off
	global_load_dword v190, v[146:147], off
	global_load_dword v191, v[144:145], off
	global_load_dword v192, v[150:151], off
	global_load_dword v193, v[148:149], off
	global_load_dword v194, v[154:155], off
	global_load_dword v195, v[152:153], off
	global_load_dword v196, v[158:159], off
	global_load_dword v197, v[156:157], off
	global_load_dword v198, v[162:163], off
	global_load_dword v199, v[160:161], off
	global_load_dword v200, v[166:167], off
	global_load_dword v201, v[164:165], off
	global_load_dword v202, v[170:171], off
	global_load_dword v203, v[168:169], off
	s_add_i32 s14, s14, 16
	s_add_i32 s15, s15, 16
	s_add_i32 s9, s9, -16
	v_mad_u64_u32 v[140:141], s[16:17], v173, s13, v[4:5]
	s_cmp_lg_u32 s9, 0
	v_mad_u64_u32 v[142:143], s[16:17], v172, s13, v[4:5]
	v_mad_u64_u32 v[144:145], s[16:17], v175, s13, v[4:5]
	v_mad_u64_u32 v[146:147], s[16:17], v174, s13, v[4:5]
	v_mad_u64_u32 v[148:149], s[16:17], v177, s13, v[4:5]
	v_mad_u64_u32 v[150:151], s[16:17], v176, s13, v[4:5]
	v_mad_u64_u32 v[152:153], s[16:17], v179, s13, v[4:5]
	v_mad_u64_u32 v[154:155], s[16:17], v178, s13, v[4:5]
	v_mad_u64_u32 v[156:157], s[16:17], v181, s13, v[4:5]
	v_mad_u64_u32 v[158:159], s[16:17], v180, s13, v[4:5]
	v_mad_u64_u32 v[160:161], s[16:17], v183, s13, v[4:5]
	v_mad_u64_u32 v[162:163], s[16:17], v182, s13, v[4:5]
	v_mad_u64_u32 v[164:165], s[16:17], v185, s13, v[4:5]
	v_mad_u64_u32 v[166:167], s[16:17], v184, s13, v[4:5]
	v_mad_u64_u32 v[168:169], s[16:17], v187, s13, v[4:5]
	v_mad_u64_u32 v[170:171], s[16:17], v186, s13, v[4:5]
	s_waitcnt vmcnt(31)
; #define LAS __attribute__((address_space(3)))
; __device__ __forceinline__ unsigned cvt_pk_bf16(float lo, float hi) { unsigned r; asm volatile("v_cvt_pk_bf16_f32 %0, %1, %2" : "=v"(r) : "v"(lo), "v"(hi)); return r; }
; #define LDS_WAIT() asm volatile("s_waitcnt lgkmcnt(0)" ::: "memory")
; __device__ __forceinline__ void p0_transpose_item(const float* W, int N, bf16_t* WT, int ldt, int k0, int n0, int nrow0, int kcol0, LAS float* scr, int lane) {
; #pragma unroll 8
;     for (int i = 0; i < 32; ++i) { const int kk = 2 * i + (lane >> 5); scr[kk * 33 + (lane & 31)] = W[(size_t)(k0 + kk) * N + n0 + (lane & 31)]; }
;     LDS_WAIT(); asm volatile("" ::: "memory");
;     const int c = lane & 7;
; #pragma unroll
;     for (int j = 0; j < 4; ++j) { const int n = (lane >> 3) + 8 * j; const LAS float* s = scr + (8 * c) * 33 + n;
;         u32x4 o; o.x = cvt_pk_bf16(s[0 * 33], s[1 * 33]); o.y = cvt_pk_bf16(s[2 * 33], s[3 * 33]); o.z = cvt_pk_bf16(s[4 * 33], s[5 * 33]); o.w = cvt_pk_bf16(s[6 * 33], s[7 * 33]);
;         *(u32x4*)(WT + (size_t)(nrow0 + n) * ldt + kcol0 + k0 + 8 * c) = o; }
;     LDS_WAIT(); asm volatile("" ::: "memory");
; }
; __device__ __forceinline__ void p0_prologue(const Frame& F) {
;     ...
;                 for (int it = first; it < nitems; it += NGW) { const int kb = it / nblk, nbk = it % nblk, n0 = nbk * 32;
;                     const int nrow0 = (jb == 0 && n0 >= 3392) ? n0 + 192 : n0;
;                     p0_transpose_item(W, J.N, WT, J.ldt, kb * 64, n0, nrow0, J.kcol0, scr, F.lane); }
	ds_write_b32 v18, v66
	s_waitcnt vmcnt(30)
	ds_write_b32 v20, v67
	s_waitcnt vmcnt(29)
	ds_write_b32 v22, v68
	s_waitcnt vmcnt(28)
	ds_write_b32 v24, v69
	s_waitcnt vmcnt(27)
	ds_write_b32 v26, v70
	s_waitcnt vmcnt(26)
	ds_write_b32 v28, v71
	s_waitcnt vmcnt(25)
	ds_write_b32 v30, v72
	s_waitcnt vmcnt(24)
	ds_write_b32 v32, v73
	s_waitcnt vmcnt(23)
	ds_write_b32 v34, v74
	s_waitcnt vmcnt(22)
	ds_write_b32 v36, v75
	s_waitcnt vmcnt(21)
	ds_write_b32 v38, v76
	s_waitcnt vmcnt(20)
	ds_write_b32 v40, v77
	s_waitcnt vmcnt(19)
	ds_write_b32 v42, v78
	s_waitcnt vmcnt(18)
	ds_write_b32 v44, v79
	s_waitcnt vmcnt(17)
	ds_write_b32 v46, v80
	s_waitcnt vmcnt(16)
	ds_write_b32 v48, v81
	s_waitcnt vmcnt(15)
	ds_write_b32 v140, v188
	s_waitcnt vmcnt(14)
	ds_write_b32 v142, v189
	s_waitcnt vmcnt(13)
	ds_write_b32 v144, v190
	s_waitcnt vmcnt(12)
	ds_write_b32 v146, v191
	s_waitcnt vmcnt(11)
	ds_write_b32 v148, v192
	s_waitcnt vmcnt(10)
	ds_write_b32 v150, v193
	s_waitcnt vmcnt(9)
	ds_write_b32 v152, v194
	s_waitcnt vmcnt(8)
	ds_write_b32 v154, v195
	s_waitcnt vmcnt(7)
	ds_write_b32 v156, v196
	s_waitcnt vmcnt(6)
	ds_write_b32 v158, v197
	s_waitcnt vmcnt(5)
	ds_write_b32 v160, v198
	s_waitcnt vmcnt(4)
	ds_write_b32 v162, v199
	s_waitcnt vmcnt(3)
	ds_write_b32 v164, v200
	s_waitcnt vmcnt(2)
	ds_write_b32 v166, v201
	s_waitcnt vmcnt(1)
	ds_write_b32 v168, v202
	s_waitcnt vmcnt(0)
	ds_write_b32 v170, v203
	s_waitcnt lgkmcnt(0)
	v_or_b32_e32 v22, s6, v3
	ds_read2_b32 v[10:11], v5 offset1:33
	s_ashr_i32 s9, s8, 31
	v_ashrrev_i32_e32 v23, 31, v22
	s_waitcnt lgkmcnt(0)
	v_cvt_pk_bf16_f32 v18, v10, v11
	ds_read2_b32 v[10:11], v5 offset0:66 offset1:99
	v_lshl_add_u64 v[24:25], s[8:9], 1, v[8:9]
	v_lshlrev_b64 v[22:23], 13, v[22:23]
	s_waitcnt lgkmcnt(0)
	v_cvt_pk_bf16_f32 v19, v10, v11
	ds_read2_b32 v[10:11], v5 offset0:132 offset1:165
	v_lshl_add_u64 v[22:23], v[24:25], 0, v[22:23]
	s_waitcnt lgkmcnt(0)
	v_cvt_pk_bf16_f32 v20, v10, v11
	ds_read2_b32 v[10:11], v5 offset0:198 offset1:231
	s_waitcnt lgkmcnt(0)
	v_cvt_pk_bf16_f32 v21, v10, v11
	global_store_dwordx4 v[22:23], v[18:21], off
	v_or_b32_e32 v22, s6, v13
	ds_read2_b32 v[10:11], v5 offset0:8 offset1:41
	v_ashrrev_i32_e32 v23, 31, v22
	s_waitcnt lgkmcnt(0)
	v_cvt_pk_bf16_f32 v18, v10, v11
	ds_read2_b32 v[10:11], v5 offset0:74 offset1:107
	v_lshlrev_b64 v[22:23], 13, v[22:23]
	s_waitcnt lgkmcnt(0)
	v_cvt_pk_bf16_f32 v19, v10, v11
	ds_read2_b32 v[10:11], v5 offset0:140 offset1:173
	v_lshl_add_u64 v[22:23], v[24:25], 0, v[22:23]
	s_waitcnt lgkmcnt(0)
	v_cvt_pk_bf16_f32 v20, v10, v11
	ds_read2_b32 v[10:11], v5 offset0:206 offset1:239
	s_waitcnt lgkmcnt(0)
	v_cvt_pk_bf16_f32 v21, v10, v11
	global_store_dwordx4 v[22:23], v[18:21], off
	v_or_b32_e32 v22, s6, v16
	ds_read2_b32 v[10:11], v5 offset0:16 offset1:49
	v_ashrrev_i32_e32 v23, 31, v22
	s_waitcnt lgkmcnt(0)
	v_cvt_pk_bf16_f32 v18, v10, v11
	ds_read2_b32 v[10:11], v5 offset0:82 offset1:115
	v_lshlrev_b64 v[22:23], 13, v[22:23]
	s_waitcnt lgkmcnt(0)
	v_cvt_pk_bf16_f32 v19, v10, v11
	ds_read2_b32 v[10:11], v5 offset0:148 offset1:181
	v_lshl_add_u64 v[22:23], v[24:25], 0, v[22:23]
	s_waitcnt lgkmcnt(0)
	v_cvt_pk_bf16_f32 v20, v10, v11
	ds_read2_b32 v[10:11], v5 offset0:214 offset1:247
	s_waitcnt lgkmcnt(0)
	v_cvt_pk_bf16_f32 v21, v10, v11
	global_store_dwordx4 v[22:23], v[18:21], off
	v_or_b32_e32 v22, s6, v17
	ds_read2_b32 v[10:11], v5 offset0:24 offset1:57
	v_ashrrev_i32_e32 v23, 31, v22
	s_waitcnt lgkmcnt(0)
	v_cvt_pk_bf16_f32 v18, v10, v11
	ds_read2_b32 v[10:11], v5 offset0:90 offset1:123
	v_lshlrev_b64 v[22:23], 13, v[22:23]
	s_waitcnt lgkmcnt(0)
	v_cvt_pk_bf16_f32 v19, v10, v11
	ds_read2_b32 v[10:11], v5 offset0:156 offset1:189
	v_lshl_add_u64 v[22:23], v[24:25], 0, v[22:23]
	s_waitcnt lgkmcnt(0)
	v_cvt_pk_bf16_f32 v20, v10, v11
	ds_read2_b32 v[10:11], v5 offset0:222 offset1:255
	s_waitcnt lgkmcnt(0)
	v_cvt_pk_bf16_f32 v21, v10, v11
	global_store_dwordx4 v[22:23], v[18:21], off
	s_waitcnt lgkmcnt(0)
	s_add_i32 s12, s12, s3
	s_cmpk_lt_i32 s12, 0x1000
	s_cbranch_scc1 .LBB0_59

; __device__ __forceinline__ void p0_transpose_item(const float* W, int N, bf16_t* WT, int ldt, int k0, int n0, int nrow0, int kcol0, LAS float* scr, int lane) {
; #pragma unroll 8
;     for (int i = 0; i < 32; ++i) { const int kk = 2 * i + (lane >> 5); scr[kk * 33 + (lane & 31)] = W[(size_t)(k0 + kk) * N + n0 + (lane & 31)]; }
.LBB0_70:
	s_lshl_b32 s16, s15, 1
	s_lshl_b32 s17, s14, 1
	v_or_b32_e32 v50, s16, v1
	v_or_b32_e32 v51, s17, v2
	s_add_i32 s18, s16, 4
	s_add_i32 s19, s17, 4
	s_add_i32 s20, s16, 8
	s_add_i32 s21, s17, 8
	s_add_i32 s22, s16, 12
	s_add_i32 s23, s17, 12
	s_add_i32 s24, s16, 16
	s_add_i32 s25, s17, 16
	s_add_i32 s26, s16, 20
	s_add_i32 s27, s17, 20
	s_add_i32 s28, s16, 24
	s_add_i32 s29, s17, 24
	s_add_i32 s16, s16, 28
	s_add_i32 s17, s17, 28
	v_add_u32_e32 v20, s8, v51
	v_or_b32_e32 v52, s18, v1
	v_or_b32_e32 v53, s19, v2
	v_or_b32_e32 v54, s20, v1
	v_or_b32_e32 v55, s21, v2
	v_or_b32_e32 v56, s22, v1
	v_or_b32_e32 v57, s23, v2
	v_or_b32_e32 v58, s24, v1
	v_or_b32_e32 v59, s25, v2
	v_or_b32_e32 v60, s26, v1
	v_or_b32_e32 v61, s27, v2
	v_or_b32_e32 v62, s28, v1
	v_or_b32_e32 v63, s29, v2
	v_or_b32_e32 v64, s16, v1
	v_or_b32_e32 v65, s17, v2
	v_add_u32_e32 v18, s7, v50
	v_ashrrev_i32_e32 v21, 31, v20
	v_add_u32_e32 v22, s7, v52
	v_add_u32_e32 v24, s8, v53
	v_add_u32_e32 v26, s7, v54
	v_add_u32_e32 v28, s8, v55
	v_add_u32_e32 v30, s7, v56
	v_add_u32_e32 v32, s8, v57
	v_add_u32_e32 v34, s7, v58
	v_add_u32_e32 v36, s8, v59
	v_add_u32_e32 v38, s7, v60
	v_add_u32_e32 v40, s8, v61
	v_add_u32_e32 v42, s7, v62
	v_add_u32_e32 v44, s8, v63
	v_add_u32_e32 v46, s7, v64
	v_add_u32_e32 v48, s8, v65
	v_ashrrev_i32_e32 v19, 31, v18
	v_lshlrev_b64 v[20:21], 14, v[20:21]
	v_ashrrev_i32_e32 v25, 31, v24
	v_ashrrev_i32_e32 v23, 31, v22
	v_ashrrev_i32_e32 v29, 31, v28
	v_ashrrev_i32_e32 v27, 31, v26
	v_ashrrev_i32_e32 v33, 31, v32
	v_ashrrev_i32_e32 v31, 31, v30
	v_ashrrev_i32_e32 v37, 31, v36
	v_ashrrev_i32_e32 v35, 31, v34
	v_ashrrev_i32_e32 v41, 31, v40
	v_ashrrev_i32_e32 v39, 31, v38
	v_ashrrev_i32_e32 v45, 31, v44
	v_ashrrev_i32_e32 v43, 31, v42
	v_ashrrev_i32_e32 v49, 31, v48
	v_ashrrev_i32_e32 v47, 31, v46
	v_lshlrev_b64 v[18:19], 14, v[18:19]
	v_lshl_add_u64 v[20:21], v[10:11], 0, v[20:21]
	v_lshlrev_b64 v[22:23], 14, v[22:23]
	v_lshlrev_b64 v[24:25], 14, v[24:25]
	v_lshlrev_b64 v[26:27], 14, v[26:27]
	v_lshlrev_b64 v[28:29], 14, v[28:29]
	v_lshlrev_b64 v[30:31], 14, v[30:31]
	v_lshlrev_b64 v[32:33], 14, v[32:33]
	v_lshlrev_b64 v[34:35], 14, v[34:35]
	v_lshlrev_b64 v[36:37], 14, v[36:37]
	v_lshlrev_b64 v[38:39], 14, v[38:39]
	v_lshlrev_b64 v[40:41], 14, v[40:41]
	v_lshlrev_b64 v[42:43], 14, v[42:43]
	v_lshlrev_b64 v[44:45], 14, v[44:45]
	v_lshlrev_b64 v[46:47], 14, v[46:47]
	v_lshlrev_b64 v[48:49], 14, v[48:49]
	v_lshl_add_u64 v[18:19], v[10:11], 0, v[18:19]
	v_lshl_add_u64 v[24:25], v[10:11], 0, v[24:25]
	v_lshl_add_u64 v[22:23], v[10:11], 0, v[22:23]
	v_lshl_add_u64 v[28:29], v[10:11], 0, v[28:29]
	v_lshl_add_u64 v[26:27], v[10:11], 0, v[26:27]
	v_lshl_add_u64 v[32:33], v[10:11], 0, v[32:33]
	v_lshl_add_u64 v[30:31], v[10:11], 0, v[30:31]
	v_lshl_add_u64 v[36:37], v[10:11], 0, v[36:37]
	v_lshl_add_u64 v[34:35], v[10:11], 0, v[34:35]
	v_lshl_add_u64 v[40:41], v[10:11], 0, v[40:41]
	v_lshl_add_u64 v[38:39], v[10:11], 0, v[38:39]
	v_lshl_add_u64 v[44:45], v[10:11], 0, v[44:45]
	v_lshl_add_u64 v[42:43], v[10:11], 0, v[42:43]
	v_lshl_add_u64 v[48:49], v[10:11], 0, v[48:49]
	v_lshl_add_u64 v[46:47], v[10:11], 0, v[46:47]
	global_load_dword v66, v[20:21], off
	global_load_dword v67, v[18:19], off
	global_load_dword v68, v[24:25], off
	global_load_dword v69, v[22:23], off
	global_load_dword v70, v[28:29], off
	global_load_dword v71, v[26:27], off
	global_load_dword v72, v[32:33], off
	global_load_dword v73, v[30:31], off
	global_load_dword v74, v[36:37], off
	global_load_dword v75, v[34:35], off
	global_load_dword v76, v[40:41], off
	global_load_dword v77, v[38:39], off
	global_load_dword v78, v[44:45], off
	global_load_dword v79, v[42:43], off
	global_load_dword v80, v[48:49], off
	global_load_dword v81, v[46:47], off
	s_add_i32 s14, s14, 16
	s_add_i32 s15, s15, 16
	s_add_i32 s9, s9, -16
	v_mad_u64_u32 v[18:19], s[16:17], v51, s13, v[4:5]
	s_cmp_lg_u32 s9, 0
	v_mad_u64_u32 v[20:21], s[16:17], v50, s13, v[4:5]
	v_mad_u64_u32 v[22:23], s[16:17], v53, s13, v[4:5]
	v_mad_u64_u32 v[24:25], s[16:17], v52, s13, v[4:5]
	v_mad_u64_u32 v[26:27], s[16:17], v55, s13, v[4:5]
	v_mad_u64_u32 v[28:29], s[16:17], v54, s13, v[4:5]
	v_mad_u64_u32 v[30:31], s[16:17], v57, s13, v[4:5]
	v_mad_u64_u32 v[32:33], s[16:17], v56, s13, v[4:5]
	v_mad_u64_u32 v[34:35], s[16:17], v59, s13, v[4:5]
	v_mad_u64_u32 v[36:37], s[16:17], v58, s13, v[4:5]
	v_mad_u64_u32 v[38:39], s[16:17], v61, s13, v[4:5]
	v_mad_u64_u32 v[40:41], s[16:17], v60, s13, v[4:5]
	v_mad_u64_u32 v[42:43], s[16:17], v63, s13, v[4:5]
	v_mad_u64_u32 v[44:45], s[16:17], v62, s13, v[4:5]
	v_mad_u64_u32 v[46:47], s[16:17], v65, s13, v[4:5]
	v_mad_u64_u32 v[48:49], s[16:17], v64, s13, v[4:5]
	s_nop 7
	s_lshl_b32 s16, s15, 1
	s_lshl_b32 s17, s14, 1
	v_or_b32_e32 v172, s16, v1
	v_or_b32_e32 v173, s17, v2
	s_add_i32 s18, s16, 4
	s_add_i32 s19, s17, 4
	s_add_i32 s20, s16, 8
	s_add_i32 s21, s17, 8
	s_add_i32 s22, s16, 12
	s_add_i32 s23, s17, 12
	s_add_i32 s24, s16, 16
	s_add_i32 s25, s17, 16
	s_add_i32 s26, s16, 20
	s_add_i32 s27, s17, 20
	s_add_i32 s28, s16, 24
	s_add_i32 s29, s17, 24
	s_add_i32 s16, s16, 28
	s_add_i32 s17, s17, 28
	v_add_u32_e32 v142, s8, v173
	v_or_b32_e32 v174, s18, v1
	v_or_b32_e32 v175, s19, v2
	v_or_b32_e32 v176, s20, v1
	v_or_b32_e32 v177, s21, v2
	v_or_b32_e32 v178, s22, v1
	v_or_b32_e32 v179, s23, v2
	v_or_b32_e32 v180, s24, v1
	v_or_b32_e32 v181, s25, v2
	v_or_b32_e32 v182, s26, v1
	v_or_b32_e32 v183, s27, v2
	v_or_b32_e32 v184, s28, v1
	v_or_b32_e32 v185, s29, v2
	v_or_b32_e32 v186, s16, v1
	v_or_b32_e32 v187, s17, v2
	v_add_u32_e32 v140, s7, v172
	v_ashrrev_i32_e32 v143, 31, v142
	v_add_u32_e32 v144, s7, v174
; __device__ __forceinline__ void p0_transpose_item(const float* W, int N, bf16_t* WT, int ldt, int k0, int n0, int nrow0, int kcol0, LAS float* scr, int lane) {
; #pragma unroll 8
;     for (int i = 0; i < 32; ++i) { const int kk = 2 * i + (lane >> 5); scr[kk * 33 + (lane & 31)] = W[(size_t)(k0 + kk) * N + n0 + (lane & 31)]; }
	v_add_u32_e32 v146, s8, v175
	v_add_u32_e32 v148, s7, v176
	v_add_u32_e32 v150, s8, v177
	v_add_u32_e32 v152, s7, v178
	v_add_u32_e32 v154, s8, v179
	v_add_u32_e32 v156, s7, v180
	v_add_u32_e32 v158, s8, v181
	v_add_u32_e32 v160, s7, v182
	v_add_u32_e32 v162, s8, v183
	v_add_u32_e32 v164, s7, v184
	v_add_u32_e32 v166, s8, v185
	v_add_u32_e32 v168, s7, v186
	v_add_u32_e32 v170, s8, v187
	v_ashrrev_i32_e32 v141, 31, v140
	v_lshlrev_b64 v[142:143], 14, v[142:143]
	v_ashrrev_i32_e32 v147, 31, v146
	v_ashrrev_i32_e32 v145, 31, v144
	v_ashrrev_i32_e32 v151, 31, v150
	v_ashrrev_i32_e32 v149, 31, v148
	v_ashrrev_i32_e32 v155, 31, v154
	v_ashrrev_i32_e32 v153, 31, v152
	v_ashrrev_i32_e32 v159, 31, v158
	v_ashrrev_i32_e32 v157, 31, v156
	v_ashrrev_i32_e32 v163, 31, v162
	v_ashrrev_i32_e32 v161, 31, v160
	v_ashrrev_i32_e32 v167, 31, v166
	v_ashrrev_i32_e32 v165, 31, v164
	v_ashrrev_i32_e32 v171, 31, v170
	v_ashrrev_i32_e32 v169, 31, v168
	v_lshlrev_b64 v[140:141], 14, v[140:141]
	v_lshl_add_u64 v[142:143], v[10:11], 0, v[142:143]
	v_lshlrev_b64 v[144:145], 14, v[144:145]
	v_lshlrev_b64 v[146:147], 14, v[146:147]
	v_lshlrev_b64 v[148:149], 14, v[148:149]
	v_lshlrev_b64 v[150:151], 14, v[150:151]
	v_lshlrev_b64 v[152:153], 14, v[152:153]
	v_lshlrev_b64 v[154:155], 14, v[154:155]
	v_lshlrev_b64 v[156:157], 14, v[156:157]
	v_lshlrev_b64 v[158:159], 14, v[158:159]
	v_lshlrev_b64 v[160:161], 14, v[160:161]
	v_lshlrev_b64 v[162:163], 14, v[162:163]
	v_lshlrev_b64 v[164:165], 14, v[164:165]
	v_lshlrev_b64 v[166:167], 14, v[166:167]
	v_lshlrev_b64 v[168:169], 14, v[168:169]
	v_lshlrev_b64 v[170:171], 14, v[170:171]
	v_lshl_add_u64 v[140:141], v[10:11], 0, v[140:141]
	v_lshl_add_u64 v[146:147], v[10:11], 0, v[146:147]
	v_lshl_add_u64 v[144:145], v[10:11], 0, v[144:145]
	v_lshl_add_u64 v[150:151], v[10:11], 0, v[150:151]
	v_lshl_add_u64 v[148:149], v[10:11], 0, v[148:149]
	v_lshl_add_u64 v[154:155], v[10:11], 0, v[154:155]
	v_lshl_add_u64 v[152:153], v[10:11], 0, v[152:153]
	v_lshl_add_u64 v[158:159], v[10:11], 0, v[158:159]
	v_lshl_add_u64 v[156:157], v[10:11], 0, v[156:157]
	v_lshl_add_u64 v[162:163], v[10:11], 0, v[162:163]
	v_lshl_add_u64 v[160:161], v[10:11], 0, v[160:161]
	v_lshl_add_u64 v[166:167], v[10:11], 0, v[166:167]
	v_lshl_add_u64 v[164:165], v[10:11], 0, v[164:165]
	v_lshl_add_u64 v[170:171], v[10:11], 0, v[170:171]
	v_lshl_add_u64 v[168:169], v[10:11], 0, v[168:169]
	global_load_dword v188, v[142:143], off
	global_load_dword v189, v[140:141], off
	global_load_dword v190, v[146:147], off
	global_load_dword v191, v[144:145], off
	global_load_dword v192, v[150:151], off
	global_load_dword v193, v[148:149], off
	global_load_dword v194, v[154:155], off
	global_load_dword v195, v[152:153], off
	global_load_dword v196, v[158:159], off
	global_load_dword v197, v[156:157], off
	global_load_dword v198, v[162:163], off
	global_load_dword v199, v[160:161], off
	global_load_dword v200, v[166:167], off
	global_load_dword v201, v[164:165], off
	global_load_dword v202, v[170:171], off
	global_load_dword v203, v[168:169], off
	s_add_i32 s14, s14, 16
	s_add_i32 s15, s15, 16
	s_add_i32 s9, s9, -16
	v_mad_u64_u32 v[140:141], s[16:17], v173, s13, v[4:5]
	s_cmp_lg_u32 s9, 0
	v_mad_u64_u32 v[142:143], s[16:17], v172, s13, v[4:5]
	v_mad_u64_u32 v[144:145], s[16:17], v175, s13, v[4:5]
	v_mad_u64_u32 v[146:147], s[16:17], v174, s13, v[4:5]
	v_mad_u64_u32 v[148:149], s[16:17], v177, s13, v[4:5]
	v_mad_u64_u32 v[150:151], s[16:17], v176, s13, v[4:5]
	v_mad_u64_u32 v[152:153], s[16:17], v179, s13, v[4:5]
	v_mad_u64_u32 v[154:155], s[16:17], v178, s13, v[4:5]
	v_mad_u64_u32 v[156:157], s[16:17], v181, s13, v[4:5]
	v_mad_u64_u32 v[158:159], s[16:17], v180, s13, v[4:5]
	v_mad_u64_u32 v[160:161], s[16:17], v183, s13, v[4:5]
	v_mad_u64_u32 v[162:163], s[16:17], v182, s13, v[4:5]
	v_mad_u64_u32 v[164:165], s[16:17], v185, s13, v[4:5]
	v_mad_u64_u32 v[166:167], s[16:17], v184, s13, v[4:5]
	v_mad_u64_u32 v[168:169], s[16:17], v187, s13, v[4:5]
	v_mad_u64_u32 v[170:171], s[16:17], v186, s13, v[4:5]
	s_waitcnt vmcnt(31)
; #define LAS __attribute__((address_space(3)))
; __device__ __forceinline__ unsigned cvt_pk_bf16(float lo, float hi) { unsigned r; asm volatile("v_cvt_pk_bf16_f32 %0, %1, %2" : "=v"(r) : "v"(lo), "v"(hi)); return r; }
; #define LDS_WAIT() asm volatile("s_waitcnt lgkmcnt(0)" ::: "memory")
; __device__ __forceinline__ void p0_transpose_item(const float* W, int N, bf16_t* WT, int ldt, int k0, int n0, int nrow0, int kcol0, LAS float* scr, int lane) {
;     ...
;     for (int i = 0; i < 32; ++i) { const int kk = 2 * i + (lane >> 5); scr[kk * 33 + (lane & 31)] = W[(size_t)(k0 + kk) * N + n0 + (lane & 31)]; }
;     LDS_WAIT(); asm volatile("" ::: "memory");
;     const int c = lane & 7;
; #pragma unroll
;     for (int j = 0; j < 4; ++j) { const int n = (lane >> 3) + 8 * j; const LAS float* s = scr + (8 * c) * 33 + n;
;         u32x4 o; o.x = cvt_pk_bf16(s[0 * 33], s[1 * 33]); o.y = cvt_pk_bf16(s[2 * 33], s[3 * 33]); o.z = cvt_pk_bf16(s[4 * 33], s[5 * 33]); o.w = cvt_pk_bf16(s[6 * 33], s[7 * 33]);
;         *(u32x4*)(WT + (size_t)(nrow0 + n) * ldt + kcol0 + k0 + 8 * c) = o; }
;     LDS_WAIT(); asm volatile("" ::: "memory");
; __device__ __forceinline__ void p0_prologue(const Frame& F) {
;     ...
;                 for (int it = first; it < nitems; it += NGW) { const int kb = it / nblk, nbk = it % nblk, n0 = nbk * 32;
;                     const int nrow0 = (jb == 0 && n0 >= 3392) ? n0 + 192 : n0;
;                     p0_transpose_item(W, J.N, WT, J.ldt, kb * 64, n0, nrow0, J.kcol0, scr, F.lane); }
	ds_write_b32 v18, v66
	s_waitcnt vmcnt(30)
	ds_write_b32 v20, v67
	s_waitcnt vmcnt(29)
	ds_write_b32 v22, v68
	s_waitcnt vmcnt(28)
	ds_write_b32 v24, v69
	s_waitcnt vmcnt(27)
	ds_write_b32 v26, v70
	s_waitcnt vmcnt(26)
	ds_write_b32 v28, v71
	s_waitcnt vmcnt(25)
	ds_write_b32 v30, v72
	s_waitcnt vmcnt(24)
	ds_write_b32 v32, v73
	s_waitcnt vmcnt(23)
	ds_write_b32 v34, v74
	s_waitcnt vmcnt(22)
	ds_write_b32 v36, v75
	s_waitcnt vmcnt(21)
	ds_write_b32 v38, v76
	s_waitcnt vmcnt(20)
	ds_write_b32 v40, v77
	s_waitcnt vmcnt(19)
	ds_write_b32 v42, v78
	s_waitcnt vmcnt(18)
	ds_write_b32 v44, v79
	s_waitcnt vmcnt(17)
	ds_write_b32 v46, v80
	s_waitcnt vmcnt(16)
	ds_write_b32 v48, v81
	s_waitcnt vmcnt(15)
	ds_write_b32 v140, v188
	s_waitcnt vmcnt(14)
	ds_write_b32 v142, v189
	s_waitcnt vmcnt(13)
	ds_write_b32 v144, v190
	s_waitcnt vmcnt(12)
	ds_write_b32 v146, v191
	s_waitcnt vmcnt(11)
	ds_write_b32 v148, v192
	s_waitcnt vmcnt(10)
	ds_write_b32 v150, v193
	s_waitcnt vmcnt(9)
	ds_write_b32 v152, v194
	s_waitcnt vmcnt(8)
	ds_write_b32 v154, v195
	s_waitcnt vmcnt(7)
	ds_write_b32 v156, v196
	s_waitcnt vmcnt(6)
	ds_write_b32 v158, v197
	s_waitcnt vmcnt(5)
	ds_write_b32 v160, v198
	s_waitcnt vmcnt(4)
	ds_write_b32 v162, v199
	s_waitcnt vmcnt(3)
	ds_write_b32 v164, v200
	s_waitcnt vmcnt(2)
	ds_write_b32 v166, v201
	s_waitcnt vmcnt(1)
	ds_write_b32 v168, v202
	s_waitcnt vmcnt(0)
	ds_write_b32 v170, v203
	s_waitcnt lgkmcnt(0)
	v_or_b32_e32 v22, s6, v3
	ds_read2_b32 v[10:11], v5 offset1:33
	s_ashr_i32 s9, s8, 31
	v_ashrrev_i32_e32 v23, 31, v22
	s_waitcnt lgkmcnt(0)
	v_cvt_pk_bf16_f32 v18, v10, v11
	ds_read2_b32 v[10:11], v5 offset0:66 offset1:99
	v_lshl_add_u64 v[24:25], s[8:9], 1, v[8:9]
	v_lshlrev_b64 v[22:23], 13, v[22:23]
	s_waitcnt lgkmcnt(0)
	v_cvt_pk_bf16_f32 v19, v10, v11
	ds_read2_b32 v[10:11], v5 offset0:132 offset1:165
	v_lshl_add_u64 v[22:23], v[24:25], 0, v[22:23]
	s_waitcnt lgkmcnt(0)
	v_cvt_pk_bf16_f32 v20, v10, v11
	ds_read2_b32 v[10:11], v5 offset0:198 offset1:231
	s_waitcnt lgkmcnt(0)
	v_cvt_pk_bf16_f32 v21, v10, v11
	global_store_dwordx4 v[22:23], v[18:21], off
	v_or_b32_e32 v22, s6, v13
	ds_read2_b32 v[10:11], v5 offset0:8 offset1:41
	v_ashrrev_i32_e32 v23, 31, v22
	s_waitcnt lgkmcnt(0)
	v_cvt_pk_bf16_f32 v18, v10, v11
	ds_read2_b32 v[10:11], v5 offset0:74 offset1:107
	v_lshlrev_b64 v[22:23], 13, v[22:23]
	s_waitcnt lgkmcnt(0)
	v_cvt_pk_bf16_f32 v19, v10, v11
	ds_read2_b32 v[10:11], v5 offset0:140 offset1:173
	v_lshl_add_u64 v[22:23], v[24:25], 0, v[22:23]
	s_waitcnt lgkmcnt(0)
	v_cvt_pk_bf16_f32 v20, v10, v11
	ds_read2_b32 v[10:11], v5 offset0:206 offset1:239
	s_waitcnt lgkmcnt(0)
	v_cvt_pk_bf16_f32 v21, v10, v11
	global_store_dwordx4 v[22:23], v[18:21], off
	v_or_b32_e32 v22, s6, v16
	ds_read2_b32 v[10:11], v5 offset0:16 offset1:49
	v_ashrrev_i32_e32 v23, 31, v22
	s_waitcnt lgkmcnt(0)
	v_cvt_pk_bf16_f32 v18, v10, v11
	ds_read2_b32 v[10:11], v5 offset0:82 offset1:115
	v_lshlrev_b64 v[22:23], 13, v[22:23]
	s_waitcnt lgkmcnt(0)
	v_cvt_pk_bf16_f32 v19, v10, v11
	ds_read2_b32 v[10:11], v5 offset0:148 offset1:181
	v_lshl_add_u64 v[22:23], v[24:25], 0, v[22:23]
	s_waitcnt lgkmcnt(0)
	v_cvt_pk_bf16_f32 v20, v10, v11
	ds_read2_b32 v[10:11], v5 offset0:214 offset1:247
	s_waitcnt lgkmcnt(0)
	v_cvt_pk_bf16_f32 v21, v10, v11
	global_store_dwordx4 v[22:23], v[18:21], off
	v_or_b32_e32 v22, s6, v17
	ds_read2_b32 v[10:11], v5 offset0:24 offset1:57
	v_ashrrev_i32_e32 v23, 31, v22
	s_waitcnt lgkmcnt(0)
	v_cvt_pk_bf16_f32 v18, v10, v11
	ds_read2_b32 v[10:11], v5 offset0:90 offset1:123
	v_lshlrev_b64 v[22:23], 13, v[22:23]
	s_waitcnt lgkmcnt(0)
	v_cvt_pk_bf16_f32 v19, v10, v11
	ds_read2_b32 v[10:11], v5 offset0:156 offset1:189
	v_lshl_add_u64 v[22:23], v[24:25], 0, v[22:23]
	s_waitcnt lgkmcnt(0)
	v_cvt_pk_bf16_f32 v20, v10, v11
	ds_read2_b32 v[10:11], v5 offset0:222 offset1:255
	s_waitcnt lgkmcnt(0)
	v_cvt_pk_bf16_f32 v21, v10, v11
	global_store_dwordx4 v[22:23], v[18:21], off
	s_waitcnt lgkmcnt(0)
	s_add_i32 s12, s12, s3
	s_cmpk_lt_i32 s12, 0x2000
	s_cbranch_scc1 .LBB0_69

; __device__ __forceinline__ void p0_transpose_item(const float* W, int N, bf16_t* WT, int ldt, int k0, int n0, int nrow0, int kcol0, LAS float* scr, int lane) {
; #pragma unroll 8
;     for (int i = 0; i < 32; ++i) { const int kk = 2 * i + (lane >> 5); scr[kk * 33 + (lane & 31)] = W[(size_t)(k0 + kk) * N + n0 + (lane & 31)]; }
.LBB0_85:
	s_lshl_b32 s16, s15, 1
	s_lshl_b32 s17, s14, 1
	v_or_b32_e32 v50, s16, v1
	v_or_b32_e32 v51, s17, v2
	s_add_i32 s18, s16, 4
	s_add_i32 s19, s17, 4
	s_add_i32 s20, s16, 8
	s_add_i32 s21, s17, 8
	s_add_i32 s22, s16, 12
	s_add_i32 s23, s17, 12
	s_add_i32 s24, s16, 16
	s_add_i32 s25, s17, 16
	s_add_i32 s26, s16, 20
	s_add_i32 s27, s17, 20
	s_add_i32 s28, s16, 24
	s_add_i32 s29, s17, 24
	s_add_i32 s16, s16, 28
	s_add_i32 s17, s17, 28
	v_add_u32_e32 v20, s8, v51
	v_or_b32_e32 v52, s18, v1
	v_or_b32_e32 v53, s19, v2
	v_or_b32_e32 v54, s20, v1
	v_or_b32_e32 v55, s21, v2
	v_or_b32_e32 v56, s22, v1
	v_or_b32_e32 v57, s23, v2
	v_or_b32_e32 v58, s24, v1
	v_or_b32_e32 v59, s25, v2
	v_or_b32_e32 v60, s26, v1
	v_or_b32_e32 v61, s27, v2
	v_or_b32_e32 v62, s28, v1
	v_or_b32_e32 v63, s29, v2
	v_or_b32_e32 v64, s16, v1
	v_or_b32_e32 v65, s17, v2
	v_add_u32_e32 v18, s7, v50
	v_ashrrev_i32_e32 v21, 31, v20
	v_add_u32_e32 v22, s7, v52
	v_add_u32_e32 v24, s8, v53
	v_add_u32_e32 v26, s7, v54
	v_add_u32_e32 v28, s8, v55
	v_add_u32_e32 v30, s7, v56
	v_add_u32_e32 v32, s8, v57
	v_add_u32_e32 v34, s7, v58
	v_add_u32_e32 v36, s8, v59
	v_add_u32_e32 v38, s7, v60
	v_add_u32_e32 v40, s8, v61
	v_add_u32_e32 v42, s7, v62
	v_add_u32_e32 v44, s8, v63
	v_add_u32_e32 v46, s7, v64
	v_add_u32_e32 v48, s8, v65
	v_ashrrev_i32_e32 v19, 31, v18
	v_lshlrev_b64 v[20:21], 14, v[20:21]
	v_ashrrev_i32_e32 v25, 31, v24
	v_ashrrev_i32_e32 v23, 31, v22
	v_ashrrev_i32_e32 v29, 31, v28
	v_ashrrev_i32_e32 v27, 31, v26
	v_ashrrev_i32_e32 v33, 31, v32
	v_ashrrev_i32_e32 v31, 31, v30
	v_ashrrev_i32_e32 v37, 31, v36
	v_ashrrev_i32_e32 v35, 31, v34
	v_ashrrev_i32_e32 v41, 31, v40
	v_ashrrev_i32_e32 v39, 31, v38
	v_ashrrev_i32_e32 v45, 31, v44
	v_ashrrev_i32_e32 v43, 31, v42
	v_ashrrev_i32_e32 v49, 31, v48
	v_ashrrev_i32_e32 v47, 31, v46
	v_lshlrev_b64 v[18:19], 14, v[18:19]
	v_lshl_add_u64 v[20:21], v[10:11], 0, v[20:21]
	v_lshlrev_b64 v[22:23], 14, v[22:23]
	v_lshlrev_b64 v[24:25], 14, v[24:25]
	v_lshlrev_b64 v[26:27], 14, v[26:27]
	v_lshlrev_b64 v[28:29], 14, v[28:29]
	v_lshlrev_b64 v[30:31], 14, v[30:31]
	v_lshlrev_b64 v[32:33], 14, v[32:33]
	v_lshlrev_b64 v[34:35], 14, v[34:35]
	v_lshlrev_b64 v[36:37], 14, v[36:37]
	v_lshlrev_b64 v[38:39], 14, v[38:39]
	v_lshlrev_b64 v[40:41], 14, v[40:41]
	v_lshlrev_b64 v[42:43], 14, v[42:43]
	v_lshlrev_b64 v[44:45], 14, v[44:45]
	v_lshlrev_b64 v[46:47], 14, v[46:47]
	v_lshlrev_b64 v[48:49], 14, v[48:49]
	v_lshl_add_u64 v[18:19], v[10:11], 0, v[18:19]
	v_lshl_add_u64 v[24:25], v[10:11], 0, v[24:25]
	v_lshl_add_u64 v[22:23], v[10:11], 0, v[22:23]
	v_lshl_add_u64 v[28:29], v[10:11], 0, v[28:29]
	v_lshl_add_u64 v[26:27], v[10:11], 0, v[26:27]
	v_lshl_add_u64 v[32:33], v[10:11], 0, v[32:33]
	v_lshl_add_u64 v[30:31], v[10:11], 0, v[30:31]
	v_lshl_add_u64 v[36:37], v[10:11], 0, v[36:37]
	v_lshl_add_u64 v[34:35], v[10:11], 0, v[34:35]
	v_lshl_add_u64 v[40:41], v[10:11], 0, v[40:41]
	v_lshl_add_u64 v[38:39], v[10:11], 0, v[38:39]
	v_lshl_add_u64 v[44:45], v[10:11], 0, v[44:45]
	v_lshl_add_u64 v[42:43], v[10:11], 0, v[42:43]
	v_lshl_add_u64 v[48:49], v[10:11], 0, v[48:49]
	v_lshl_add_u64 v[46:47], v[10:11], 0, v[46:47]
	global_load_dword v66, v[20:21], off
	global_load_dword v67, v[18:19], off
	global_load_dword v68, v[24:25], off
	global_load_dword v69, v[22:23], off
	global_load_dword v70, v[28:29], off
	global_load_dword v71, v[26:27], off
	global_load_dword v72, v[32:33], off
	global_load_dword v73, v[30:31], off
	global_load_dword v74, v[36:37], off
	global_load_dword v75, v[34:35], off
	global_load_dword v76, v[40:41], off
	global_load_dword v77, v[38:39], off
	global_load_dword v78, v[44:45], off
	global_load_dword v79, v[42:43], off
	global_load_dword v80, v[48:49], off
	global_load_dword v81, v[46:47], off
	s_add_i32 s14, s14, 16
	s_add_i32 s15, s15, 16
	s_add_i32 s9, s9, -16
	v_mad_u64_u32 v[18:19], s[16:17], v51, s13, v[6:7]
	s_cmp_lg_u32 s9, 0
	v_mad_u64_u32 v[20:21], s[16:17], v50, s13, v[6:7]
	v_mad_u64_u32 v[22:23], s[16:17], v53, s13, v[6:7]
	v_mad_u64_u32 v[24:25], s[16:17], v52, s13, v[6:7]
	v_mad_u64_u32 v[26:27], s[16:17], v55, s13, v[6:7]
	v_mad_u64_u32 v[28:29], s[16:17], v54, s13, v[6:7]
	v_mad_u64_u32 v[30:31], s[16:17], v57, s13, v[6:7]
	v_mad_u64_u32 v[32:33], s[16:17], v56, s13, v[6:7]
	v_mad_u64_u32 v[34:35], s[16:17], v59, s13, v[6:7]
	v_mad_u64_u32 v[36:37], s[16:17], v58, s13, v[6:7]
	v_mad_u64_u32 v[38:39], s[16:17], v61, s13, v[6:7]
	v_mad_u64_u32 v[40:41], s[16:17], v60, s13, v[6:7]
	v_mad_u64_u32 v[42:43], s[16:17], v63, s13, v[6:7]
	v_mad_u64_u32 v[44:45], s[16:17], v62, s13, v[6:7]
	v_mad_u64_u32 v[46:47], s[16:17], v65, s13, v[6:7]
	v_mad_u64_u32 v[48:49], s[16:17], v64, s13, v[6:7]
	s_nop 7
	s_lshl_b32 s16, s15, 1
	s_lshl_b32 s17, s14, 1
	v_or_b32_e32 v172, s16, v1
	v_or_b32_e32 v173, s17, v2
	s_add_i32 s18, s16, 4
	s_add_i32 s19, s17, 4
	s_add_i32 s20, s16, 8
	s_add_i32 s21, s17, 8
	s_add_i32 s22, s16, 12
	s_add_i32 s23, s17, 12
	s_add_i32 s24, s16, 16
	s_add_i32 s25, s17, 16
	s_add_i32 s26, s16, 20
	s_add_i32 s27, s17, 20
	s_add_i32 s28, s16, 24
	s_add_i32 s29, s17, 24
	s_add_i32 s16, s16, 28
	s_add_i32 s17, s17, 28
	v_add_u32_e32 v142, s8, v173
	v_or_b32_e32 v174, s18, v1
	v_or_b32_e32 v175, s19, v2
	v_or_b32_e32 v176, s20, v1
	v_or_b32_e32 v177, s21, v2
	v_or_b32_e32 v178, s22, v1
	v_or_b32_e32 v179, s23, v2
	v_or_b32_e32 v180, s24, v1
	v_or_b32_e32 v181, s25, v2
	v_or_b32_e32 v182, s26, v1
	v_or_b32_e32 v183, s27, v2
	v_or_b32_e32 v184, s28, v1
	v_or_b32_e32 v185, s29, v2
	v_or_b32_e32 v186, s16, v1
	v_or_b32_e32 v187, s17, v2
	v_add_u32_e32 v140, s7, v172
	v_ashrrev_i32_e32 v143, 31, v142
	v_add_u32_e32 v144, s7, v174
; __device__ __forceinline__ void p0_transpose_item(const float* W, int N, bf16_t* WT, int ldt, int k0, int n0, int nrow0, int kcol0, LAS float* scr, int lane) {
;     ...
;     for (int i = 0; i < 32; ++i) { const int kk = 2 * i + (lane >> 5); scr[kk * 33 + (lane & 31)] = W[(size_t)(k0 + kk) * N + n0 + (lane & 31)]; }
	v_add_u32_e32 v146, s8, v175
	v_add_u32_e32 v148, s7, v176
	v_add_u32_e32 v150, s8, v177
	v_add_u32_e32 v152, s7, v178
	v_add_u32_e32 v154, s8, v179
	v_add_u32_e32 v156, s7, v180
	v_add_u32_e32 v158, s8, v181
	v_add_u32_e32 v160, s7, v182
	v_add_u32_e32 v162, s8, v183
	v_add_u32_e32 v164, s7, v184
	v_add_u32_e32 v166, s8, v185
	v_add_u32_e32 v168, s7, v186
	v_add_u32_e32 v170, s8, v187
	v_ashrrev_i32_e32 v141, 31, v140
	v_lshlrev_b64 v[142:143], 14, v[142:143]
	v_ashrrev_i32_e32 v147, 31, v146
	v_ashrrev_i32_e32 v145, 31, v144
	v_ashrrev_i32_e32 v151, 31, v150
	v_ashrrev_i32_e32 v149, 31, v148
	v_ashrrev_i32_e32 v155, 31, v154
	v_ashrrev_i32_e32 v153, 31, v152
	v_ashrrev_i32_e32 v159, 31, v158
	v_ashrrev_i32_e32 v157, 31, v156
	v_ashrrev_i32_e32 v163, 31, v162
	v_ashrrev_i32_e32 v161, 31, v160
	v_ashrrev_i32_e32 v167, 31, v166
	v_ashrrev_i32_e32 v165, 31, v164
	v_ashrrev_i32_e32 v171, 31, v170
	v_ashrrev_i32_e32 v169, 31, v168
	v_lshlrev_b64 v[140:141], 14, v[140:141]
	v_lshl_add_u64 v[142:143], v[10:11], 0, v[142:143]
	v_lshlrev_b64 v[144:145], 14, v[144:145]
	v_lshlrev_b64 v[146:147], 14, v[146:147]
	v_lshlrev_b64 v[148:149], 14, v[148:149]
	v_lshlrev_b64 v[150:151], 14, v[150:151]
	v_lshlrev_b64 v[152:153], 14, v[152:153]
	v_lshlrev_b64 v[154:155], 14, v[154:155]
	v_lshlrev_b64 v[156:157], 14, v[156:157]
	v_lshlrev_b64 v[158:159], 14, v[158:159]
	v_lshlrev_b64 v[160:161], 14, v[160:161]
	v_lshlrev_b64 v[162:163], 14, v[162:163]
	v_lshlrev_b64 v[164:165], 14, v[164:165]
	v_lshlrev_b64 v[166:167], 14, v[166:167]
	v_lshlrev_b64 v[168:169], 14, v[168:169]
	v_lshlrev_b64 v[170:171], 14, v[170:171]
	v_lshl_add_u64 v[140:141], v[10:11], 0, v[140:141]
	v_lshl_add_u64 v[146:147], v[10:11], 0, v[146:147]
	v_lshl_add_u64 v[144:145], v[10:11], 0, v[144:145]
	v_lshl_add_u64 v[150:151], v[10:11], 0, v[150:151]
	v_lshl_add_u64 v[148:149], v[10:11], 0, v[148:149]
	v_lshl_add_u64 v[154:155], v[10:11], 0, v[154:155]
	v_lshl_add_u64 v[152:153], v[10:11], 0, v[152:153]
	v_lshl_add_u64 v[158:159], v[10:11], 0, v[158:159]
	v_lshl_add_u64 v[156:157], v[10:11], 0, v[156:157]
	v_lshl_add_u64 v[162:163], v[10:11], 0, v[162:163]
	v_lshl_add_u64 v[160:161], v[10:11], 0, v[160:161]
	v_lshl_add_u64 v[166:167], v[10:11], 0, v[166:167]
	v_lshl_add_u64 v[164:165], v[10:11], 0, v[164:165]
	v_lshl_add_u64 v[170:171], v[10:11], 0, v[170:171]
	v_lshl_add_u64 v[168:169], v[10:11], 0, v[168:169]
	global_load_dword v188, v[142:143], off
	global_load_dword v189, v[140:141], off
	global_load_dword v190, v[146:147], off
	global_load_dword v191, v[144:145], off
	global_load_dword v192, v[150:151], off
	global_load_dword v193, v[148:149], off
	global_load_dword v194, v[154:155], off
	global_load_dword v195, v[152:153], off
	global_load_dword v196, v[158:159], off
	global_load_dword v197, v[156:157], off
	global_load_dword v198, v[162:163], off
	global_load_dword v199, v[160:161], off
	global_load_dword v200, v[166:167], off
	global_load_dword v201, v[164:165], off
	global_load_dword v202, v[170:171], off
	global_load_dword v203, v[168:169], off
	s_add_i32 s14, s14, 16
	s_add_i32 s15, s15, 16
	s_add_i32 s9, s9, -16
	v_mad_u64_u32 v[140:141], s[16:17], v173, s13, v[6:7]
	s_cmp_lg_u32 s9, 0
	v_mad_u64_u32 v[142:143], s[16:17], v172, s13, v[6:7]
	v_mad_u64_u32 v[144:145], s[16:17], v175, s13, v[6:7]
	v_mad_u64_u32 v[146:147], s[16:17], v174, s13, v[6:7]
	v_mad_u64_u32 v[148:149], s[16:17], v177, s13, v[6:7]
	v_mad_u64_u32 v[150:151], s[16:17], v176, s13, v[6:7]
	v_mad_u64_u32 v[152:153], s[16:17], v179, s13, v[6:7]
	v_mad_u64_u32 v[154:155], s[16:17], v178, s13, v[6:7]
	v_mad_u64_u32 v[156:157], s[16:17], v181, s13, v[6:7]
	v_mad_u64_u32 v[158:159], s[16:17], v180, s13, v[6:7]
	v_mad_u64_u32 v[160:161], s[16:17], v183, s13, v[6:7]
	v_mad_u64_u32 v[162:163], s[16:17], v182, s13, v[6:7]
	v_mad_u64_u32 v[164:165], s[16:17], v185, s13, v[6:7]
	v_mad_u64_u32 v[166:167], s[16:17], v184, s13, v[6:7]
	v_mad_u64_u32 v[168:169], s[16:17], v187, s13, v[6:7]
	v_mad_u64_u32 v[170:171], s[16:17], v186, s13, v[6:7]
	s_waitcnt vmcnt(31)
; #define LAS __attribute__((address_space(3)))
; __device__ __forceinline__ unsigned cvt_pk_bf16(float lo, float hi) { unsigned r; asm volatile("v_cvt_pk_bf16_f32 %0, %1, %2" : "=v"(r) : "v"(lo), "v"(hi)); return r; }
; #define LDS_WAIT() asm volatile("s_waitcnt lgkmcnt(0)" ::: "memory")
; __device__ __forceinline__ void p0_transpose_item(const float* W, int N, bf16_t* WT, int ldt, int k0, int n0, int nrow0, int kcol0, LAS float* scr, int lane) {
;     ...
;     for (int i = 0; i < 32; ++i) { const int kk = 2 * i + (lane >> 5); scr[kk * 33 + (lane & 31)] = W[(size_t)(k0 + kk) * N + n0 + (lane & 31)]; }
;     LDS_WAIT(); asm volatile("" ::: "memory");
;     const int c = lane & 7;
; #pragma unroll
;     for (int j = 0; j < 4; ++j) { const int n = (lane >> 3) + 8 * j; const LAS float* s = scr + (8 * c) * 33 + n;
;         u32x4 o; o.x = cvt_pk_bf16(s[0 * 33], s[1 * 33]); o.y = cvt_pk_bf16(s[2 * 33], s[3 * 33]); o.z = cvt_pk_bf16(s[4 * 33], s[5 * 33]); o.w = cvt_pk_bf16(s[6 * 33], s[7 * 33]);
;         *(u32x4*)(WT + (size_t)(nrow0 + n) * ldt + kcol0 + k0 + 8 * c) = o; }
;     LDS_WAIT(); asm volatile("" ::: "memory");
; __device__ __forceinline__ void p0_prologue(const Frame& F) {
;     ...
;                 for (int it = first; it < nitems; it += NGW) { const int kb = it / nblk, nbk = it % nblk, n0 = nbk * 32;
;                     const int nrow0 = (jb == 0 && n0 >= 3392) ? n0 + 192 : n0;
;                     p0_transpose_item(W, J.N, WT, J.ldt, kb * 64, n0, nrow0, J.kcol0, scr, F.lane); }
	ds_write_b32 v18, v66
	s_waitcnt vmcnt(30)
	ds_write_b32 v20, v67
	s_waitcnt vmcnt(29)
	ds_write_b32 v22, v68
	s_waitcnt vmcnt(28)
	ds_write_b32 v24, v69
	s_waitcnt vmcnt(27)
	ds_write_b32 v26, v70
	s_waitcnt vmcnt(26)
	ds_write_b32 v28, v71
	s_waitcnt vmcnt(25)
	ds_write_b32 v30, v72
	s_waitcnt vmcnt(24)
	ds_write_b32 v32, v73
	s_waitcnt vmcnt(23)
	ds_write_b32 v34, v74
	s_waitcnt vmcnt(22)
	ds_write_b32 v36, v75
	s_waitcnt vmcnt(21)
	ds_write_b32 v38, v76
	s_waitcnt vmcnt(20)
	ds_write_b32 v40, v77
	s_waitcnt vmcnt(19)
	ds_write_b32 v42, v78
	s_waitcnt vmcnt(18)
	ds_write_b32 v44, v79
	s_waitcnt vmcnt(17)
	ds_write_b32 v46, v80
	s_waitcnt vmcnt(16)
	ds_write_b32 v48, v81
	s_waitcnt vmcnt(15)
	ds_write_b32 v140, v188
	s_waitcnt vmcnt(14)
	ds_write_b32 v142, v189
	s_waitcnt vmcnt(13)
	ds_write_b32 v144, v190
	s_waitcnt vmcnt(12)
	ds_write_b32 v146, v191
	s_waitcnt vmcnt(11)
	ds_write_b32 v148, v192
	s_waitcnt vmcnt(10)
	ds_write_b32 v150, v193
	s_waitcnt vmcnt(9)
	ds_write_b32 v152, v194
	s_waitcnt vmcnt(8)
	ds_write_b32 v154, v195
	s_waitcnt vmcnt(7)
	ds_write_b32 v156, v196
	s_waitcnt vmcnt(6)
	ds_write_b32 v158, v197
	s_waitcnt vmcnt(5)
	ds_write_b32 v160, v198
	s_waitcnt vmcnt(4)
	ds_write_b32 v162, v199
	s_waitcnt vmcnt(3)
	ds_write_b32 v164, v200
	s_waitcnt vmcnt(2)
	ds_write_b32 v166, v201
	s_waitcnt vmcnt(1)
	ds_write_b32 v168, v202
	s_waitcnt vmcnt(0)
	ds_write_b32 v170, v203
	s_waitcnt lgkmcnt(0)
	v_or_b32_e32 v22, s6, v3
	ds_read2_b32 v[10:11], v7 offset1:33
	s_ashr_i32 s9, s8, 31
	v_ashrrev_i32_e32 v23, 31, v22
	s_waitcnt lgkmcnt(0)
	v_cvt_pk_bf16_f32 v18, v10, v11
	ds_read2_b32 v[10:11], v7 offset0:66 offset1:99
	v_lshl_add_u64 v[24:25], s[8:9], 1, v[8:9]
	v_lshlrev_b64 v[22:23], 10, v[22:23]
	s_waitcnt lgkmcnt(0)
	v_cvt_pk_bf16_f32 v19, v10, v11
	ds_read2_b32 v[10:11], v7 offset0:132 offset1:165
	v_lshl_add_u64 v[22:23], v[24:25], 0, v[22:23]
	s_waitcnt lgkmcnt(0)
	v_cvt_pk_bf16_f32 v20, v10, v11
	ds_read2_b32 v[10:11], v7 offset0:198 offset1:231
	s_waitcnt lgkmcnt(0)
	v_cvt_pk_bf16_f32 v21, v10, v11
	global_store_dwordx4 v[22:23], v[18:21], off
	v_or_b32_e32 v22, s6, v13
	ds_read2_b32 v[10:11], v7 offset0:8 offset1:41
	v_ashrrev_i32_e32 v23, 31, v22
	s_waitcnt lgkmcnt(0)
	v_cvt_pk_bf16_f32 v18, v10, v11
	ds_read2_b32 v[10:11], v7 offset0:74 offset1:107
	v_lshlrev_b64 v[22:23], 10, v[22:23]
	s_waitcnt lgkmcnt(0)
	v_cvt_pk_bf16_f32 v19, v10, v11
	ds_read2_b32 v[10:11], v7 offset0:140 offset1:173
	v_lshl_add_u64 v[22:23], v[24:25], 0, v[22:23]
	s_waitcnt lgkmcnt(0)
	v_cvt_pk_bf16_f32 v20, v10, v11
	ds_read2_b32 v[10:11], v7 offset0:206 offset1:239
	s_waitcnt lgkmcnt(0)
	v_cvt_pk_bf16_f32 v21, v10, v11
	global_store_dwordx4 v[22:23], v[18:21], off
	v_or_b32_e32 v22, s6, v16
	ds_read2_b32 v[10:11], v7 offset0:16 offset1:49
	v_ashrrev_i32_e32 v23, 31, v22
	s_waitcnt lgkmcnt(0)
	v_cvt_pk_bf16_f32 v18, v10, v11
	ds_read2_b32 v[10:11], v7 offset0:82 offset1:115
	v_lshlrev_b64 v[22:23], 10, v[22:23]
	s_waitcnt lgkmcnt(0)
	v_cvt_pk_bf16_f32 v19, v10, v11
	ds_read2_b32 v[10:11], v7 offset0:148 offset1:181
	v_lshl_add_u64 v[22:23], v[24:25], 0, v[22:23]
	s_waitcnt lgkmcnt(0)
	v_cvt_pk_bf16_f32 v20, v10, v11
	ds_read2_b32 v[10:11], v7 offset0:214 offset1:247
	s_waitcnt lgkmcnt(0)
	v_cvt_pk_bf16_f32 v21, v10, v11
	global_store_dwordx4 v[22:23], v[18:21], off
	v_or_b32_e32 v22, s6, v17
	ds_read2_b32 v[10:11], v7 offset0:24 offset1:57
	v_ashrrev_i32_e32 v23, 31, v22
	s_waitcnt lgkmcnt(0)
	v_cvt_pk_bf16_f32 v18, v10, v11
	ds_read2_b32 v[10:11], v7 offset0:90 offset1:123
	v_lshlrev_b64 v[22:23], 10, v[22:23]
	s_waitcnt lgkmcnt(0)
	v_cvt_pk_bf16_f32 v19, v10, v11
	ds_read2_b32 v[10:11], v7 offset0:156 offset1:189
	v_lshl_add_u64 v[22:23], v[24:25], 0, v[22:23]
	s_waitcnt lgkmcnt(0)
	v_cvt_pk_bf16_f32 v20, v10, v11
	ds_read2_b32 v[10:11], v7 offset0:222 offset1:255
	s_waitcnt lgkmcnt(0)
	v_cvt_pk_bf16_f32 v21, v10, v11
	global_store_dwordx4 v[22:23], v[18:21], off
	s_waitcnt lgkmcnt(0)
	s_add_i32 s12, s12, s3
	s_cmpk_lt_i32 s12, 0x400
	s_cbranch_scc1 .LBB0_84

; __device__ __forceinline__ void p0_transpose_item(const float* W, int N, bf16_t* WT, int ldt, int k0, int n0, int nrow0, int kcol0, LAS float* scr, int lane) {
; #pragma unroll 8
;     for (int i = 0; i < 32; ++i) { const int kk = 2 * i + (lane >> 5); scr[kk * 33 + (lane & 31)] = W[(size_t)(k0 + kk) * N + n0 + (lane & 31)]; }
.LBB0_90:
	s_lshl_b32 s16, s15, 1
	s_lshl_b32 s17, s14, 1
	v_or_b32_e32 v50, s16, v1
	v_or_b32_e32 v51, s17, v2
	s_add_i32 s18, s16, 4
	s_add_i32 s19, s17, 4
	s_add_i32 s20, s16, 8
	s_add_i32 s21, s17, 8
	s_add_i32 s22, s16, 12
	s_add_i32 s23, s17, 12
	s_add_i32 s24, s16, 16
	s_add_i32 s25, s17, 16
	s_add_i32 s26, s16, 20
	s_add_i32 s27, s17, 20
	s_add_i32 s28, s16, 24
	s_add_i32 s29, s17, 24
	s_add_i32 s16, s16, 28
	s_add_i32 s17, s17, 28
	v_add_u32_e32 v20, s8, v51
	v_or_b32_e32 v52, s18, v1
	v_or_b32_e32 v53, s19, v2
	v_or_b32_e32 v54, s20, v1
	v_or_b32_e32 v55, s21, v2
	v_or_b32_e32 v56, s22, v1
	v_or_b32_e32 v57, s23, v2
	v_or_b32_e32 v58, s24, v1
	v_or_b32_e32 v59, s25, v2
	v_or_b32_e32 v60, s26, v1
	v_or_b32_e32 v61, s27, v2
	v_or_b32_e32 v62, s28, v1
	v_or_b32_e32 v63, s29, v2
	v_or_b32_e32 v64, s16, v1
	v_or_b32_e32 v65, s17, v2
	v_add_u32_e32 v18, s7, v50
	v_ashrrev_i32_e32 v21, 31, v20
	v_add_u32_e32 v22, s7, v52
	v_add_u32_e32 v24, s8, v53
	v_add_u32_e32 v26, s7, v54
	v_add_u32_e32 v28, s8, v55
	v_add_u32_e32 v30, s7, v56
	v_add_u32_e32 v32, s8, v57
	v_add_u32_e32 v34, s7, v58
	v_add_u32_e32 v36, s8, v59
	v_add_u32_e32 v38, s7, v60
	v_add_u32_e32 v40, s8, v61
	v_add_u32_e32 v42, s7, v62
	v_add_u32_e32 v44, s8, v63
	v_add_u32_e32 v46, s7, v64
	v_add_u32_e32 v48, s8, v65
	v_ashrrev_i32_e32 v19, 31, v18
	v_lshlrev_b64 v[20:21], 12, v[20:21]
	v_ashrrev_i32_e32 v25, 31, v24
	v_ashrrev_i32_e32 v23, 31, v22
	v_ashrrev_i32_e32 v29, 31, v28
	v_ashrrev_i32_e32 v27, 31, v26
	v_ashrrev_i32_e32 v33, 31, v32
	v_ashrrev_i32_e32 v31, 31, v30
	v_ashrrev_i32_e32 v37, 31, v36
	v_ashrrev_i32_e32 v35, 31, v34
	v_ashrrev_i32_e32 v41, 31, v40
	v_ashrrev_i32_e32 v39, 31, v38
	v_ashrrev_i32_e32 v45, 31, v44
	v_ashrrev_i32_e32 v43, 31, v42
	v_ashrrev_i32_e32 v49, 31, v48
	v_ashrrev_i32_e32 v47, 31, v46
	v_lshlrev_b64 v[18:19], 12, v[18:19]
	v_lshl_add_u64 v[20:21], v[10:11], 0, v[20:21]
	v_lshlrev_b64 v[22:23], 12, v[22:23]
	v_lshlrev_b64 v[24:25], 12, v[24:25]
	v_lshlrev_b64 v[26:27], 12, v[26:27]
	v_lshlrev_b64 v[28:29], 12, v[28:29]
	v_lshlrev_b64 v[30:31], 12, v[30:31]
	v_lshlrev_b64 v[32:33], 12, v[32:33]
	v_lshlrev_b64 v[34:35], 12, v[34:35]
	v_lshlrev_b64 v[36:37], 12, v[36:37]
	v_lshlrev_b64 v[38:39], 12, v[38:39]
	v_lshlrev_b64 v[40:41], 12, v[40:41]
	v_lshlrev_b64 v[42:43], 12, v[42:43]
	v_lshlrev_b64 v[44:45], 12, v[44:45]
	v_lshlrev_b64 v[46:47], 12, v[46:47]
	v_lshlrev_b64 v[48:49], 12, v[48:49]
	v_lshl_add_u64 v[18:19], v[10:11], 0, v[18:19]
	v_lshl_add_u64 v[24:25], v[10:11], 0, v[24:25]
	v_lshl_add_u64 v[22:23], v[10:11], 0, v[22:23]
	v_lshl_add_u64 v[28:29], v[10:11], 0, v[28:29]
	v_lshl_add_u64 v[26:27], v[10:11], 0, v[26:27]
	v_lshl_add_u64 v[32:33], v[10:11], 0, v[32:33]
	v_lshl_add_u64 v[30:31], v[10:11], 0, v[30:31]
	v_lshl_add_u64 v[36:37], v[10:11], 0, v[36:37]
	v_lshl_add_u64 v[34:35], v[10:11], 0, v[34:35]
	v_lshl_add_u64 v[40:41], v[10:11], 0, v[40:41]
	v_lshl_add_u64 v[38:39], v[10:11], 0, v[38:39]
	v_lshl_add_u64 v[44:45], v[10:11], 0, v[44:45]
	v_lshl_add_u64 v[42:43], v[10:11], 0, v[42:43]
	v_lshl_add_u64 v[48:49], v[10:11], 0, v[48:49]
	v_lshl_add_u64 v[46:47], v[10:11], 0, v[46:47]
	global_load_dword v66, v[20:21], off
	global_load_dword v67, v[18:19], off
	global_load_dword v68, v[24:25], off
	global_load_dword v69, v[22:23], off
	global_load_dword v70, v[28:29], off
	global_load_dword v71, v[26:27], off
	global_load_dword v72, v[32:33], off
	global_load_dword v73, v[30:31], off
	global_load_dword v74, v[36:37], off
	global_load_dword v75, v[34:35], off
	global_load_dword v76, v[40:41], off
	global_load_dword v77, v[38:39], off
	global_load_dword v78, v[44:45], off
	global_load_dword v79, v[42:43], off
	global_load_dword v80, v[48:49], off
	global_load_dword v81, v[46:47], off
	s_add_i32 s14, s14, 16
	s_add_i32 s15, s15, 16
	s_add_i32 s9, s9, -16
	v_mad_u64_u32 v[18:19], s[16:17], v51, s13, v[6:7]
	s_cmp_lg_u32 s9, 0
	v_mad_u64_u32 v[20:21], s[16:17], v50, s13, v[6:7]
	v_mad_u64_u32 v[22:23], s[16:17], v53, s13, v[6:7]
	v_mad_u64_u32 v[24:25], s[16:17], v52, s13, v[6:7]
	v_mad_u64_u32 v[26:27], s[16:17], v55, s13, v[6:7]
	v_mad_u64_u32 v[28:29], s[16:17], v54, s13, v[6:7]
	v_mad_u64_u32 v[30:31], s[16:17], v57, s13, v[6:7]
	v_mad_u64_u32 v[32:33], s[16:17], v56, s13, v[6:7]
	v_mad_u64_u32 v[34:35], s[16:17], v59, s13, v[6:7]
	v_mad_u64_u32 v[36:37], s[16:17], v58, s13, v[6:7]
	v_mad_u64_u32 v[38:39], s[16:17], v61, s13, v[6:7]
	v_mad_u64_u32 v[40:41], s[16:17], v60, s13, v[6:7]
	v_mad_u64_u32 v[42:43], s[16:17], v63, s13, v[6:7]
	v_mad_u64_u32 v[44:45], s[16:17], v62, s13, v[6:7]
	v_mad_u64_u32 v[46:47], s[16:17], v65, s13, v[6:7]
	v_mad_u64_u32 v[48:49], s[16:17], v64, s13, v[6:7]
	s_nop 7
	s_lshl_b32 s16, s15, 1
	s_lshl_b32 s17, s14, 1
	v_or_b32_e32 v172, s16, v1
	v_or_b32_e32 v173, s17, v2
	s_add_i32 s18, s16, 4
	s_add_i32 s19, s17, 4
	s_add_i32 s20, s16, 8
	s_add_i32 s21, s17, 8
	s_add_i32 s22, s16, 12
	s_add_i32 s23, s17, 12
	s_add_i32 s24, s16, 16
	s_add_i32 s25, s17, 16
	s_add_i32 s26, s16, 20
	s_add_i32 s27, s17, 20
	s_add_i32 s28, s16, 24
	s_add_i32 s29, s17, 24
	s_add_i32 s16, s16, 28
	s_add_i32 s17, s17, 28
	v_add_u32_e32 v142, s8, v173
	v_or_b32_e32 v174, s18, v1
	v_or_b32_e32 v175, s19, v2
	v_or_b32_e32 v176, s20, v1
	v_or_b32_e32 v177, s21, v2
	v_or_b32_e32 v178, s22, v1
	v_or_b32_e32 v179, s23, v2
	v_or_b32_e32 v180, s24, v1
	v_or_b32_e32 v181, s25, v2
	v_or_b32_e32 v182, s26, v1
	v_or_b32_e32 v183, s27, v2
	v_or_b32_e32 v184, s28, v1
	v_or_b32_e32 v185, s29, v2
	v_or_b32_e32 v186, s16, v1
	v_or_b32_e32 v187, s17, v2
	v_add_u32_e32 v140, s7, v172
	v_ashrrev_i32_e32 v143, 31, v142
	v_add_u32_e32 v144, s7, v174
; __device__ __forceinline__ void p0_transpose_item(const float* W, int N, bf16_t* WT, int ldt, int k0, int n0, int nrow0, int kcol0, LAS float* scr, int lane) {
;     ...
;     for (int i = 0; i < 32; ++i) { const int kk = 2 * i + (lane >> 5); scr[kk * 33 + (lane & 31)] = W[(size_t)(k0 + kk) * N + n0 + (lane & 31)]; }
	v_add_u32_e32 v146, s8, v175
	v_add_u32_e32 v148, s7, v176
	v_add_u32_e32 v150, s8, v177
	v_add_u32_e32 v152, s7, v178
	v_add_u32_e32 v154, s8, v179
	v_add_u32_e32 v156, s7, v180
	v_add_u32_e32 v158, s8, v181
	v_add_u32_e32 v160, s7, v182
	v_add_u32_e32 v162, s8, v183
	v_add_u32_e32 v164, s7, v184
	v_add_u32_e32 v166, s8, v185
	v_add_u32_e32 v168, s7, v186
	v_add_u32_e32 v170, s8, v187
	v_ashrrev_i32_e32 v141, 31, v140
	v_lshlrev_b64 v[142:143], 12, v[142:143]
	v_ashrrev_i32_e32 v147, 31, v146
	v_ashrrev_i32_e32 v145, 31, v144
	v_ashrrev_i32_e32 v151, 31, v150
	v_ashrrev_i32_e32 v149, 31, v148
	v_ashrrev_i32_e32 v155, 31, v154
	v_ashrrev_i32_e32 v153, 31, v152
	v_ashrrev_i32_e32 v159, 31, v158
	v_ashrrev_i32_e32 v157, 31, v156
	v_ashrrev_i32_e32 v163, 31, v162
	v_ashrrev_i32_e32 v161, 31, v160
	v_ashrrev_i32_e32 v167, 31, v166
	v_ashrrev_i32_e32 v165, 31, v164
	v_ashrrev_i32_e32 v171, 31, v170
	v_ashrrev_i32_e32 v169, 31, v168
	v_lshlrev_b64 v[140:141], 12, v[140:141]
	v_lshl_add_u64 v[142:143], v[10:11], 0, v[142:143]
	v_lshlrev_b64 v[144:145], 12, v[144:145]
	v_lshlrev_b64 v[146:147], 12, v[146:147]
	v_lshlrev_b64 v[148:149], 12, v[148:149]
	v_lshlrev_b64 v[150:151], 12, v[150:151]
	v_lshlrev_b64 v[152:153], 12, v[152:153]
	v_lshlrev_b64 v[154:155], 12, v[154:155]
	v_lshlrev_b64 v[156:157], 12, v[156:157]
	v_lshlrev_b64 v[158:159], 12, v[158:159]
	v_lshlrev_b64 v[160:161], 12, v[160:161]
	v_lshlrev_b64 v[162:163], 12, v[162:163]
	v_lshlrev_b64 v[164:165], 12, v[164:165]
	v_lshlrev_b64 v[166:167], 12, v[166:167]
	v_lshlrev_b64 v[168:169], 12, v[168:169]
	v_lshlrev_b64 v[170:171], 12, v[170:171]
	v_lshl_add_u64 v[140:141], v[10:11], 0, v[140:141]
	v_lshl_add_u64 v[146:147], v[10:11], 0, v[146:147]
	v_lshl_add_u64 v[144:145], v[10:11], 0, v[144:145]
	v_lshl_add_u64 v[150:151], v[10:11], 0, v[150:151]
	v_lshl_add_u64 v[148:149], v[10:11], 0, v[148:149]
	v_lshl_add_u64 v[154:155], v[10:11], 0, v[154:155]
	v_lshl_add_u64 v[152:153], v[10:11], 0, v[152:153]
	v_lshl_add_u64 v[158:159], v[10:11], 0, v[158:159]
	v_lshl_add_u64 v[156:157], v[10:11], 0, v[156:157]
	v_lshl_add_u64 v[162:163], v[10:11], 0, v[162:163]
	v_lshl_add_u64 v[160:161], v[10:11], 0, v[160:161]
	v_lshl_add_u64 v[166:167], v[10:11], 0, v[166:167]
	v_lshl_add_u64 v[164:165], v[10:11], 0, v[164:165]
	v_lshl_add_u64 v[170:171], v[10:11], 0, v[170:171]
	v_lshl_add_u64 v[168:169], v[10:11], 0, v[168:169]
	global_load_dword v188, v[142:143], off
	global_load_dword v189, v[140:141], off
	global_load_dword v190, v[146:147], off
	global_load_dword v191, v[144:145], off
	global_load_dword v192, v[150:151], off
	global_load_dword v193, v[148:149], off
	global_load_dword v194, v[154:155], off
	global_load_dword v195, v[152:153], off
	global_load_dword v196, v[158:159], off
	global_load_dword v197, v[156:157], off
	global_load_dword v198, v[162:163], off
	global_load_dword v199, v[160:161], off
	global_load_dword v200, v[166:167], off
	global_load_dword v201, v[164:165], off
	global_load_dword v202, v[170:171], off
	global_load_dword v203, v[168:169], off
	s_add_i32 s14, s14, 16
	s_add_i32 s15, s15, 16
	s_add_i32 s9, s9, -16
	v_mad_u64_u32 v[140:141], s[16:17], v173, s13, v[6:7]
	s_cmp_lg_u32 s9, 0
	v_mad_u64_u32 v[142:143], s[16:17], v172, s13, v[6:7]
	v_mad_u64_u32 v[144:145], s[16:17], v175, s13, v[6:7]
	v_mad_u64_u32 v[146:147], s[16:17], v174, s13, v[6:7]
	v_mad_u64_u32 v[148:149], s[16:17], v177, s13, v[6:7]
	v_mad_u64_u32 v[150:151], s[16:17], v176, s13, v[6:7]
	v_mad_u64_u32 v[152:153], s[16:17], v179, s13, v[6:7]
	v_mad_u64_u32 v[154:155], s[16:17], v178, s13, v[6:7]
	v_mad_u64_u32 v[156:157], s[16:17], v181, s13, v[6:7]
	v_mad_u64_u32 v[158:159], s[16:17], v180, s13, v[6:7]
	v_mad_u64_u32 v[160:161], s[16:17], v183, s13, v[6:7]
	v_mad_u64_u32 v[162:163], s[16:17], v182, s13, v[6:7]
	v_mad_u64_u32 v[164:165], s[16:17], v185, s13, v[6:7]
	v_mad_u64_u32 v[166:167], s[16:17], v184, s13, v[6:7]
	v_mad_u64_u32 v[168:169], s[16:17], v187, s13, v[6:7]
	v_mad_u64_u32 v[170:171], s[16:17], v186, s13, v[6:7]
	s_waitcnt vmcnt(31)
; #define LAS __attribute__((address_space(3)))
; __device__ __forceinline__ unsigned cvt_pk_bf16(float lo, float hi) { unsigned r; asm volatile("v_cvt_pk_bf16_f32 %0, %1, %2" : "=v"(r) : "v"(lo), "v"(hi)); return r; }
; #define LDS_WAIT() asm volatile("s_waitcnt lgkmcnt(0)" ::: "memory")
; __device__ __forceinline__ void p0_transpose_item(const float* W, int N, bf16_t* WT, int ldt, int k0, int n0, int nrow0, int kcol0, LAS float* scr, int lane) {
;     ...
;     for (int i = 0; i < 32; ++i) { const int kk = 2 * i + (lane >> 5); scr[kk * 33 + (lane & 31)] = W[(size_t)(k0 + kk) * N + n0 + (lane & 31)]; }
;     LDS_WAIT(); asm volatile("" ::: "memory");
;     const int c = lane & 7;
; #pragma unroll
;     for (int j = 0; j < 4; ++j) { const int n = (lane >> 3) + 8 * j; const LAS float* s = scr + (8 * c) * 33 + n;
;         u32x4 o; o.x = cvt_pk_bf16(s[0 * 33], s[1 * 33]); o.y = cvt_pk_bf16(s[2 * 33], s[3 * 33]); o.z = cvt_pk_bf16(s[4 * 33], s[5 * 33]); o.w = cvt_pk_bf16(s[6 * 33], s[7 * 33]);
;         *(u32x4*)(WT + (size_t)(nrow0 + n) * ldt + kcol0 + k0 + 8 * c) = o; }
;     LDS_WAIT(); asm volatile("" ::: "memory");
; __device__ __forceinline__ void p0_prologue(const Frame& F) {
;     ...
;                 for (int it = first; it < nitems; it += NGW) { const int kb = it / nblk, nbk = it % nblk, n0 = nbk * 32;
;                     const int nrow0 = (jb == 0 && n0 >= 3392) ? n0 + 192 : n0;
;                     p0_transpose_item(W, J.N, WT, J.ldt, kb * 64, n0, nrow0, J.kcol0, scr, F.lane); }
	ds_write_b32 v18, v66
	s_waitcnt vmcnt(30)
	ds_write_b32 v20, v67
	s_waitcnt vmcnt(29)
	ds_write_b32 v22, v68
	s_waitcnt vmcnt(28)
	ds_write_b32 v24, v69
	s_waitcnt vmcnt(27)
	ds_write_b32 v26, v70
	s_waitcnt vmcnt(26)
	ds_write_b32 v28, v71
	s_waitcnt vmcnt(25)
	ds_write_b32 v30, v72
	s_waitcnt vmcnt(24)
	ds_write_b32 v32, v73
	s_waitcnt vmcnt(23)
	ds_write_b32 v34, v74
	s_waitcnt vmcnt(22)
	ds_write_b32 v36, v75
	s_waitcnt vmcnt(21)
	ds_write_b32 v38, v76
	s_waitcnt vmcnt(20)
	ds_write_b32 v40, v77
	s_waitcnt vmcnt(19)
	ds_write_b32 v42, v78
	s_waitcnt vmcnt(18)
	ds_write_b32 v44, v79
	s_waitcnt vmcnt(17)
	ds_write_b32 v46, v80
	s_waitcnt vmcnt(16)
	ds_write_b32 v48, v81
	s_waitcnt vmcnt(15)
	ds_write_b32 v140, v188
	s_waitcnt vmcnt(14)
	ds_write_b32 v142, v189
	s_waitcnt vmcnt(13)
	ds_write_b32 v144, v190
	s_waitcnt vmcnt(12)
	ds_write_b32 v146, v191
	s_waitcnt vmcnt(11)
	ds_write_b32 v148, v192
	s_waitcnt vmcnt(10)
	ds_write_b32 v150, v193
	s_waitcnt vmcnt(9)
	ds_write_b32 v152, v194
	s_waitcnt vmcnt(8)
	ds_write_b32 v154, v195
	s_waitcnt vmcnt(7)
	ds_write_b32 v156, v196
	s_waitcnt vmcnt(6)
	ds_write_b32 v158, v197
	s_waitcnt vmcnt(5)
	ds_write_b32 v160, v198
	s_waitcnt vmcnt(4)
	ds_write_b32 v162, v199
	s_waitcnt vmcnt(3)
	ds_write_b32 v164, v200
	s_waitcnt vmcnt(2)
	ds_write_b32 v166, v201
	s_waitcnt vmcnt(1)
	ds_write_b32 v168, v202
	s_waitcnt vmcnt(0)
	ds_write_b32 v170, v203
	s_waitcnt lgkmcnt(0)
	v_or_b32_e32 v22, s6, v3
	ds_read2_b32 v[10:11], v7 offset1:33
	s_ashr_i32 s9, s8, 31
	v_ashrrev_i32_e32 v23, 31, v22
	s_waitcnt lgkmcnt(0)
	v_cvt_pk_bf16_f32 v18, v10, v11
	ds_read2_b32 v[10:11], v7 offset0:66 offset1:99
	v_lshl_add_u64 v[24:25], s[8:9], 1, v[8:9]
	v_lshlrev_b64 v[22:23], 11, v[22:23]
	s_waitcnt lgkmcnt(0)
	v_cvt_pk_bf16_f32 v19, v10, v11
	ds_read2_b32 v[10:11], v7 offset0:132 offset1:165
	v_lshl_add_u64 v[22:23], v[24:25], 0, v[22:23]
	s_waitcnt lgkmcnt(0)
	v_cvt_pk_bf16_f32 v20, v10, v11
	ds_read2_b32 v[10:11], v7 offset0:198 offset1:231
	s_waitcnt lgkmcnt(0)
	v_cvt_pk_bf16_f32 v21, v10, v11
	global_store_dwordx4 v[22:23], v[18:21], off
	v_or_b32_e32 v22, s6, v13
	ds_read2_b32 v[10:11], v7 offset0:8 offset1:41
	v_ashrrev_i32_e32 v23, 31, v22
	s_waitcnt lgkmcnt(0)
	v_cvt_pk_bf16_f32 v18, v10, v11
	ds_read2_b32 v[10:11], v7 offset0:74 offset1:107
	v_lshlrev_b64 v[22:23], 11, v[22:23]
	s_waitcnt lgkmcnt(0)
	v_cvt_pk_bf16_f32 v19, v10, v11
	ds_read2_b32 v[10:11], v7 offset0:140 offset1:173
	v_lshl_add_u64 v[22:23], v[24:25], 0, v[22:23]
	s_waitcnt lgkmcnt(0)
	v_cvt_pk_bf16_f32 v20, v10, v11
	ds_read2_b32 v[10:11], v7 offset0:206 offset1:239
	s_waitcnt lgkmcnt(0)
	v_cvt_pk_bf16_f32 v21, v10, v11
	global_store_dwordx4 v[22:23], v[18:21], off
	v_or_b32_e32 v22, s6, v16
	ds_read2_b32 v[10:11], v7 offset0:16 offset1:49
	v_ashrrev_i32_e32 v23, 31, v22
	s_waitcnt lgkmcnt(0)
	v_cvt_pk_bf16_f32 v18, v10, v11
	ds_read2_b32 v[10:11], v7 offset0:82 offset1:115
	v_lshlrev_b64 v[22:23], 11, v[22:23]
	s_waitcnt lgkmcnt(0)
	v_cvt_pk_bf16_f32 v19, v10, v11
	ds_read2_b32 v[10:11], v7 offset0:148 offset1:181
	v_lshl_add_u64 v[22:23], v[24:25], 0, v[22:23]
	s_waitcnt lgkmcnt(0)
	v_cvt_pk_bf16_f32 v20, v10, v11
	ds_read2_b32 v[10:11], v7 offset0:214 offset1:247
	s_waitcnt lgkmcnt(0)
	v_cvt_pk_bf16_f32 v21, v10, v11
	global_store_dwordx4 v[22:23], v[18:21], off
	v_or_b32_e32 v22, s6, v17
	ds_read2_b32 v[10:11], v7 offset0:24 offset1:57
	v_ashrrev_i32_e32 v23, 31, v22
	s_waitcnt lgkmcnt(0)
	v_cvt_pk_bf16_f32 v18, v10, v11
	ds_read2_b32 v[10:11], v7 offset0:90 offset1:123
	v_lshlrev_b64 v[22:23], 11, v[22:23]
	s_waitcnt lgkmcnt(0)
	v_cvt_pk_bf16_f32 v19, v10, v11
	ds_read2_b32 v[10:11], v7 offset0:156 offset1:189
	v_lshl_add_u64 v[22:23], v[24:25], 0, v[22:23]
	s_waitcnt lgkmcnt(0)
	v_cvt_pk_bf16_f32 v20, v10, v11
	ds_read2_b32 v[10:11], v7 offset0:222 offset1:255
	s_waitcnt lgkmcnt(0)
	v_cvt_pk_bf16_f32 v21, v10, v11
	global_store_dwordx4 v[22:23], v[18:21], off
	s_waitcnt lgkmcnt(0)
	s_add_i32 s12, s12, s3
	s_cmpk_lt_i32 s12, 0x200
	s_cbranch_scc1 .LBB0_89

; __device__ __forceinline__ void p0_transpose_item(const float* W, int N, bf16_t* WT, int ldt, int k0, int n0, int nrow0, int kcol0, LAS float* scr, int lane) {
; #pragma unroll 8
;     for (int i = 0; i < 32; ++i) { const int kk = 2 * i + (lane >> 5); scr[kk * 33 + (lane & 31)] = W[(size_t)(k0 + kk) * N + n0 + (lane & 31)]; }
.LBB0_100:
	s_lshl_b32 s16, s15, 1
	s_lshl_b32 s17, s14, 1
	v_or_b32_e32 v50, s16, v1
	v_or_b32_e32 v51, s17, v2
	s_add_i32 s18, s16, 4
	s_add_i32 s19, s17, 4
	s_add_i32 s20, s16, 8
	s_add_i32 s21, s17, 8
	s_add_i32 s22, s16, 12
	s_add_i32 s23, s17, 12
	s_add_i32 s24, s16, 16
	s_add_i32 s25, s17, 16
	s_add_i32 s26, s16, 20
	s_add_i32 s27, s17, 20
	s_add_i32 s28, s16, 24
	s_add_i32 s29, s17, 24
	s_add_i32 s16, s16, 28
	s_add_i32 s17, s17, 28
	v_add_u32_e32 v20, s8, v51
	v_or_b32_e32 v52, s18, v1
	v_or_b32_e32 v53, s19, v2
	v_or_b32_e32 v54, s20, v1
	v_or_b32_e32 v55, s21, v2
	v_or_b32_e32 v56, s22, v1
	v_or_b32_e32 v57, s23, v2
	v_or_b32_e32 v58, s24, v1
	v_or_b32_e32 v59, s25, v2
	v_or_b32_e32 v60, s26, v1
	v_or_b32_e32 v61, s27, v2
	v_or_b32_e32 v62, s28, v1
	v_or_b32_e32 v63, s29, v2
	v_or_b32_e32 v64, s16, v1
	v_or_b32_e32 v65, s17, v2
	v_add_u32_e32 v18, s7, v50
	v_ashrrev_i32_e32 v21, 31, v20
	v_add_u32_e32 v22, s7, v52
	v_add_u32_e32 v24, s8, v53
	v_add_u32_e32 v26, s7, v54
	v_add_u32_e32 v28, s8, v55
	v_add_u32_e32 v30, s7, v56
	v_add_u32_e32 v32, s8, v57
	v_add_u32_e32 v34, s7, v58
	v_add_u32_e32 v36, s8, v59
	v_add_u32_e32 v38, s7, v60
	v_add_u32_e32 v40, s8, v61
	v_add_u32_e32 v42, s7, v62
	v_add_u32_e32 v44, s8, v63
	v_add_u32_e32 v46, s7, v64
	v_add_u32_e32 v48, s8, v65
	v_ashrrev_i32_e32 v19, 31, v18
	v_lshlrev_b64 v[20:21], 14, v[20:21]
	v_ashrrev_i32_e32 v25, 31, v24
	v_ashrrev_i32_e32 v23, 31, v22
	v_ashrrev_i32_e32 v29, 31, v28
	v_ashrrev_i32_e32 v27, 31, v26
	v_ashrrev_i32_e32 v33, 31, v32
	v_ashrrev_i32_e32 v31, 31, v30
	v_ashrrev_i32_e32 v37, 31, v36
	v_ashrrev_i32_e32 v35, 31, v34
	v_ashrrev_i32_e32 v41, 31, v40
	v_ashrrev_i32_e32 v39, 31, v38
	v_ashrrev_i32_e32 v45, 31, v44
	v_ashrrev_i32_e32 v43, 31, v42
	v_ashrrev_i32_e32 v49, 31, v48
	v_ashrrev_i32_e32 v47, 31, v46
	v_lshlrev_b64 v[18:19], 14, v[18:19]
	v_lshl_add_u64 v[20:21], v[10:11], 0, v[20:21]
	v_lshlrev_b64 v[22:23], 14, v[22:23]
	v_lshlrev_b64 v[24:25], 14, v[24:25]
	v_lshlrev_b64 v[26:27], 14, v[26:27]
	v_lshlrev_b64 v[28:29], 14, v[28:29]
	v_lshlrev_b64 v[30:31], 14, v[30:31]
	v_lshlrev_b64 v[32:33], 14, v[32:33]
	v_lshlrev_b64 v[34:35], 14, v[34:35]
	v_lshlrev_b64 v[36:37], 14, v[36:37]
	v_lshlrev_b64 v[38:39], 14, v[38:39]
	v_lshlrev_b64 v[40:41], 14, v[40:41]
	v_lshlrev_b64 v[42:43], 14, v[42:43]
	v_lshlrev_b64 v[44:45], 14, v[44:45]
	v_lshlrev_b64 v[46:47], 14, v[46:47]
	v_lshlrev_b64 v[48:49], 14, v[48:49]
	v_lshl_add_u64 v[18:19], v[10:11], 0, v[18:19]
	v_lshl_add_u64 v[24:25], v[10:11], 0, v[24:25]
	v_lshl_add_u64 v[22:23], v[10:11], 0, v[22:23]
	v_lshl_add_u64 v[28:29], v[10:11], 0, v[28:29]
	v_lshl_add_u64 v[26:27], v[10:11], 0, v[26:27]
	v_lshl_add_u64 v[32:33], v[10:11], 0, v[32:33]
	v_lshl_add_u64 v[30:31], v[10:11], 0, v[30:31]
	v_lshl_add_u64 v[36:37], v[10:11], 0, v[36:37]
	v_lshl_add_u64 v[34:35], v[10:11], 0, v[34:35]
	v_lshl_add_u64 v[40:41], v[10:11], 0, v[40:41]
	v_lshl_add_u64 v[38:39], v[10:11], 0, v[38:39]
	v_lshl_add_u64 v[44:45], v[10:11], 0, v[44:45]
	v_lshl_add_u64 v[42:43], v[10:11], 0, v[42:43]
	v_lshl_add_u64 v[48:49], v[10:11], 0, v[48:49]
	v_lshl_add_u64 v[46:47], v[10:11], 0, v[46:47]
	global_load_dword v66, v[20:21], off
	global_load_dword v67, v[18:19], off
	global_load_dword v68, v[24:25], off
	global_load_dword v69, v[22:23], off
	global_load_dword v70, v[28:29], off
	global_load_dword v71, v[26:27], off
	global_load_dword v72, v[32:33], off
	global_load_dword v73, v[30:31], off
	global_load_dword v74, v[36:37], off
	global_load_dword v75, v[34:35], off
	global_load_dword v76, v[40:41], off
	global_load_dword v77, v[38:39], off
	global_load_dword v78, v[44:45], off
	global_load_dword v79, v[42:43], off
	global_load_dword v80, v[48:49], off
	global_load_dword v81, v[46:47], off
	s_add_i32 s14, s14, 16
	s_add_i32 s15, s15, 16
	s_add_i32 s9, s9, -16
	v_mad_u64_u32 v[18:19], s[16:17], v51, s13, v[6:7]
	s_cmp_lg_u32 s9, 0
	v_mad_u64_u32 v[20:21], s[16:17], v50, s13, v[6:7]
	v_mad_u64_u32 v[22:23], s[16:17], v53, s13, v[6:7]
	v_mad_u64_u32 v[24:25], s[16:17], v52, s13, v[6:7]
	v_mad_u64_u32 v[26:27], s[16:17], v55, s13, v[6:7]
	v_mad_u64_u32 v[28:29], s[16:17], v54, s13, v[6:7]
	v_mad_u64_u32 v[30:31], s[16:17], v57, s13, v[6:7]
	v_mad_u64_u32 v[32:33], s[16:17], v56, s13, v[6:7]
	v_mad_u64_u32 v[34:35], s[16:17], v59, s13, v[6:7]
	v_mad_u64_u32 v[36:37], s[16:17], v58, s13, v[6:7]
	v_mad_u64_u32 v[38:39], s[16:17], v61, s13, v[6:7]
	v_mad_u64_u32 v[40:41], s[16:17], v60, s13, v[6:7]
	v_mad_u64_u32 v[42:43], s[16:17], v63, s13, v[6:7]
	v_mad_u64_u32 v[44:45], s[16:17], v62, s13, v[6:7]
	v_mad_u64_u32 v[46:47], s[16:17], v65, s13, v[6:7]
	v_mad_u64_u32 v[48:49], s[16:17], v64, s13, v[6:7]
	s_nop 7
	s_lshl_b32 s16, s15, 1
	s_lshl_b32 s17, s14, 1
	v_or_b32_e32 v172, s16, v1
	v_or_b32_e32 v173, s17, v2
	s_add_i32 s18, s16, 4
	s_add_i32 s19, s17, 4
	s_add_i32 s20, s16, 8
	s_add_i32 s21, s17, 8
	s_add_i32 s22, s16, 12
	s_add_i32 s23, s17, 12
	s_add_i32 s24, s16, 16
	s_add_i32 s25, s17, 16
	s_add_i32 s26, s16, 20
	s_add_i32 s27, s17, 20
	s_add_i32 s28, s16, 24
	s_add_i32 s29, s17, 24
	s_add_i32 s16, s16, 28
	s_add_i32 s17, s17, 28
	v_add_u32_e32 v142, s8, v173
	v_or_b32_e32 v174, s18, v1
	v_or_b32_e32 v175, s19, v2
	v_or_b32_e32 v176, s20, v1
	v_or_b32_e32 v177, s21, v2
	v_or_b32_e32 v178, s22, v1
	v_or_b32_e32 v179, s23, v2
	v_or_b32_e32 v180, s24, v1
	v_or_b32_e32 v181, s25, v2
	v_or_b32_e32 v182, s26, v1
	v_or_b32_e32 v183, s27, v2
	v_or_b32_e32 v184, s28, v1
	v_or_b32_e32 v185, s29, v2
	v_or_b32_e32 v186, s16, v1
	v_or_b32_e32 v187, s17, v2
	v_add_u32_e32 v140, s7, v172
	v_ashrrev_i32_e32 v143, 31, v142
	v_add_u32_e32 v144, s7, v174
; __device__ __forceinline__ void p0_transpose_item(const float* W, int N, bf16_t* WT, int ldt, int k0, int n0, int nrow0, int kcol0, LAS float* scr, int lane) {
;     ...
;     for (int i = 0; i < 32; ++i) { const int kk = 2 * i + (lane >> 5); scr[kk * 33 + (lane & 31)] = W[(size_t)(k0 + kk) * N + n0 + (lane & 31)]; }
	v_add_u32_e32 v146, s8, v175
	v_add_u32_e32 v148, s7, v176
	v_add_u32_e32 v150, s8, v177
	v_add_u32_e32 v152, s7, v178
	v_add_u32_e32 v154, s8, v179
	v_add_u32_e32 v156, s7, v180
	v_add_u32_e32 v158, s8, v181
	v_add_u32_e32 v160, s7, v182
	v_add_u32_e32 v162, s8, v183
	v_add_u32_e32 v164, s7, v184
	v_add_u32_e32 v166, s8, v185
	v_add_u32_e32 v168, s7, v186
	v_add_u32_e32 v170, s8, v187
	v_ashrrev_i32_e32 v141, 31, v140
	v_lshlrev_b64 v[142:143], 14, v[142:143]
	v_ashrrev_i32_e32 v147, 31, v146
	v_ashrrev_i32_e32 v145, 31, v144
	v_ashrrev_i32_e32 v151, 31, v150
	v_ashrrev_i32_e32 v149, 31, v148
	v_ashrrev_i32_e32 v155, 31, v154
	v_ashrrev_i32_e32 v153, 31, v152
	v_ashrrev_i32_e32 v159, 31, v158
	v_ashrrev_i32_e32 v157, 31, v156
	v_ashrrev_i32_e32 v163, 31, v162
	v_ashrrev_i32_e32 v161, 31, v160
	v_ashrrev_i32_e32 v167, 31, v166
	v_ashrrev_i32_e32 v165, 31, v164
	v_ashrrev_i32_e32 v171, 31, v170
	v_ashrrev_i32_e32 v169, 31, v168
	v_lshlrev_b64 v[140:141], 14, v[140:141]
	v_lshl_add_u64 v[142:143], v[10:11], 0, v[142:143]
	v_lshlrev_b64 v[144:145], 14, v[144:145]
	v_lshlrev_b64 v[146:147], 14, v[146:147]
	v_lshlrev_b64 v[148:149], 14, v[148:149]
	v_lshlrev_b64 v[150:151], 14, v[150:151]
	v_lshlrev_b64 v[152:153], 14, v[152:153]
	v_lshlrev_b64 v[154:155], 14, v[154:155]
	v_lshlrev_b64 v[156:157], 14, v[156:157]
	v_lshlrev_b64 v[158:159], 14, v[158:159]
	v_lshlrev_b64 v[160:161], 14, v[160:161]
	v_lshlrev_b64 v[162:163], 14, v[162:163]
	v_lshlrev_b64 v[164:165], 14, v[164:165]
	v_lshlrev_b64 v[166:167], 14, v[166:167]
	v_lshlrev_b64 v[168:169], 14, v[168:169]
	v_lshlrev_b64 v[170:171], 14, v[170:171]
	v_lshl_add_u64 v[140:141], v[10:11], 0, v[140:141]
	v_lshl_add_u64 v[146:147], v[10:11], 0, v[146:147]
	v_lshl_add_u64 v[144:145], v[10:11], 0, v[144:145]
	v_lshl_add_u64 v[150:151], v[10:11], 0, v[150:151]
	v_lshl_add_u64 v[148:149], v[10:11], 0, v[148:149]
	v_lshl_add_u64 v[154:155], v[10:11], 0, v[154:155]
	v_lshl_add_u64 v[152:153], v[10:11], 0, v[152:153]
	v_lshl_add_u64 v[158:159], v[10:11], 0, v[158:159]
	v_lshl_add_u64 v[156:157], v[10:11], 0, v[156:157]
	v_lshl_add_u64 v[162:163], v[10:11], 0, v[162:163]
	v_lshl_add_u64 v[160:161], v[10:11], 0, v[160:161]
	v_lshl_add_u64 v[166:167], v[10:11], 0, v[166:167]
	v_lshl_add_u64 v[164:165], v[10:11], 0, v[164:165]
	v_lshl_add_u64 v[170:171], v[10:11], 0, v[170:171]
	v_lshl_add_u64 v[168:169], v[10:11], 0, v[168:169]
	global_load_dword v188, v[142:143], off
	global_load_dword v189, v[140:141], off
	global_load_dword v190, v[146:147], off
	global_load_dword v191, v[144:145], off
	global_load_dword v192, v[150:151], off
	global_load_dword v193, v[148:149], off
	global_load_dword v194, v[154:155], off
	global_load_dword v195, v[152:153], off
	global_load_dword v196, v[158:159], off
	global_load_dword v197, v[156:157], off
	global_load_dword v198, v[162:163], off
	global_load_dword v199, v[160:161], off
	global_load_dword v200, v[166:167], off
	global_load_dword v201, v[164:165], off
	global_load_dword v202, v[170:171], off
	global_load_dword v203, v[168:169], off
	s_add_i32 s14, s14, 16
	s_add_i32 s15, s15, 16
	s_add_i32 s9, s9, -16
	v_mad_u64_u32 v[140:141], s[16:17], v173, s13, v[6:7]
	s_cmp_lg_u32 s9, 0
	v_mad_u64_u32 v[142:143], s[16:17], v172, s13, v[6:7]
	v_mad_u64_u32 v[144:145], s[16:17], v175, s13, v[6:7]
	v_mad_u64_u32 v[146:147], s[16:17], v174, s13, v[6:7]
	v_mad_u64_u32 v[148:149], s[16:17], v177, s13, v[6:7]
	v_mad_u64_u32 v[150:151], s[16:17], v176, s13, v[6:7]
	v_mad_u64_u32 v[152:153], s[16:17], v179, s13, v[6:7]
	v_mad_u64_u32 v[154:155], s[16:17], v178, s13, v[6:7]
	v_mad_u64_u32 v[156:157], s[16:17], v181, s13, v[6:7]
	v_mad_u64_u32 v[158:159], s[16:17], v180, s13, v[6:7]
	v_mad_u64_u32 v[160:161], s[16:17], v183, s13, v[6:7]
	v_mad_u64_u32 v[162:163], s[16:17], v182, s13, v[6:7]
	v_mad_u64_u32 v[164:165], s[16:17], v185, s13, v[6:7]
	v_mad_u64_u32 v[166:167], s[16:17], v184, s13, v[6:7]
	v_mad_u64_u32 v[168:169], s[16:17], v187, s13, v[6:7]
	v_mad_u64_u32 v[170:171], s[16:17], v186, s13, v[6:7]
	s_waitcnt vmcnt(31)
; #define LAS __attribute__((address_space(3)))
; __device__ __forceinline__ unsigned cvt_pk_bf16(float lo, float hi) { unsigned r; asm volatile("v_cvt_pk_bf16_f32 %0, %1, %2" : "=v"(r) : "v"(lo), "v"(hi)); return r; }
; #define LDS_WAIT() asm volatile("s_waitcnt lgkmcnt(0)" ::: "memory")
; __device__ __forceinline__ void p0_transpose_item(const float* W, int N, bf16_t* WT, int ldt, int k0, int n0, int nrow0, int kcol0, LAS float* scr, int lane) {
;     ...
;     for (int i = 0; i < 32; ++i) { const int kk = 2 * i + (lane >> 5); scr[kk * 33 + (lane & 31)] = W[(size_t)(k0 + kk) * N + n0 + (lane & 31)]; }
;     LDS_WAIT(); asm volatile("" ::: "memory");
;     const int c = lane & 7;
; #pragma unroll
;     for (int j = 0; j < 4; ++j) { const int n = (lane >> 3) + 8 * j; const LAS float* s = scr + (8 * c) * 33 + n;
;         u32x4 o; o.x = cvt_pk_bf16(s[0 * 33], s[1 * 33]); o.y = cvt_pk_bf16(s[2 * 33], s[3 * 33]); o.z = cvt_pk_bf16(s[4 * 33], s[5 * 33]); o.w = cvt_pk_bf16(s[6 * 33], s[7 * 33]);
;         *(u32x4*)(WT + (size_t)(nrow0 + n) * ldt + kcol0 + k0 + 8 * c) = o; }
;     LDS_WAIT(); asm volatile("" ::: "memory");
; __device__ __forceinline__ void p0_prologue(const Frame& F) {
;     ...
;                 for (int it = first; it < nitems; it += NGW) { const int kb = it / nblk, nbk = it % nblk, n0 = nbk * 32;
;                     const int nrow0 = (jb == 0 && n0 >= 3392) ? n0 + 192 : n0;
;                     p0_transpose_item(W, J.N, WT, J.ldt, kb * 64, n0, nrow0, J.kcol0, scr, F.lane); }
	ds_write_b32 v18, v66
	s_waitcnt vmcnt(30)
	ds_write_b32 v20, v67
	s_waitcnt vmcnt(29)
	ds_write_b32 v22, v68
	s_waitcnt vmcnt(28)
	ds_write_b32 v24, v69
	s_waitcnt vmcnt(27)
	ds_write_b32 v26, v70
	s_waitcnt vmcnt(26)
	ds_write_b32 v28, v71
	s_waitcnt vmcnt(25)
	ds_write_b32 v30, v72
	s_waitcnt vmcnt(24)
	ds_write_b32 v32, v73
	s_waitcnt vmcnt(23)
	ds_write_b32 v34, v74
	s_waitcnt vmcnt(22)
	ds_write_b32 v36, v75
	s_waitcnt vmcnt(21)
	ds_write_b32 v38, v76
	s_waitcnt vmcnt(20)
	ds_write_b32 v40, v77
	s_waitcnt vmcnt(19)
	ds_write_b32 v42, v78
	s_waitcnt vmcnt(18)
	ds_write_b32 v44, v79
	s_waitcnt vmcnt(17)
	ds_write_b32 v46, v80
	s_waitcnt vmcnt(16)
	ds_write_b32 v48, v81
	s_waitcnt vmcnt(15)
	ds_write_b32 v140, v188
	s_waitcnt vmcnt(14)
	ds_write_b32 v142, v189
	s_waitcnt vmcnt(13)
	ds_write_b32 v144, v190
	s_waitcnt vmcnt(12)
	ds_write_b32 v146, v191
	s_waitcnt vmcnt(11)
	ds_write_b32 v148, v192
	s_waitcnt vmcnt(10)
	ds_write_b32 v150, v193
	s_waitcnt vmcnt(9)
	ds_write_b32 v152, v194
	s_waitcnt vmcnt(8)
	ds_write_b32 v154, v195
	s_waitcnt vmcnt(7)
	ds_write_b32 v156, v196
	s_waitcnt vmcnt(6)
	ds_write_b32 v158, v197
	s_waitcnt vmcnt(5)
	ds_write_b32 v160, v198
	s_waitcnt vmcnt(4)
	ds_write_b32 v162, v199
	s_waitcnt vmcnt(3)
	ds_write_b32 v164, v200
	s_waitcnt vmcnt(2)
	ds_write_b32 v166, v201
	s_waitcnt vmcnt(1)
	ds_write_b32 v168, v202
	s_waitcnt vmcnt(0)
	ds_write_b32 v170, v203
	s_waitcnt lgkmcnt(0)
	v_or_b32_e32 v22, s6, v3
	ds_read2_b32 v[10:11], v7 offset1:33
	s_ashr_i32 s9, s8, 31
	v_ashrrev_i32_e32 v23, 31, v22
	s_waitcnt lgkmcnt(0)
	v_cvt_pk_bf16_f32 v18, v10, v11
	ds_read2_b32 v[10:11], v7 offset0:66 offset1:99
	v_lshl_add_u64 v[24:25], s[8:9], 1, v[8:9]
	v_lshlrev_b64 v[22:23], 13, v[22:23]
	s_waitcnt lgkmcnt(0)
	v_cvt_pk_bf16_f32 v19, v10, v11
	ds_read2_b32 v[10:11], v7 offset0:132 offset1:165
	v_lshl_add_u64 v[22:23], v[24:25], 0, v[22:23]
	s_waitcnt lgkmcnt(0)
	v_cvt_pk_bf16_f32 v20, v10, v11
	ds_read2_b32 v[10:11], v7 offset0:198 offset1:231
	s_waitcnt lgkmcnt(0)
	v_cvt_pk_bf16_f32 v21, v10, v11
	global_store_dwordx4 v[22:23], v[18:21], off
	v_or_b32_e32 v22, s6, v13
	ds_read2_b32 v[10:11], v7 offset0:8 offset1:41
	v_ashrrev_i32_e32 v23, 31, v22
	s_waitcnt lgkmcnt(0)
	v_cvt_pk_bf16_f32 v18, v10, v11
	ds_read2_b32 v[10:11], v7 offset0:74 offset1:107
	v_lshlrev_b64 v[22:23], 13, v[22:23]
	s_waitcnt lgkmcnt(0)
	v_cvt_pk_bf16_f32 v19, v10, v11
	ds_read2_b32 v[10:11], v7 offset0:140 offset1:173
	v_lshl_add_u64 v[22:23], v[24:25], 0, v[22:23]
	s_waitcnt lgkmcnt(0)
	v_cvt_pk_bf16_f32 v20, v10, v11
	ds_read2_b32 v[10:11], v7 offset0:206 offset1:239
	s_waitcnt lgkmcnt(0)
	v_cvt_pk_bf16_f32 v21, v10, v11
	global_store_dwordx4 v[22:23], v[18:21], off
	v_or_b32_e32 v22, s6, v16
	ds_read2_b32 v[10:11], v7 offset0:16 offset1:49
	v_ashrrev_i32_e32 v23, 31, v22
	s_waitcnt lgkmcnt(0)
	v_cvt_pk_bf16_f32 v18, v10, v11
	ds_read2_b32 v[10:11], v7 offset0:82 offset1:115
	v_lshlrev_b64 v[22:23], 13, v[22:23]
	s_waitcnt lgkmcnt(0)
	v_cvt_pk_bf16_f32 v19, v10, v11
	ds_read2_b32 v[10:11], v7 offset0:148 offset1:181
	v_lshl_add_u64 v[22:23], v[24:25], 0, v[22:23]
	s_waitcnt lgkmcnt(0)
	v_cvt_pk_bf16_f32 v20, v10, v11
	ds_read2_b32 v[10:11], v7 offset0:214 offset1:247
	s_waitcnt lgkmcnt(0)
	v_cvt_pk_bf16_f32 v21, v10, v11
	global_store_dwordx4 v[22:23], v[18:21], off
	v_or_b32_e32 v22, s6, v17
	ds_read2_b32 v[10:11], v7 offset0:24 offset1:57
	v_ashrrev_i32_e32 v23, 31, v22
	s_waitcnt lgkmcnt(0)
	v_cvt_pk_bf16_f32 v18, v10, v11
	ds_read2_b32 v[10:11], v7 offset0:90 offset1:123
	v_lshlrev_b64 v[22:23], 13, v[22:23]
	s_waitcnt lgkmcnt(0)
	v_cvt_pk_bf16_f32 v19, v10, v11
	ds_read2_b32 v[10:11], v7 offset0:156 offset1:189
	v_lshl_add_u64 v[22:23], v[24:25], 0, v[22:23]
	s_waitcnt lgkmcnt(0)
	v_cvt_pk_bf16_f32 v20, v10, v11
	ds_read2_b32 v[10:11], v7 offset0:222 offset1:255
	s_waitcnt lgkmcnt(0)
	v_cvt_pk_bf16_f32 v21, v10, v11
	global_store_dwordx4 v[22:23], v[18:21], off
	s_waitcnt lgkmcnt(0)
	s_add_i32 s12, s12, s3
	s_cmpk_lt_i32 s12, 0x800
	s_cbranch_scc1 .LBB0_99

; __device__ __forceinline__ void p0_transpose_item(const float* W, int N, bf16_t* WT, int ldt, int k0, int n0, int nrow0, int kcol0, LAS float* scr, int lane) {
; #pragma unroll 8
;     for (int i = 0; i < 32; ++i) { const int kk = 2 * i + (lane >> 5); scr[kk * 33 + (lane & 31)] = W[(size_t)(k0 + kk) * N + n0 + (lane & 31)]; }
.LBB0_105:
	s_lshl_b32 s16, s15, 1
	s_lshl_b32 s17, s14, 1
	v_or_b32_e32 v50, s16, v1
	v_or_b32_e32 v51, s17, v2
	s_add_i32 s18, s16, 4
	s_add_i32 s19, s17, 4
	s_add_i32 s20, s16, 8
	s_add_i32 s21, s17, 8
	s_add_i32 s22, s16, 12
	s_add_i32 s23, s17, 12
	s_add_i32 s24, s16, 16
	s_add_i32 s25, s17, 16
	s_add_i32 s26, s16, 20
	s_add_i32 s27, s17, 20
	s_add_i32 s28, s16, 24
	s_add_i32 s29, s17, 24
	s_add_i32 s16, s16, 28
	s_add_i32 s17, s17, 28
	v_add_u32_e32 v20, s8, v51
	v_or_b32_e32 v52, s18, v1
	v_or_b32_e32 v53, s19, v2
	v_or_b32_e32 v54, s20, v1
	v_or_b32_e32 v55, s21, v2
	v_or_b32_e32 v56, s22, v1
	v_or_b32_e32 v57, s23, v2
	v_or_b32_e32 v58, s24, v1
	v_or_b32_e32 v59, s25, v2
	v_or_b32_e32 v60, s26, v1
	v_or_b32_e32 v61, s27, v2
	v_or_b32_e32 v62, s28, v1
	v_or_b32_e32 v63, s29, v2
	v_or_b32_e32 v64, s16, v1
	v_or_b32_e32 v65, s17, v2
	v_add_u32_e32 v18, s7, v50
	v_ashrrev_i32_e32 v21, 31, v20
	v_add_u32_e32 v22, s7, v52
	v_add_u32_e32 v24, s8, v53
	v_add_u32_e32 v26, s7, v54
	v_add_u32_e32 v28, s8, v55
	v_add_u32_e32 v30, s7, v56
	v_add_u32_e32 v32, s8, v57
	v_add_u32_e32 v34, s7, v58
	v_add_u32_e32 v36, s8, v59
	v_add_u32_e32 v38, s7, v60
	v_add_u32_e32 v40, s8, v61
	v_add_u32_e32 v42, s7, v62
	v_add_u32_e32 v44, s8, v63
	v_add_u32_e32 v46, s7, v64
	v_add_u32_e32 v48, s8, v65
	v_ashrrev_i32_e32 v19, 31, v18
	v_lshlrev_b64 v[20:21], 14, v[20:21]
	v_ashrrev_i32_e32 v25, 31, v24
	v_ashrrev_i32_e32 v23, 31, v22
	v_ashrrev_i32_e32 v29, 31, v28
	v_ashrrev_i32_e32 v27, 31, v26
	v_ashrrev_i32_e32 v33, 31, v32
	v_ashrrev_i32_e32 v31, 31, v30
	v_ashrrev_i32_e32 v37, 31, v36
	v_ashrrev_i32_e32 v35, 31, v34
	v_ashrrev_i32_e32 v41, 31, v40
	v_ashrrev_i32_e32 v39, 31, v38
	v_ashrrev_i32_e32 v45, 31, v44
	v_ashrrev_i32_e32 v43, 31, v42
	v_ashrrev_i32_e32 v49, 31, v48
	v_ashrrev_i32_e32 v47, 31, v46
	v_lshlrev_b64 v[18:19], 14, v[18:19]
	v_lshl_add_u64 v[20:21], v[10:11], 0, v[20:21]
	v_lshlrev_b64 v[22:23], 14, v[22:23]
	v_lshlrev_b64 v[24:25], 14, v[24:25]
	v_lshlrev_b64 v[26:27], 14, v[26:27]
	v_lshlrev_b64 v[28:29], 14, v[28:29]
	v_lshlrev_b64 v[30:31], 14, v[30:31]
	v_lshlrev_b64 v[32:33], 14, v[32:33]
	v_lshlrev_b64 v[34:35], 14, v[34:35]
	v_lshlrev_b64 v[36:37], 14, v[36:37]
	v_lshlrev_b64 v[38:39], 14, v[38:39]
	v_lshlrev_b64 v[40:41], 14, v[40:41]
	v_lshlrev_b64 v[42:43], 14, v[42:43]
	v_lshlrev_b64 v[44:45], 14, v[44:45]
	v_lshlrev_b64 v[46:47], 14, v[46:47]
	v_lshlrev_b64 v[48:49], 14, v[48:49]
	v_lshl_add_u64 v[18:19], v[10:11], 0, v[18:19]
	v_lshl_add_u64 v[24:25], v[10:11], 0, v[24:25]
	v_lshl_add_u64 v[22:23], v[10:11], 0, v[22:23]
	v_lshl_add_u64 v[28:29], v[10:11], 0, v[28:29]
	v_lshl_add_u64 v[26:27], v[10:11], 0, v[26:27]
	v_lshl_add_u64 v[32:33], v[10:11], 0, v[32:33]
	v_lshl_add_u64 v[30:31], v[10:11], 0, v[30:31]
	v_lshl_add_u64 v[36:37], v[10:11], 0, v[36:37]
	v_lshl_add_u64 v[34:35], v[10:11], 0, v[34:35]
	v_lshl_add_u64 v[40:41], v[10:11], 0, v[40:41]
	v_lshl_add_u64 v[38:39], v[10:11], 0, v[38:39]
	v_lshl_add_u64 v[44:45], v[10:11], 0, v[44:45]
	v_lshl_add_u64 v[42:43], v[10:11], 0, v[42:43]
	v_lshl_add_u64 v[48:49], v[10:11], 0, v[48:49]
	v_lshl_add_u64 v[46:47], v[10:11], 0, v[46:47]
	global_load_dword v66, v[20:21], off
	global_load_dword v67, v[18:19], off
	global_load_dword v68, v[24:25], off
	global_load_dword v69, v[22:23], off
	global_load_dword v70, v[28:29], off
	global_load_dword v71, v[26:27], off
	global_load_dword v72, v[32:33], off
	global_load_dword v73, v[30:31], off
	global_load_dword v74, v[36:37], off
	global_load_dword v75, v[34:35], off
	global_load_dword v76, v[40:41], off
	global_load_dword v77, v[38:39], off
	global_load_dword v78, v[44:45], off
	global_load_dword v79, v[42:43], off
	global_load_dword v80, v[48:49], off
	global_load_dword v81, v[46:47], off
	s_add_i32 s14, s14, 16
	s_add_i32 s15, s15, 16
	s_add_i32 s9, s9, -16
	v_mad_u64_u32 v[18:19], s[16:17], v51, s13, v[6:7]
	s_cmp_lg_u32 s9, 0
	v_mad_u64_u32 v[20:21], s[16:17], v50, s13, v[6:7]
	v_mad_u64_u32 v[22:23], s[16:17], v53, s13, v[6:7]
	v_mad_u64_u32 v[24:25], s[16:17], v52, s13, v[6:7]
	v_mad_u64_u32 v[26:27], s[16:17], v55, s13, v[6:7]
	v_mad_u64_u32 v[28:29], s[16:17], v54, s13, v[6:7]
	v_mad_u64_u32 v[30:31], s[16:17], v57, s13, v[6:7]
	v_mad_u64_u32 v[32:33], s[16:17], v56, s13, v[6:7]
	v_mad_u64_u32 v[34:35], s[16:17], v59, s13, v[6:7]
	v_mad_u64_u32 v[36:37], s[16:17], v58, s13, v[6:7]
	v_mad_u64_u32 v[38:39], s[16:17], v61, s13, v[6:7]
	v_mad_u64_u32 v[40:41], s[16:17], v60, s13, v[6:7]
	v_mad_u64_u32 v[42:43], s[16:17], v63, s13, v[6:7]
	v_mad_u64_u32 v[44:45], s[16:17], v62, s13, v[6:7]
	v_mad_u64_u32 v[46:47], s[16:17], v65, s13, v[6:7]
	v_mad_u64_u32 v[48:49], s[16:17], v64, s13, v[6:7]
	s_nop 7
	s_lshl_b32 s16, s15, 1
	s_lshl_b32 s17, s14, 1
	v_or_b32_e32 v172, s16, v1
	v_or_b32_e32 v173, s17, v2
	s_add_i32 s18, s16, 4
	s_add_i32 s19, s17, 4
	s_add_i32 s20, s16, 8
	s_add_i32 s21, s17, 8
	s_add_i32 s22, s16, 12
	s_add_i32 s23, s17, 12
	s_add_i32 s24, s16, 16
	s_add_i32 s25, s17, 16
	s_add_i32 s26, s16, 20
	s_add_i32 s27, s17, 20
	s_add_i32 s28, s16, 24
	s_add_i32 s29, s17, 24
	s_add_i32 s16, s16, 28
	s_add_i32 s17, s17, 28
	v_add_u32_e32 v142, s8, v173
	v_or_b32_e32 v174, s18, v1
	v_or_b32_e32 v175, s19, v2
	v_or_b32_e32 v176, s20, v1
	v_or_b32_e32 v177, s21, v2
	v_or_b32_e32 v178, s22, v1
	v_or_b32_e32 v179, s23, v2
	v_or_b32_e32 v180, s24, v1
	v_or_b32_e32 v181, s25, v2
	v_or_b32_e32 v182, s26, v1
	v_or_b32_e32 v183, s27, v2
	v_or_b32_e32 v184, s28, v1
	v_or_b32_e32 v185, s29, v2
	v_or_b32_e32 v186, s16, v1
	v_or_b32_e32 v187, s17, v2
	v_add_u32_e32 v140, s7, v172
	v_ashrrev_i32_e32 v143, 31, v142
	v_add_u32_e32 v144, s7, v174
; __device__ __forceinline__ void p0_transpose_item(const float* W, int N, bf16_t* WT, int ldt, int k0, int n0, int nrow0, int kcol0, LAS float* scr, int lane) {
;     ...
;     for (int i = 0; i < 32; ++i) { const int kk = 2 * i + (lane >> 5); scr[kk * 33 + (lane & 31)] = W[(size_t)(k0 + kk) * N + n0 + (lane & 31)]; }
	v_add_u32_e32 v146, s8, v175
	v_add_u32_e32 v148, s7, v176
	v_add_u32_e32 v150, s8, v177
	v_add_u32_e32 v152, s7, v178
	v_add_u32_e32 v154, s8, v179
	v_add_u32_e32 v156, s7, v180
	v_add_u32_e32 v158, s8, v181
	v_add_u32_e32 v160, s7, v182
	v_add_u32_e32 v162, s8, v183
	v_add_u32_e32 v164, s7, v184
	v_add_u32_e32 v166, s8, v185
	v_add_u32_e32 v168, s7, v186
	v_add_u32_e32 v170, s8, v187
	v_ashrrev_i32_e32 v141, 31, v140
	v_lshlrev_b64 v[142:143], 14, v[142:143]
	v_ashrrev_i32_e32 v147, 31, v146
	v_ashrrev_i32_e32 v145, 31, v144
	v_ashrrev_i32_e32 v151, 31, v150
	v_ashrrev_i32_e32 v149, 31, v148
	v_ashrrev_i32_e32 v155, 31, v154
	v_ashrrev_i32_e32 v153, 31, v152
	v_ashrrev_i32_e32 v159, 31, v158
	v_ashrrev_i32_e32 v157, 31, v156
	v_ashrrev_i32_e32 v163, 31, v162
	v_ashrrev_i32_e32 v161, 31, v160
	v_ashrrev_i32_e32 v167, 31, v166
	v_ashrrev_i32_e32 v165, 31, v164
	v_ashrrev_i32_e32 v171, 31, v170
	v_ashrrev_i32_e32 v169, 31, v168
	v_lshlrev_b64 v[140:141], 14, v[140:141]
	v_lshl_add_u64 v[142:143], v[10:11], 0, v[142:143]
	v_lshlrev_b64 v[144:145], 14, v[144:145]
	v_lshlrev_b64 v[146:147], 14, v[146:147]
	v_lshlrev_b64 v[148:149], 14, v[148:149]
	v_lshlrev_b64 v[150:151], 14, v[150:151]
	v_lshlrev_b64 v[152:153], 14, v[152:153]
	v_lshlrev_b64 v[154:155], 14, v[154:155]
	v_lshlrev_b64 v[156:157], 14, v[156:157]
	v_lshlrev_b64 v[158:159], 14, v[158:159]
	v_lshlrev_b64 v[160:161], 14, v[160:161]
	v_lshlrev_b64 v[162:163], 14, v[162:163]
	v_lshlrev_b64 v[164:165], 14, v[164:165]
	v_lshlrev_b64 v[166:167], 14, v[166:167]
	v_lshlrev_b64 v[168:169], 14, v[168:169]
	v_lshlrev_b64 v[170:171], 14, v[170:171]
	v_lshl_add_u64 v[140:141], v[10:11], 0, v[140:141]
	v_lshl_add_u64 v[146:147], v[10:11], 0, v[146:147]
	v_lshl_add_u64 v[144:145], v[10:11], 0, v[144:145]
	v_lshl_add_u64 v[150:151], v[10:11], 0, v[150:151]
	v_lshl_add_u64 v[148:149], v[10:11], 0, v[148:149]
	v_lshl_add_u64 v[154:155], v[10:11], 0, v[154:155]
	v_lshl_add_u64 v[152:153], v[10:11], 0, v[152:153]
	v_lshl_add_u64 v[158:159], v[10:11], 0, v[158:159]
	v_lshl_add_u64 v[156:157], v[10:11], 0, v[156:157]
	v_lshl_add_u64 v[162:163], v[10:11], 0, v[162:163]
	v_lshl_add_u64 v[160:161], v[10:11], 0, v[160:161]
	v_lshl_add_u64 v[166:167], v[10:11], 0, v[166:167]
	v_lshl_add_u64 v[164:165], v[10:11], 0, v[164:165]
	v_lshl_add_u64 v[170:171], v[10:11], 0, v[170:171]
	v_lshl_add_u64 v[168:169], v[10:11], 0, v[168:169]
	global_load_dword v188, v[142:143], off
	global_load_dword v189, v[140:141], off
	global_load_dword v190, v[146:147], off
	global_load_dword v191, v[144:145], off
	global_load_dword v192, v[150:151], off
	global_load_dword v193, v[148:149], off
	global_load_dword v194, v[154:155], off
	global_load_dword v195, v[152:153], off
	global_load_dword v196, v[158:159], off
	global_load_dword v197, v[156:157], off
	global_load_dword v198, v[162:163], off
	global_load_dword v199, v[160:161], off
	global_load_dword v200, v[166:167], off
	global_load_dword v201, v[164:165], off
	global_load_dword v202, v[170:171], off
	global_load_dword v203, v[168:169], off
	s_add_i32 s14, s14, 16
	s_add_i32 s15, s15, 16
	s_add_i32 s9, s9, -16
	v_mad_u64_u32 v[140:141], s[16:17], v173, s13, v[6:7]
	s_cmp_lg_u32 s9, 0
	v_mad_u64_u32 v[142:143], s[16:17], v172, s13, v[6:7]
	v_mad_u64_u32 v[144:145], s[16:17], v175, s13, v[6:7]
	v_mad_u64_u32 v[146:147], s[16:17], v174, s13, v[6:7]
	v_mad_u64_u32 v[148:149], s[16:17], v177, s13, v[6:7]
	v_mad_u64_u32 v[150:151], s[16:17], v176, s13, v[6:7]
	v_mad_u64_u32 v[152:153], s[16:17], v179, s13, v[6:7]
	v_mad_u64_u32 v[154:155], s[16:17], v178, s13, v[6:7]
	v_mad_u64_u32 v[156:157], s[16:17], v181, s13, v[6:7]
	v_mad_u64_u32 v[158:159], s[16:17], v180, s13, v[6:7]
	v_mad_u64_u32 v[160:161], s[16:17], v183, s13, v[6:7]
	v_mad_u64_u32 v[162:163], s[16:17], v182, s13, v[6:7]
	v_mad_u64_u32 v[164:165], s[16:17], v185, s13, v[6:7]
	v_mad_u64_u32 v[166:167], s[16:17], v184, s13, v[6:7]
	v_mad_u64_u32 v[168:169], s[16:17], v187, s13, v[6:7]
	v_mad_u64_u32 v[170:171], s[16:17], v186, s13, v[6:7]
	s_waitcnt vmcnt(31)
; #define LAS __attribute__((address_space(3)))
; __device__ __forceinline__ unsigned cvt_pk_bf16(float lo, float hi) { unsigned r; asm volatile("v_cvt_pk_bf16_f32 %0, %1, %2" : "=v"(r) : "v"(lo), "v"(hi)); return r; }
; #define LDS_WAIT() asm volatile("s_waitcnt lgkmcnt(0)" ::: "memory")
; __device__ __forceinline__ void p0_transpose_item(const float* W, int N, bf16_t* WT, int ldt, int k0, int n0, int nrow0, int kcol0, LAS float* scr, int lane) {
;     ...
;     for (int i = 0; i < 32; ++i) { const int kk = 2 * i + (lane >> 5); scr[kk * 33 + (lane & 31)] = W[(size_t)(k0 + kk) * N + n0 + (lane & 31)]; }
;     LDS_WAIT(); asm volatile("" ::: "memory");
;     const int c = lane & 7;
; #pragma unroll
;     for (int j = 0; j < 4; ++j) { const int n = (lane >> 3) + 8 * j; const LAS float* s = scr + (8 * c) * 33 + n;
;         u32x4 o; o.x = cvt_pk_bf16(s[0 * 33], s[1 * 33]); o.y = cvt_pk_bf16(s[2 * 33], s[3 * 33]); o.z = cvt_pk_bf16(s[4 * 33], s[5 * 33]); o.w = cvt_pk_bf16(s[6 * 33], s[7 * 33]);
;         *(u32x4*)(WT + (size_t)(nrow0 + n) * ldt + kcol0 + k0 + 8 * c) = o; }
;     LDS_WAIT(); asm volatile("" ::: "memory");
; __device__ __forceinline__ void p0_prologue(const Frame& F) {
;     ...
;                 for (int it = first; it < nitems; it += NGW) { const int kb = it / nblk, nbk = it % nblk, n0 = nbk * 32;
;                     const int nrow0 = (jb == 0 && n0 >= 3392) ? n0 + 192 : n0;
;                     p0_transpose_item(W, J.N, WT, J.ldt, kb * 64, n0, nrow0, J.kcol0, scr, F.lane); }
	ds_write_b32 v18, v66
	s_waitcnt vmcnt(30)
	ds_write_b32 v20, v67
	s_waitcnt vmcnt(29)
	ds_write_b32 v22, v68
	s_waitcnt vmcnt(28)
	ds_write_b32 v24, v69
	s_waitcnt vmcnt(27)
	ds_write_b32 v26, v70
	s_waitcnt vmcnt(26)
	ds_write_b32 v28, v71
	s_waitcnt vmcnt(25)
	ds_write_b32 v30, v72
	s_waitcnt vmcnt(24)
	ds_write_b32 v32, v73
	s_waitcnt vmcnt(23)
	ds_write_b32 v34, v74
	s_waitcnt vmcnt(22)
	ds_write_b32 v36, v75
	s_waitcnt vmcnt(21)
	ds_write_b32 v38, v76
	s_waitcnt vmcnt(20)
	ds_write_b32 v40, v77
	s_waitcnt vmcnt(19)
	ds_write_b32 v42, v78
	s_waitcnt vmcnt(18)
	ds_write_b32 v44, v79
	s_waitcnt vmcnt(17)
	ds_write_b32 v46, v80
	s_waitcnt vmcnt(16)
	ds_write_b32 v48, v81
	s_waitcnt vmcnt(15)
	ds_write_b32 v140, v188
	s_waitcnt vmcnt(14)
	ds_write_b32 v142, v189
	s_waitcnt vmcnt(13)
	ds_write_b32 v144, v190
	s_waitcnt vmcnt(12)
	ds_write_b32 v146, v191
	s_waitcnt vmcnt(11)
	ds_write_b32 v148, v192
	s_waitcnt vmcnt(10)
	ds_write_b32 v150, v193
	s_waitcnt vmcnt(9)
	ds_write_b32 v152, v194
	s_waitcnt vmcnt(8)
	ds_write_b32 v154, v195
	s_waitcnt vmcnt(7)
	ds_write_b32 v156, v196
	s_waitcnt vmcnt(6)
	ds_write_b32 v158, v197
	s_waitcnt vmcnt(5)
	ds_write_b32 v160, v198
	s_waitcnt vmcnt(4)
	ds_write_b32 v162, v199
	s_waitcnt vmcnt(3)
	ds_write_b32 v164, v200
	s_waitcnt vmcnt(2)
	ds_write_b32 v166, v201
	s_waitcnt vmcnt(1)
	ds_write_b32 v168, v202
	s_waitcnt vmcnt(0)
	ds_write_b32 v170, v203
	s_waitcnt lgkmcnt(0)
	v_or_b32_e32 v22, s6, v3
	ds_read2_b32 v[10:11], v7 offset1:33
	s_ashr_i32 s9, s8, 31
	v_ashrrev_i32_e32 v23, 31, v22
	s_waitcnt lgkmcnt(0)
	v_cvt_pk_bf16_f32 v18, v10, v11
	ds_read2_b32 v[10:11], v7 offset0:66 offset1:99
	v_lshl_add_u64 v[24:25], s[8:9], 1, v[8:9]
	v_lshlrev_b64 v[22:23], 13, v[22:23]
	s_waitcnt lgkmcnt(0)
	v_cvt_pk_bf16_f32 v19, v10, v11
	ds_read2_b32 v[10:11], v7 offset0:132 offset1:165
	v_lshl_add_u64 v[22:23], v[24:25], 0, v[22:23]
	s_waitcnt lgkmcnt(0)
	v_cvt_pk_bf16_f32 v20, v10, v11
	ds_read2_b32 v[10:11], v7 offset0:198 offset1:231
	s_waitcnt lgkmcnt(0)
	v_cvt_pk_bf16_f32 v21, v10, v11
	global_store_dwordx4 v[22:23], v[18:21], off
	v_or_b32_e32 v22, s6, v13
	ds_read2_b32 v[10:11], v7 offset0:8 offset1:41
	v_ashrrev_i32_e32 v23, 31, v22
	s_waitcnt lgkmcnt(0)
	v_cvt_pk_bf16_f32 v18, v10, v11
	ds_read2_b32 v[10:11], v7 offset0:74 offset1:107
	v_lshlrev_b64 v[22:23], 13, v[22:23]
	s_waitcnt lgkmcnt(0)
	v_cvt_pk_bf16_f32 v19, v10, v11
	ds_read2_b32 v[10:11], v7 offset0:140 offset1:173
	v_lshl_add_u64 v[22:23], v[24:25], 0, v[22:23]
	s_waitcnt lgkmcnt(0)
	v_cvt_pk_bf16_f32 v20, v10, v11
	ds_read2_b32 v[10:11], v7 offset0:206 offset1:239
	s_waitcnt lgkmcnt(0)
	v_cvt_pk_bf16_f32 v21, v10, v11
	global_store_dwordx4 v[22:23], v[18:21], off
	v_or_b32_e32 v22, s6, v16
	ds_read2_b32 v[10:11], v7 offset0:16 offset1:49
	v_ashrrev_i32_e32 v23, 31, v22
	s_waitcnt lgkmcnt(0)
	v_cvt_pk_bf16_f32 v18, v10, v11
	ds_read2_b32 v[10:11], v7 offset0:82 offset1:115
	v_lshlrev_b64 v[22:23], 13, v[22:23]
	s_waitcnt lgkmcnt(0)
	v_cvt_pk_bf16_f32 v19, v10, v11
	ds_read2_b32 v[10:11], v7 offset0:148 offset1:181
	v_lshl_add_u64 v[22:23], v[24:25], 0, v[22:23]
	s_waitcnt lgkmcnt(0)
	v_cvt_pk_bf16_f32 v20, v10, v11
	ds_read2_b32 v[10:11], v7 offset0:214 offset1:247
	s_waitcnt lgkmcnt(0)
	v_cvt_pk_bf16_f32 v21, v10, v11
	global_store_dwordx4 v[22:23], v[18:21], off
	v_or_b32_e32 v22, s6, v17
	ds_read2_b32 v[10:11], v7 offset0:24 offset1:57
	v_ashrrev_i32_e32 v23, 31, v22
	s_waitcnt lgkmcnt(0)
	v_cvt_pk_bf16_f32 v18, v10, v11
	ds_read2_b32 v[10:11], v7 offset0:90 offset1:123
	v_lshlrev_b64 v[22:23], 13, v[22:23]
	s_waitcnt lgkmcnt(0)
	v_cvt_pk_bf16_f32 v19, v10, v11
	ds_read2_b32 v[10:11], v7 offset0:156 offset1:189
	v_lshl_add_u64 v[22:23], v[24:25], 0, v[22:23]
	s_waitcnt lgkmcnt(0)
	v_cvt_pk_bf16_f32 v20, v10, v11
	ds_read2_b32 v[10:11], v7 offset0:222 offset1:255
	s_waitcnt lgkmcnt(0)
	v_cvt_pk_bf16_f32 v21, v10, v11
	global_store_dwordx4 v[22:23], v[18:21], off
	s_waitcnt lgkmcnt(0)
	s_add_i32 s12, s12, s3
	s_cmpk_lt_i32 s12, 0x1000
	s_cbranch_scc1 .LBB0_104

; __device__ __forceinline__ void p0_transpose_item(const float* W, int N, bf16_t* WT, int ldt, int k0, int n0, int nrow0, int kcol0, LAS float* scr, int lane) {
; #pragma unroll 8
;     for (int i = 0; i < 32; ++i) { const int kk = 2 * i + (lane >> 5); scr[kk * 33 + (lane & 31)] = W[(size_t)(k0 + kk) * N + n0 + (lane & 31)]; }
.LBB0_115:
	s_lshl_b32 s12, s11, 1
	s_lshl_b32 s13, s9, 1
	v_or_b32_e32 v48, s12, v1
	v_or_b32_e32 v49, s13, v2
	s_add_i32 s14, s12, 4
	s_add_i32 s15, s13, 4
	s_add_i32 s16, s12, 8
	s_add_i32 s17, s13, 8
	s_add_i32 s18, s12, 12
	s_add_i32 s19, s13, 12
	s_add_i32 s20, s12, 16
	s_add_i32 s21, s13, 16
	s_add_i32 s22, s12, 20
	s_add_i32 s23, s13, 20
	s_add_i32 s24, s12, 24
	s_add_i32 s25, s13, 24
	s_add_i32 s12, s12, 28
	s_add_i32 s13, s13, 28
	v_add_u32_e32 v18, s8, v49
	v_or_b32_e32 v50, s14, v1
	v_or_b32_e32 v51, s15, v2
	v_or_b32_e32 v52, s16, v1
	v_or_b32_e32 v53, s17, v2
	v_or_b32_e32 v54, s18, v1
	v_or_b32_e32 v55, s19, v2
	v_or_b32_e32 v56, s20, v1
	v_or_b32_e32 v57, s21, v2
	v_or_b32_e32 v58, s22, v1
	v_or_b32_e32 v59, s23, v2
	v_or_b32_e32 v60, s24, v1
	v_or_b32_e32 v61, s25, v2
	v_or_b32_e32 v62, s12, v1
	v_or_b32_e32 v63, s13, v2
	v_add_u32_e32 v16, s4, v48
	v_ashrrev_i32_e32 v19, 31, v18
	v_add_u32_e32 v20, s4, v50
	v_add_u32_e32 v22, s8, v51
	v_add_u32_e32 v24, s4, v52
	v_add_u32_e32 v26, s8, v53
	v_add_u32_e32 v28, s4, v54
	v_add_u32_e32 v30, s8, v55
	v_add_u32_e32 v32, s4, v56
	v_add_u32_e32 v34, s8, v57
	v_add_u32_e32 v36, s4, v58
	v_add_u32_e32 v38, s8, v59
	v_add_u32_e32 v40, s4, v60
	v_add_u32_e32 v42, s8, v61
	v_add_u32_e32 v44, s4, v62
	v_add_u32_e32 v46, s8, v63
	v_ashrrev_i32_e32 v17, 31, v16
	v_lshlrev_b64 v[18:19], 14, v[18:19]
	v_ashrrev_i32_e32 v23, 31, v22
	v_ashrrev_i32_e32 v21, 31, v20
	v_ashrrev_i32_e32 v27, 31, v26
	v_ashrrev_i32_e32 v25, 31, v24
	v_ashrrev_i32_e32 v31, 31, v30
	v_ashrrev_i32_e32 v29, 31, v28
	v_ashrrev_i32_e32 v35, 31, v34
	v_ashrrev_i32_e32 v33, 31, v32
	v_ashrrev_i32_e32 v39, 31, v38
	v_ashrrev_i32_e32 v37, 31, v36
	v_ashrrev_i32_e32 v43, 31, v42
	v_ashrrev_i32_e32 v41, 31, v40
	v_ashrrev_i32_e32 v47, 31, v46
	v_ashrrev_i32_e32 v45, 31, v44
	v_lshlrev_b64 v[16:17], 14, v[16:17]
	v_lshl_add_u64 v[18:19], v[10:11], 0, v[18:19]
	v_lshlrev_b64 v[20:21], 14, v[20:21]
	v_lshlrev_b64 v[22:23], 14, v[22:23]
	v_lshlrev_b64 v[24:25], 14, v[24:25]
	v_lshlrev_b64 v[26:27], 14, v[26:27]
	v_lshlrev_b64 v[28:29], 14, v[28:29]
	v_lshlrev_b64 v[30:31], 14, v[30:31]
	v_lshlrev_b64 v[32:33], 14, v[32:33]
	v_lshlrev_b64 v[34:35], 14, v[34:35]
	v_lshlrev_b64 v[36:37], 14, v[36:37]
	v_lshlrev_b64 v[38:39], 14, v[38:39]
	v_lshlrev_b64 v[40:41], 14, v[40:41]
	v_lshlrev_b64 v[42:43], 14, v[42:43]
	v_lshlrev_b64 v[44:45], 14, v[44:45]
	v_lshlrev_b64 v[46:47], 14, v[46:47]
	v_lshl_add_u64 v[16:17], v[10:11], 0, v[16:17]
	v_lshl_add_u64 v[22:23], v[10:11], 0, v[22:23]
	v_lshl_add_u64 v[20:21], v[10:11], 0, v[20:21]
	v_lshl_add_u64 v[26:27], v[10:11], 0, v[26:27]
	v_lshl_add_u64 v[24:25], v[10:11], 0, v[24:25]
	v_lshl_add_u64 v[30:31], v[10:11], 0, v[30:31]
	v_lshl_add_u64 v[28:29], v[10:11], 0, v[28:29]
	v_lshl_add_u64 v[34:35], v[10:11], 0, v[34:35]
	v_lshl_add_u64 v[32:33], v[10:11], 0, v[32:33]
	v_lshl_add_u64 v[38:39], v[10:11], 0, v[38:39]
	v_lshl_add_u64 v[36:37], v[10:11], 0, v[36:37]
	v_lshl_add_u64 v[42:43], v[10:11], 0, v[42:43]
	v_lshl_add_u64 v[40:41], v[10:11], 0, v[40:41]
	v_lshl_add_u64 v[46:47], v[10:11], 0, v[46:47]
	v_lshl_add_u64 v[44:45], v[10:11], 0, v[44:45]
	global_load_dword v64, v[18:19], off
	global_load_dword v65, v[16:17], off
	global_load_dword v66, v[22:23], off
	global_load_dword v67, v[20:21], off
	global_load_dword v68, v[26:27], off
	global_load_dword v69, v[24:25], off
	global_load_dword v70, v[30:31], off
	global_load_dword v71, v[28:29], off
	global_load_dword v72, v[34:35], off
	global_load_dword v73, v[32:33], off
	global_load_dword v74, v[38:39], off
	global_load_dword v75, v[36:37], off
	global_load_dword v76, v[42:43], off
	global_load_dword v77, v[40:41], off
	global_load_dword v78, v[46:47], off
	global_load_dword v79, v[44:45], off
	s_add_i32 s9, s9, 16
	s_add_i32 s11, s11, 16
	s_add_i32 s7, s7, -16
	v_mad_u64_u32 v[16:17], s[12:13], v49, s10, v[6:7]
	s_cmp_lg_u32 s7, 0
	v_mad_u64_u32 v[18:19], s[12:13], v48, s10, v[6:7]
	v_mad_u64_u32 v[20:21], s[12:13], v51, s10, v[6:7]
	v_mad_u64_u32 v[22:23], s[12:13], v50, s10, v[6:7]
	v_mad_u64_u32 v[24:25], s[12:13], v53, s10, v[6:7]
	v_mad_u64_u32 v[26:27], s[12:13], v52, s10, v[6:7]
	v_mad_u64_u32 v[28:29], s[12:13], v55, s10, v[6:7]
	v_mad_u64_u32 v[30:31], s[12:13], v54, s10, v[6:7]
	v_mad_u64_u32 v[32:33], s[12:13], v57, s10, v[6:7]
	v_mad_u64_u32 v[34:35], s[12:13], v56, s10, v[6:7]
	v_mad_u64_u32 v[36:37], s[12:13], v59, s10, v[6:7]
	v_mad_u64_u32 v[38:39], s[12:13], v58, s10, v[6:7]
	v_mad_u64_u32 v[40:41], s[12:13], v61, s10, v[6:7]
	v_mad_u64_u32 v[42:43], s[12:13], v60, s10, v[6:7]
	v_mad_u64_u32 v[44:45], s[12:13], v63, s10, v[6:7]
	v_mad_u64_u32 v[46:47], s[12:13], v62, s10, v[6:7]
	s_nop 7
	s_lshl_b32 s12, s11, 1
	s_lshl_b32 s13, s9, 1
	v_or_b32_e32 v172, s12, v1
	v_or_b32_e32 v173, s13, v2
	s_add_i32 s14, s12, 4
	s_add_i32 s15, s13, 4
	s_add_i32 s16, s12, 8
	s_add_i32 s17, s13, 8
	s_add_i32 s18, s12, 12
	s_add_i32 s19, s13, 12
	s_add_i32 s20, s12, 16
	s_add_i32 s21, s13, 16
	s_add_i32 s22, s12, 20
	s_add_i32 s23, s13, 20
	s_add_i32 s24, s12, 24
	s_add_i32 s25, s13, 24
	s_add_i32 s12, s12, 28
	s_add_i32 s13, s13, 28
	v_add_u32_e32 v142, s8, v173
	v_or_b32_e32 v174, s14, v1
	v_or_b32_e32 v175, s15, v2
	v_or_b32_e32 v176, s16, v1
	v_or_b32_e32 v177, s17, v2
	v_or_b32_e32 v178, s18, v1
	v_or_b32_e32 v179, s19, v2
	v_or_b32_e32 v180, s20, v1
	v_or_b32_e32 v181, s21, v2
	v_or_b32_e32 v182, s22, v1
	v_or_b32_e32 v183, s23, v2
	v_or_b32_e32 v184, s24, v1
	v_or_b32_e32 v185, s25, v2
	v_or_b32_e32 v186, s12, v1
	v_or_b32_e32 v187, s13, v2
	v_add_u32_e32 v140, s4, v172
	v_ashrrev_i32_e32 v143, 31, v142
	v_add_u32_e32 v144, s4, v174
; __device__ __forceinline__ void p0_transpose_item(const float* W, int N, bf16_t* WT, int ldt, int k0, int n0, int nrow0, int kcol0, LAS float* scr, int lane) {
;     ...
;     for (int i = 0; i < 32; ++i) { const int kk = 2 * i + (lane >> 5); scr[kk * 33 + (lane & 31)] = W[(size_t)(k0 + kk) * N + n0 + (lane & 31)]; }
	v_add_u32_e32 v146, s8, v175
	v_add_u32_e32 v148, s4, v176
	v_add_u32_e32 v150, s8, v177
	v_add_u32_e32 v152, s4, v178
	v_add_u32_e32 v154, s8, v179
	v_add_u32_e32 v156, s4, v180
	v_add_u32_e32 v158, s8, v181
	v_add_u32_e32 v160, s4, v182
	v_add_u32_e32 v162, s8, v183
	v_add_u32_e32 v164, s4, v184
	v_add_u32_e32 v166, s8, v185
	v_add_u32_e32 v168, s4, v186
	v_add_u32_e32 v170, s8, v187
	v_ashrrev_i32_e32 v141, 31, v140
	v_lshlrev_b64 v[142:143], 14, v[142:143]
	v_ashrrev_i32_e32 v147, 31, v146
	v_ashrrev_i32_e32 v145, 31, v144
	v_ashrrev_i32_e32 v151, 31, v150
	v_ashrrev_i32_e32 v149, 31, v148
	v_ashrrev_i32_e32 v155, 31, v154
	v_ashrrev_i32_e32 v153, 31, v152
	v_ashrrev_i32_e32 v159, 31, v158
	v_ashrrev_i32_e32 v157, 31, v156
	v_ashrrev_i32_e32 v163, 31, v162
	v_ashrrev_i32_e32 v161, 31, v160
	v_ashrrev_i32_e32 v167, 31, v166
	v_ashrrev_i32_e32 v165, 31, v164
	v_ashrrev_i32_e32 v171, 31, v170
	v_ashrrev_i32_e32 v169, 31, v168
	v_lshlrev_b64 v[140:141], 14, v[140:141]
	v_lshl_add_u64 v[142:143], v[10:11], 0, v[142:143]
	v_lshlrev_b64 v[144:145], 14, v[144:145]
	v_lshlrev_b64 v[146:147], 14, v[146:147]
	v_lshlrev_b64 v[148:149], 14, v[148:149]
	v_lshlrev_b64 v[150:151], 14, v[150:151]
	v_lshlrev_b64 v[152:153], 14, v[152:153]
	v_lshlrev_b64 v[154:155], 14, v[154:155]
	v_lshlrev_b64 v[156:157], 14, v[156:157]
	v_lshlrev_b64 v[158:159], 14, v[158:159]
	v_lshlrev_b64 v[160:161], 14, v[160:161]
	v_lshlrev_b64 v[162:163], 14, v[162:163]
	v_lshlrev_b64 v[164:165], 14, v[164:165]
	v_lshlrev_b64 v[166:167], 14, v[166:167]
	v_lshlrev_b64 v[168:169], 14, v[168:169]
	v_lshlrev_b64 v[170:171], 14, v[170:171]
	v_lshl_add_u64 v[140:141], v[10:11], 0, v[140:141]
	v_lshl_add_u64 v[146:147], v[10:11], 0, v[146:147]
	v_lshl_add_u64 v[144:145], v[10:11], 0, v[144:145]
	v_lshl_add_u64 v[150:151], v[10:11], 0, v[150:151]
	v_lshl_add_u64 v[148:149], v[10:11], 0, v[148:149]
	v_lshl_add_u64 v[154:155], v[10:11], 0, v[154:155]
	v_lshl_add_u64 v[152:153], v[10:11], 0, v[152:153]
	v_lshl_add_u64 v[158:159], v[10:11], 0, v[158:159]
	v_lshl_add_u64 v[156:157], v[10:11], 0, v[156:157]
	v_lshl_add_u64 v[162:163], v[10:11], 0, v[162:163]
	v_lshl_add_u64 v[160:161], v[10:11], 0, v[160:161]
	v_lshl_add_u64 v[166:167], v[10:11], 0, v[166:167]
	v_lshl_add_u64 v[164:165], v[10:11], 0, v[164:165]
	v_lshl_add_u64 v[170:171], v[10:11], 0, v[170:171]
	v_lshl_add_u64 v[168:169], v[10:11], 0, v[168:169]
	global_load_dword v188, v[142:143], off
	global_load_dword v189, v[140:141], off
	global_load_dword v190, v[146:147], off
	global_load_dword v191, v[144:145], off
	global_load_dword v192, v[150:151], off
	global_load_dword v193, v[148:149], off
	global_load_dword v194, v[154:155], off
	global_load_dword v195, v[152:153], off
	global_load_dword v196, v[158:159], off
	global_load_dword v197, v[156:157], off
	global_load_dword v198, v[162:163], off
	global_load_dword v199, v[160:161], off
	global_load_dword v200, v[166:167], off
	global_load_dword v201, v[164:165], off
	global_load_dword v202, v[170:171], off
	global_load_dword v203, v[168:169], off
	s_add_i32 s9, s9, 16
	s_add_i32 s11, s11, 16
	s_add_i32 s7, s7, -16
	v_mad_u64_u32 v[140:141], s[12:13], v173, s10, v[6:7]
	s_cmp_lg_u32 s7, 0
	v_mad_u64_u32 v[142:143], s[12:13], v172, s10, v[6:7]
	v_mad_u64_u32 v[144:145], s[12:13], v175, s10, v[6:7]
	v_mad_u64_u32 v[146:147], s[12:13], v174, s10, v[6:7]
	v_mad_u64_u32 v[148:149], s[12:13], v177, s10, v[6:7]
	v_mad_u64_u32 v[150:151], s[12:13], v176, s10, v[6:7]
	v_mad_u64_u32 v[152:153], s[12:13], v179, s10, v[6:7]
	v_mad_u64_u32 v[154:155], s[12:13], v178, s10, v[6:7]
	v_mad_u64_u32 v[156:157], s[12:13], v181, s10, v[6:7]
	v_mad_u64_u32 v[158:159], s[12:13], v180, s10, v[6:7]
	v_mad_u64_u32 v[160:161], s[12:13], v183, s10, v[6:7]
	v_mad_u64_u32 v[162:163], s[12:13], v182, s10, v[6:7]
	v_mad_u64_u32 v[164:165], s[12:13], v185, s10, v[6:7]
	v_mad_u64_u32 v[166:167], s[12:13], v184, s10, v[6:7]
	v_mad_u64_u32 v[168:169], s[12:13], v187, s10, v[6:7]
	v_mad_u64_u32 v[170:171], s[12:13], v186, s10, v[6:7]
	s_waitcnt vmcnt(31)
; #define LAS __attribute__((address_space(3)))
; __device__ __forceinline__ unsigned cvt_pk_bf16(float lo, float hi) { unsigned r; asm volatile("v_cvt_pk_bf16_f32 %0, %1, %2" : "=v"(r) : "v"(lo), "v"(hi)); return r; }
; #define LDS_WAIT() asm volatile("s_waitcnt lgkmcnt(0)" ::: "memory")
; __device__ __forceinline__ void p0_transpose_item(const float* W, int N, bf16_t* WT, int ldt, int k0, int n0, int nrow0, int kcol0, LAS float* scr, int lane) {
;     ...
;     for (int i = 0; i < 32; ++i) { const int kk = 2 * i + (lane >> 5); scr[kk * 33 + (lane & 31)] = W[(size_t)(k0 + kk) * N + n0 + (lane & 31)]; }
;     LDS_WAIT(); asm volatile("" ::: "memory");
;     const int c = lane & 7;
; #pragma unroll
;     for (int j = 0; j < 4; ++j) { const int n = (lane >> 3) + 8 * j; const LAS float* s = scr + (8 * c) * 33 + n;
;         u32x4 o; o.x = cvt_pk_bf16(s[0 * 33], s[1 * 33]); o.y = cvt_pk_bf16(s[2 * 33], s[3 * 33]); o.z = cvt_pk_bf16(s[4 * 33], s[5 * 33]); o.w = cvt_pk_bf16(s[6 * 33], s[7 * 33]);
;         *(u32x4*)(WT + (size_t)(nrow0 + n) * ldt + kcol0 + k0 + 8 * c) = o; }
;     LDS_WAIT(); asm volatile("" ::: "memory");
; __device__ __forceinline__ void p0_prologue(const Frame& F) {
;     ...
;                 for (int it = first; it < nitems; it += NGW) { const int kb = it / nblk, nbk = it % nblk, n0 = nbk * 32;
;                     const int nrow0 = (jb == 0 && n0 >= 3392) ? n0 + 192 : n0;
;                     p0_transpose_item(W, J.N, WT, J.ldt, kb * 64, n0, nrow0, J.kcol0, scr, F.lane); }
	ds_write_b32 v16, v64
	s_waitcnt vmcnt(30)
	ds_write_b32 v18, v65
	s_waitcnt vmcnt(29)
	ds_write_b32 v20, v66
	s_waitcnt vmcnt(28)
	ds_write_b32 v22, v67
	s_waitcnt vmcnt(27)
	ds_write_b32 v24, v68
	s_waitcnt vmcnt(26)
	ds_write_b32 v26, v69
	s_waitcnt vmcnt(25)
	ds_write_b32 v28, v70
	s_waitcnt vmcnt(24)
	ds_write_b32 v30, v71
	s_waitcnt vmcnt(23)
	ds_write_b32 v32, v72
	s_waitcnt vmcnt(22)
	ds_write_b32 v34, v73
	s_waitcnt vmcnt(21)
	ds_write_b32 v36, v74
	s_waitcnt vmcnt(20)
	ds_write_b32 v38, v75
	s_waitcnt vmcnt(19)
	ds_write_b32 v40, v76
	s_waitcnt vmcnt(18)
	ds_write_b32 v42, v77
	s_waitcnt vmcnt(17)
	ds_write_b32 v44, v78
	s_waitcnt vmcnt(16)
	ds_write_b32 v46, v79
	s_waitcnt vmcnt(15)
	ds_write_b32 v140, v188
	s_waitcnt vmcnt(14)
	ds_write_b32 v142, v189
	s_waitcnt vmcnt(13)
	ds_write_b32 v144, v190
	s_waitcnt vmcnt(12)
	ds_write_b32 v146, v191
	s_waitcnt vmcnt(11)
	ds_write_b32 v148, v192
	s_waitcnt vmcnt(10)
	ds_write_b32 v150, v193
	s_waitcnt vmcnt(9)
	ds_write_b32 v152, v194
	s_waitcnt vmcnt(8)
	ds_write_b32 v154, v195
	s_waitcnt vmcnt(7)
	ds_write_b32 v156, v196
	s_waitcnt vmcnt(6)
	ds_write_b32 v158, v197
	s_waitcnt vmcnt(5)
	ds_write_b32 v160, v198
	s_waitcnt vmcnt(4)
	ds_write_b32 v162, v199
	s_waitcnt vmcnt(3)
	ds_write_b32 v164, v200
	s_waitcnt vmcnt(2)
	ds_write_b32 v166, v201
	s_waitcnt vmcnt(1)
	ds_write_b32 v168, v202
	s_waitcnt vmcnt(0)
	ds_write_b32 v170, v203
	s_waitcnt lgkmcnt(0)
	v_or_b32_e32 v20, s6, v3
	ds_read2_b32 v[10:11], v7 offset1:33
	s_ashr_i32 s9, s8, 31
	v_ashrrev_i32_e32 v21, 31, v20
	s_waitcnt lgkmcnt(0)
	v_cvt_pk_bf16_f32 v16, v10, v11
	ds_read2_b32 v[10:11], v7 offset0:66 offset1:99
	v_lshl_add_u64 v[22:23], s[8:9], 1, v[8:9]
	v_lshlrev_b64 v[20:21], 13, v[20:21]
	s_waitcnt lgkmcnt(0)
	v_cvt_pk_bf16_f32 v17, v10, v11
	ds_read2_b32 v[10:11], v7 offset0:132 offset1:165
	v_lshl_add_u64 v[20:21], v[22:23], 0, v[20:21]
	s_waitcnt lgkmcnt(0)
	v_cvt_pk_bf16_f32 v18, v10, v11
	ds_read2_b32 v[10:11], v7 offset0:198 offset1:231
	s_waitcnt lgkmcnt(0)
	v_cvt_pk_bf16_f32 v19, v10, v11
	global_store_dwordx4 v[20:21], v[16:19], off
	v_or_b32_e32 v20, s6, v12
	ds_read2_b32 v[10:11], v7 offset0:8 offset1:41
	v_ashrrev_i32_e32 v21, 31, v20
	s_waitcnt lgkmcnt(0)
	v_cvt_pk_bf16_f32 v16, v10, v11
	ds_read2_b32 v[10:11], v7 offset0:74 offset1:107
	v_lshlrev_b64 v[20:21], 13, v[20:21]
	s_waitcnt lgkmcnt(0)
	v_cvt_pk_bf16_f32 v17, v10, v11
	ds_read2_b32 v[10:11], v7 offset0:140 offset1:173
	v_lshl_add_u64 v[20:21], v[22:23], 0, v[20:21]
	s_waitcnt lgkmcnt(0)
	v_cvt_pk_bf16_f32 v18, v10, v11
	ds_read2_b32 v[10:11], v7 offset0:206 offset1:239
	s_waitcnt lgkmcnt(0)
	v_cvt_pk_bf16_f32 v19, v10, v11
	global_store_dwordx4 v[20:21], v[16:19], off
	v_or_b32_e32 v20, s6, v13
	ds_read2_b32 v[10:11], v7 offset0:16 offset1:49
	v_ashrrev_i32_e32 v21, 31, v20
	s_waitcnt lgkmcnt(0)
	v_cvt_pk_bf16_f32 v16, v10, v11
	ds_read2_b32 v[10:11], v7 offset0:82 offset1:115
	v_lshlrev_b64 v[20:21], 13, v[20:21]
	s_waitcnt lgkmcnt(0)
	v_cvt_pk_bf16_f32 v17, v10, v11
	ds_read2_b32 v[10:11], v7 offset0:148 offset1:181
	v_lshl_add_u64 v[20:21], v[22:23], 0, v[20:21]
	s_waitcnt lgkmcnt(0)
	v_cvt_pk_bf16_f32 v18, v10, v11
	ds_read2_b32 v[10:11], v7 offset0:214 offset1:247
	s_waitcnt lgkmcnt(0)
	v_cvt_pk_bf16_f32 v19, v10, v11
	global_store_dwordx4 v[20:21], v[16:19], off
	v_or_b32_e32 v20, s6, v15
	ds_read2_b32 v[10:11], v7 offset0:24 offset1:57
	v_ashrrev_i32_e32 v21, 31, v20
	s_waitcnt lgkmcnt(0)
	v_cvt_pk_bf16_f32 v16, v10, v11
	ds_read2_b32 v[10:11], v7 offset0:90 offset1:123
	v_lshlrev_b64 v[20:21], 13, v[20:21]
	s_waitcnt lgkmcnt(0)
	v_cvt_pk_bf16_f32 v17, v10, v11
	ds_read2_b32 v[10:11], v7 offset0:156 offset1:189
	v_lshl_add_u64 v[20:21], v[22:23], 0, v[20:21]
	s_waitcnt lgkmcnt(0)
	v_cvt_pk_bf16_f32 v18, v10, v11
	ds_read2_b32 v[10:11], v7 offset0:222 offset1:255
	s_waitcnt lgkmcnt(0)
	v_cvt_pk_bf16_f32 v19, v10, v11
	global_store_dwordx4 v[20:21], v[16:19], off
	s_waitcnt lgkmcnt(0)
	s_add_i32 s5, s5, s3
	s_cmpk_lt_i32 s5, 0x2000
	s_cbranch_scc1 .LBB0_114
